# BM selected-attention: valid-column mask built with scalar ops into an SGPR pair and per-group bias registers kept up to date, so the per-pair bias is one v_cndmask (was v_and+v_cmp+v_add+v_cndmask)
# baseline (speedup 1.0000x reference)
.LBB0_1549:
.LBB0_1550:
	v_readfirstlane_b32 s46, v70
	v_readfirstlane_b32 s47, v71
	v_readfirstlane_b32 s62, v72
	v_readfirstlane_b32 s63, v73
	v_and_b32_e32 v248, 15, v181
	v_lshrrev_b32_e32 v249, 4, v181
	v_lshrrev_b32_e32 v248, 2, v248
	v_lshlrev_b32_e32 v249, 2, v249
	v_readlane_b32 s23, v243, 32
	v_mov_b32_e32 v244, 1
	v_lshlrev_b32_e32 v244, v248, v244
	s_mov_b32 s16, 0x3e38aa3b
	s_mov_b32 s17, 0x3e38aa3b
	v_lshlrev_b32_e32 v79, 4, v181
	s_add_i32 s23, s23, s97
	v_add_u32_e32 v247, s23, v248
	v_mad_u64_u32 v[250:251], s[50:51], v247, v212, v[68:69]
	global_load_dwordx4 v[100:103], v[250:251], off
	global_load_dwordx4 v[104:107], v[250:251], off offset:64
	v_add_u32_e32 v249, 4, v247
	v_mad_u64_u32 v[250:251], s[50:51], v249, v212, v[68:69]
	global_load_dwordx4 v[108:111], v[250:251], off
	global_load_dwordx4 v[112:115], v[250:251], off offset:64
	v_add_u32_e32 v249, 8, v247
	v_mad_u64_u32 v[250:251], s[50:51], v249, v212, v[68:69]
	global_load_dwordx4 v[116:119], v[250:251], off
	global_load_dwordx4 v[120:123], v[250:251], off offset:64
	v_add_u32_e32 v249, 12, v247
	v_mad_u64_u32 v[250:251], s[50:51], v249, v212, v[68:69]
	global_load_dwordx4 v[124:127], v[250:251], off
	global_load_dwordx4 v[128:131], v[250:251], off offset:64
	v_and_b32_e32 v248, 15, v181
	v_lshrrev_b32_e32 v249, 4, v181
	v_lshlrev_b32_e32 v198, 6, v248
	v_lshl_add_u32 v198, v249, 2, v198
	v_add_u32_e32 v198, s96, v198
	v_lshl_add_u32 v199, v248, 2, s96
	ds_read_b32 v12, v198 offset:16384
	ds_read_b32 v13, v198 offset:16400
	ds_read_b32 v14, v198 offset:16416
	ds_read_b32 v15, v198 offset:16432
	ds_read_b32 v16, v199 offset:17408
	v_lshl_add_u32 v199, v181, 2, s96
	v_mov_b32_e32 v17, 1
	v_lshlrev_b32_e32 v17, v248, v17
	s_waitcnt lgkmcnt(0)
	v_mul_f32_e32 v81, 0x3fb8aa3b, v81
	ds_write_b32 v199, v11 offset:16384
	ds_write_b32 v199, v11 offset:16640
	ds_write_b32 v199, v11 offset:16896
	ds_write_b32 v199, v11 offset:17152
	v_cmp_lt_i32_e32 vcc, v249, v16
	v_and_b32_e32 v12, 0xff, v12
	v_lshl_add_u32 v12, v12, 2, s96
	v_cndmask_b32_e32 v18, 0, v17, vcc
	ds_or_b32 v12, v18 offset:16384
	v_add_u32_e32 v18, 4, v249
	v_cmp_lt_i32_e32 vcc, v18, v16
	v_and_b32_e32 v13, 0xff, v13
	v_lshl_add_u32 v13, v13, 2, s96
	v_cndmask_b32_e32 v18, 0, v17, vcc
	ds_or_b32 v13, v18 offset:16384
	v_add_u32_e32 v18, 8, v249
	v_cmp_lt_i32_e32 vcc, v18, v16
	v_and_b32_e32 v14, 0xff, v14
	v_lshl_add_u32 v14, v14, 2, s96
	v_cndmask_b32_e32 v18, 0, v17, vcc
	ds_or_b32 v14, v18 offset:16384
	v_add_u32_e32 v18, 12, v249
	v_cmp_lt_i32_e32 vcc, v18, v16
	v_and_b32_e32 v15, 0xff, v15
	v_lshl_add_u32 v15, v15, 2, s96
	v_cndmask_b32_e32 v18, 0, v17, vcc
	ds_or_b32 v15, v18 offset:16384
	s_waitcnt lgkmcnt(0)
	ds_read_b32 v12, v199 offset:16384
	ds_read_b32 v13, v199 offset:16640
	ds_read_b32 v14, v199 offset:16896
	ds_read_b32 v15, v199 offset:17152
	s_mov_b32 s25, 0
	s_waitcnt lgkmcnt(0)
	v_cmp_ne_u32_e64 s[4:5], 0, v12
	v_lshlrev_b32_e32 v16, 16, v12
	v_add_u32_e32 v17, 0, v181
	v_or_b32_e32 v16, v16, v17
	v_mbcnt_lo_u32_b32 v17, s4, 0
	v_mbcnt_hi_u32_b32 v17, s5, v17
	v_add_u32_e32 v17, s25, v17
	v_lshl_add_u32 v17, v17, 2, s96
	v_add_u32_e32 v17, 0x4000, v17
	v_add_u32_e32 v18, 0x4400, v199
	s_bcnt1_i32_b64 s13, s[4:5]
	v_cndmask_b32_e64 v17, v18, v17, s[4:5]
	s_add_i32 s25, s25, s13
	ds_write_b32 v17, v16
	v_cmp_ne_u32_e64 s[4:5], 0, v13
	v_lshlrev_b32_e32 v16, 16, v13
	v_add_u32_e32 v17, 64, v181
	v_or_b32_e32 v16, v16, v17
	v_mbcnt_lo_u32_b32 v17, s4, 0
	v_mbcnt_hi_u32_b32 v17, s5, v17
	v_add_u32_e32 v17, s25, v17
	v_lshl_add_u32 v17, v17, 2, s96
	v_add_u32_e32 v17, 0x4000, v17
	v_add_u32_e32 v18, 0x4400, v199
	s_bcnt1_i32_b64 s13, s[4:5]
	v_cndmask_b32_e64 v17, v18, v17, s[4:5]
	s_add_i32 s25, s25, s13
	ds_write_b32 v17, v16
	v_cmp_ne_u32_e64 s[4:5], 0, v14
	v_lshlrev_b32_e32 v16, 16, v14
	v_add_u32_e32 v17, 128, v181
	v_or_b32_e32 v16, v16, v17
	v_mbcnt_lo_u32_b32 v17, s4, 0
	v_mbcnt_hi_u32_b32 v17, s5, v17
	v_add_u32_e32 v17, s25, v17
	v_lshl_add_u32 v17, v17, 2, s96
	v_add_u32_e32 v17, 0x4000, v17
	v_add_u32_e32 v18, 0x4400, v199
	s_bcnt1_i32_b64 s13, s[4:5]
	v_cndmask_b32_e64 v17, v18, v17, s[4:5]
	s_add_i32 s25, s25, s13
	ds_write_b32 v17, v16
	v_cmp_ne_u32_e64 s[4:5], 0, v15
	v_lshlrev_b32_e32 v16, 16, v15
	v_add_u32_e32 v17, 192, v181
	v_or_b32_e32 v16, v16, v17
	v_mbcnt_lo_u32_b32 v17, s4, 0
	v_mbcnt_hi_u32_b32 v17, s5, v17
	v_add_u32_e32 v17, s25, v17
	v_lshl_add_u32 v17, v17, 2, s96
	v_add_u32_e32 v17, 0x4000, v17
	v_add_u32_e32 v18, 0x4400, v199
	s_bcnt1_i32_b64 s13, s[4:5]
	v_cndmask_b32_e64 v17, v18, v17, s[4:5]
	s_add_i32 s25, s25, s13
	ds_write_b32 v17, v16
	s_waitcnt vmcnt(0)
	v_lshlrev_b32_e32 v245, 16, v100
	v_and_b32_e32 v246, 0xffff0000, v100
	v_mul_f32_e32 v245, 0x41000000, v245
	v_mul_f32_e32 v246, 0x41000000, v246
	v_lshlrev_b32_e32 v248, 16, v101
	v_and_b32_e32 v249, 0xffff0000, v101
	v_cvt_pk_fp8_f32 v164, v245, v246
	v_mul_f32_e32 v248, 0x41000000, v248
	v_mul_f32_e32 v249, 0x41000000, v249
	s_nop 0
	v_cvt_pk_fp8_f32 v164, v248, v249 op_sel:[0,0,1]
	v_lshlrev_b32_e32 v245, 16, v102
	v_and_b32_e32 v246, 0xffff0000, v102
	v_mul_f32_e32 v245, 0x41000000, v245
	v_mul_f32_e32 v246, 0x41000000, v246
	v_lshlrev_b32_e32 v248, 16, v103
	v_and_b32_e32 v249, 0xffff0000, v103
	v_cvt_pk_fp8_f32 v165, v245, v246
	v_mul_f32_e32 v248, 0x41000000, v248
	v_mul_f32_e32 v249, 0x41000000, v249
	s_nop 0
	v_cvt_pk_fp8_f32 v165, v248, v249 op_sel:[0,0,1]
	v_lshlrev_b32_e32 v245, 16, v104
	v_and_b32_e32 v246, 0xffff0000, v104
	v_mul_f32_e32 v245, 0x41000000, v245
	v_mul_f32_e32 v246, 0x41000000, v246
	v_lshlrev_b32_e32 v248, 16, v105
	v_and_b32_e32 v249, 0xffff0000, v105
	v_cvt_pk_fp8_f32 v166, v245, v246
	v_mul_f32_e32 v248, 0x41000000, v248
	v_mul_f32_e32 v249, 0x41000000, v249
	s_nop 0
	v_cvt_pk_fp8_f32 v166, v248, v249 op_sel:[0,0,1]
	v_lshlrev_b32_e32 v245, 16, v106
	v_and_b32_e32 v246, 0xffff0000, v106
	v_mul_f32_e32 v245, 0x41000000, v245
	v_mul_f32_e32 v246, 0x41000000, v246
	v_lshlrev_b32_e32 v248, 16, v107
	v_and_b32_e32 v249, 0xffff0000, v107
	v_cvt_pk_fp8_f32 v167, v245, v246
	v_mul_f32_e32 v248, 0x41000000, v248
	v_mul_f32_e32 v249, 0x41000000, v249
	s_nop 0
	v_cvt_pk_fp8_f32 v167, v248, v249 op_sel:[0,0,1]
	v_lshlrev_b32_e32 v245, 16, v108
	v_and_b32_e32 v246, 0xffff0000, v108
	v_mul_f32_e32 v245, 0x41000000, v245
	v_mul_f32_e32 v246, 0x41000000, v246
	v_lshlrev_b32_e32 v248, 16, v109
	v_and_b32_e32 v249, 0xffff0000, v109
	v_cvt_pk_fp8_f32 v168, v245, v246
	v_mul_f32_e32 v248, 0x41000000, v248
	v_mul_f32_e32 v249, 0x41000000, v249
	s_nop 0
	v_cvt_pk_fp8_f32 v168, v248, v249 op_sel:[0,0,1]
	v_lshlrev_b32_e32 v245, 16, v110
	v_and_b32_e32 v246, 0xffff0000, v110
	v_mul_f32_e32 v245, 0x41000000, v245
	v_mul_f32_e32 v246, 0x41000000, v246
	v_lshlrev_b32_e32 v248, 16, v111
	v_and_b32_e32 v249, 0xffff0000, v111
	v_cvt_pk_fp8_f32 v169, v245, v246
	v_mul_f32_e32 v248, 0x41000000, v248
	v_mul_f32_e32 v249, 0x41000000, v249
	s_nop 0
	v_cvt_pk_fp8_f32 v169, v248, v249 op_sel:[0,0,1]
	v_lshlrev_b32_e32 v245, 16, v112
	v_and_b32_e32 v246, 0xffff0000, v112
	v_mul_f32_e32 v245, 0x41000000, v245
	v_mul_f32_e32 v246, 0x41000000, v246
	v_lshlrev_b32_e32 v248, 16, v113
	v_and_b32_e32 v249, 0xffff0000, v113
	v_cvt_pk_fp8_f32 v170, v245, v246
	v_mul_f32_e32 v248, 0x41000000, v248
	v_mul_f32_e32 v249, 0x41000000, v249
	s_nop 0
	v_cvt_pk_fp8_f32 v170, v248, v249 op_sel:[0,0,1]
	v_lshlrev_b32_e32 v245, 16, v114
	v_and_b32_e32 v246, 0xffff0000, v114
	v_mul_f32_e32 v245, 0x41000000, v245
	v_mul_f32_e32 v246, 0x41000000, v246
	v_lshlrev_b32_e32 v248, 16, v115
	v_and_b32_e32 v249, 0xffff0000, v115
	v_cvt_pk_fp8_f32 v171, v245, v246
	v_mul_f32_e32 v248, 0x41000000, v248
	v_mul_f32_e32 v249, 0x41000000, v249
	s_nop 0
	v_cvt_pk_fp8_f32 v171, v248, v249 op_sel:[0,0,1]
	v_lshlrev_b32_e32 v245, 16, v116
	v_and_b32_e32 v246, 0xffff0000, v116
	v_mul_f32_e32 v245, 0x41000000, v245
	v_mul_f32_e32 v246, 0x41000000, v246
	v_lshlrev_b32_e32 v248, 16, v117
	v_and_b32_e32 v249, 0xffff0000, v117
	v_cvt_pk_fp8_f32 v182, v245, v246
	v_mul_f32_e32 v248, 0x41000000, v248
	v_mul_f32_e32 v249, 0x41000000, v249
	s_nop 0
	v_cvt_pk_fp8_f32 v182, v248, v249 op_sel:[0,0,1]
	v_lshlrev_b32_e32 v245, 16, v118
	v_and_b32_e32 v246, 0xffff0000, v118
	v_mul_f32_e32 v245, 0x41000000, v245
	v_mul_f32_e32 v246, 0x41000000, v246
	v_lshlrev_b32_e32 v248, 16, v119
	v_and_b32_e32 v249, 0xffff0000, v119
	v_cvt_pk_fp8_f32 v183, v245, v246
	v_mul_f32_e32 v248, 0x41000000, v248
	v_mul_f32_e32 v249, 0x41000000, v249
	s_nop 0
	v_cvt_pk_fp8_f32 v183, v248, v249 op_sel:[0,0,1]
	v_lshlrev_b32_e32 v245, 16, v120
	v_and_b32_e32 v246, 0xffff0000, v120
	v_mul_f32_e32 v245, 0x41000000, v245
	v_mul_f32_e32 v246, 0x41000000, v246
	v_lshlrev_b32_e32 v248, 16, v121
	v_and_b32_e32 v249, 0xffff0000, v121
	v_cvt_pk_fp8_f32 v184, v245, v246
	v_mul_f32_e32 v248, 0x41000000, v248
	v_mul_f32_e32 v249, 0x41000000, v249
	s_nop 0
	v_cvt_pk_fp8_f32 v184, v248, v249 op_sel:[0,0,1]
	v_lshlrev_b32_e32 v245, 16, v122
	v_and_b32_e32 v246, 0xffff0000, v122
	v_mul_f32_e32 v245, 0x41000000, v245
	v_mul_f32_e32 v246, 0x41000000, v246
	v_lshlrev_b32_e32 v248, 16, v123
	v_and_b32_e32 v249, 0xffff0000, v123
	v_cvt_pk_fp8_f32 v185, v245, v246
	v_mul_f32_e32 v248, 0x41000000, v248
	v_mul_f32_e32 v249, 0x41000000, v249
	s_nop 0
	v_cvt_pk_fp8_f32 v185, v248, v249 op_sel:[0,0,1]
	v_lshlrev_b32_e32 v245, 16, v124
	v_and_b32_e32 v246, 0xffff0000, v124
	v_mul_f32_e32 v245, 0x41000000, v245
	v_mul_f32_e32 v246, 0x41000000, v246
	v_lshlrev_b32_e32 v248, 16, v125
	v_and_b32_e32 v249, 0xffff0000, v125
	v_cvt_pk_fp8_f32 v186, v245, v246
	v_mul_f32_e32 v248, 0x41000000, v248
	v_mul_f32_e32 v249, 0x41000000, v249
	s_nop 0
	v_cvt_pk_fp8_f32 v186, v248, v249 op_sel:[0,0,1]
	v_lshlrev_b32_e32 v245, 16, v126
	v_and_b32_e32 v246, 0xffff0000, v126
	v_mul_f32_e32 v245, 0x41000000, v245
	v_mul_f32_e32 v246, 0x41000000, v246
	v_lshlrev_b32_e32 v248, 16, v127
	v_and_b32_e32 v249, 0xffff0000, v127
	v_cvt_pk_fp8_f32 v187, v245, v246
	v_mul_f32_e32 v248, 0x41000000, v248
	v_mul_f32_e32 v249, 0x41000000, v249
	s_nop 0
	v_cvt_pk_fp8_f32 v187, v248, v249 op_sel:[0,0,1]
	v_lshlrev_b32_e32 v245, 16, v128
	v_and_b32_e32 v246, 0xffff0000, v128
	v_mul_f32_e32 v245, 0x41000000, v245
	v_mul_f32_e32 v246, 0x41000000, v246
	v_lshlrev_b32_e32 v248, 16, v129
	v_and_b32_e32 v249, 0xffff0000, v129
	v_cvt_pk_fp8_f32 v188, v245, v246
	v_mul_f32_e32 v248, 0x41000000, v248
	v_mul_f32_e32 v249, 0x41000000, v249
	s_nop 0
	v_cvt_pk_fp8_f32 v188, v248, v249 op_sel:[0,0,1]
	v_lshlrev_b32_e32 v245, 16, v130
	v_and_b32_e32 v246, 0xffff0000, v130
	v_mul_f32_e32 v245, 0x41000000, v245
	v_mul_f32_e32 v246, 0x41000000, v246
	v_lshlrev_b32_e32 v248, 16, v131
	v_and_b32_e32 v249, 0xffff0000, v131
	v_cvt_pk_fp8_f32 v189, v245, v246
	v_mul_f32_e32 v248, 0x41000000, v248
	v_mul_f32_e32 v249, 0x41000000, v249
	s_nop 0
	v_cvt_pk_fp8_f32 v189, v248, v249 op_sel:[0,0,1]
	v_mov_b64_e32 v[100:101], 0
	v_mov_b64_e32 v[102:103], 0
	v_mov_b64_e32 v[104:105], 0
	v_mov_b64_e32 v[106:107], 0
	v_mov_b64_e32 v[108:109], 0
	v_mov_b64_e32 v[110:111], 0
	v_mov_b64_e32 v[112:113], 0
	v_mov_b64_e32 v[114:115], 0
	v_mov_b32_e32 v190, 0
	v_mov_b32_e32 v252, v81
	v_mov_b32_e32 v194, 0
	v_mov_b64_e32 v[116:117], 0
	v_mov_b64_e32 v[118:119], 0
	v_mov_b64_e32 v[120:121], 0
	v_mov_b64_e32 v[122:123], 0
	v_mov_b64_e32 v[124:125], 0
	v_mov_b64_e32 v[126:127], 0
	v_mov_b64_e32 v[128:129], 0
	v_mov_b64_e32 v[130:131], 0
	v_mov_b32_e32 v191, 0
	v_mov_b32_e32 v253, v81
	v_mov_b32_e32 v195, 0
	v_mov_b64_e32 v[132:133], 0
	v_mov_b64_e32 v[134:135], 0
	v_mov_b64_e32 v[136:137], 0
	v_mov_b64_e32 v[138:139], 0
	v_mov_b64_e32 v[140:141], 0
	v_mov_b64_e32 v[142:143], 0
	v_mov_b64_e32 v[144:145], 0
	v_mov_b64_e32 v[146:147], 0
	v_mov_b32_e32 v192, 0
	v_mov_b32_e32 v254, v81
	v_mov_b32_e32 v196, 0
	v_mov_b64_e32 v[148:149], 0
	v_mov_b64_e32 v[150:151], 0
	v_mov_b64_e32 v[152:153], 0
	v_mov_b64_e32 v[154:155], 0
	v_mov_b64_e32 v[156:157], 0
	v_mov_b64_e32 v[158:159], 0
	v_mov_b64_e32 v[160:161], 0
	v_mov_b64_e32 v[162:163], 0
	v_mov_b32_e32 v193, 0
	v_mov_b32_e32 v255, v81
	v_mov_b32_e32 v197, 0
	v_mov_b32_e32 v77, 0xff800000
	v_mov_b32_e32 v78, 0xff800000
	s_waitcnt lgkmcnt(0)
	s_mov_b32 s35, 0
	s_lshl_b32 s13, s35, 2
	s_add_i32 s13, s13, s96
	v_mov_b32_e32 v76, s13
	ds_read_b32 v76, v76 offset:16384
	s_add_i32 s14, s25, -1
	s_min_i32 s14, s14, 1
	s_waitcnt lgkmcnt(0)
	v_readfirstlane_b32 s13, v76
	s_and_b32 s54, s13, 0xffff
	s_lshr_b32 s48, s13, 16
	s_lshl_b32 s13, s14, 2
	s_add_i32 s13, s13, s96
	v_mov_b32_e32 v76, s13
	ds_read_b32 v76, v76 offset:16384
	s_lshl_b32 s12, s54, 12
	s_add_u32 s30, s46, s12
	s_addc_u32 s31, s47, 0
	global_load_dwordx4 v[2:5], v79, s[30:31]
	global_load_dwordx4 v[6:9], v79, s[30:31] offset:1024
	global_load_dwordx4 v[12:15], v79, s[30:31] offset:2048
	global_load_dwordx4 v[16:19], v79, s[30:31] offset:3072
	s_lshl_b32 s12, s54, 12
	s_add_u32 s30, s62, s12
	s_addc_u32 s31, s63, 0
	global_load_dwordx4 v[36:39], v79, s[30:31]
	global_load_dwordx4 v[40:43], v79, s[30:31] offset:1024
	global_load_dwordx4 v[44:47], v79, s[30:31] offset:2048
	global_load_dwordx4 v[48:51], v79, s[30:31] offset:3072
	s_waitcnt lgkmcnt(0)
	v_readfirstlane_b32 s13, v76
	s_and_b32 s15, s13, 0xffff
	s_lshr_b32 s27, s13, 16
	s_add_i32 s83, s25, -1
	s_min_i32 s83, s83, 2
	s_lshl_b32 s83, s83, 2
	s_add_i32 s83, s83, s96
	v_mov_b32_e32 v76, s83
	ds_read_b32 v76, v76 offset:16384
	s_lshl_b32 s83, s15, 12
	s_add_u32 s30, s46, s83
	s_addc_u32 s31, s47, 0
	global_load_dwordx4 v[20:23], v79, s[30:31]
	global_load_dwordx4 v[24:27], v79, s[30:31] offset:1024
	global_load_dwordx4 v[28:31], v79, s[30:31] offset:2048
	global_load_dwordx4 v[32:35], v79, s[30:31] offset:3072
	s_waitcnt lgkmcnt(0)
	v_readfirstlane_b32 s13, v76
	s_and_b32 s32, s13, 0xffff
	s_lshr_b32 s55, s13, 16
	v_readfirstlane_b32 s83, v1
	s_bitcmp1_b32 s83, 8
	s_cbranch_scc0 .Lbm2_nostag
	s_sleep 4
.Lbm2_nostag:
.Lbm2_blkA:
	s_lshl_b32 s12, s15, 12
	s_add_u32 s30, s62, s12
	s_addc_u32 s31, s63, 0
	global_load_dwordx4 v[52:55], v79, s[30:31]
	global_load_dwordx4 v[56:59], v79, s[30:31] offset:1024
	global_load_dwordx4 v[60:63], v79, s[30:31] offset:2048
	global_load_dwordx4 v[64:67], v79, s[30:31] offset:3072
	s_add_i32 s14, s35, 3
	s_add_i32 s13, s25, -1
	s_min_i32 s14, s14, s13
	s_lshl_b32 s13, s14, 2
	s_add_i32 s13, s13, s96
	v_mov_b32_e32 v76, s13
	ds_read_b32 v76, v76 offset:16384
	s_cmp_ge_i32 s54, s21
	s_cselect_b32 s14, 1, 0
	s_bfe_u32 s29, s48, 0x40000
	s_cmp_eq_u32 s29, 0
	s_cbranch_scc1 .Lbm2_Ag0_skip
	s_waitcnt vmcnt(12)
	v_mfma_f32_16x16x32_fp8_fp8 v[84:87], v[2:3], v[164:165], 0
	v_mfma_f32_16x16x32_fp8_fp8 v[84:87], v[4:5], v[166:167], v[84:87]
	v_mfma_f32_16x16x32_fp8_fp8 v[88:91], v[6:7], v[164:165], 0
	v_mfma_f32_16x16x32_fp8_fp8 v[88:91], v[8:9], v[166:167], v[88:91]
	s_lshl_b32 s98, s29, 3
	s_lshl_b32 s18, s29, 6
	s_or_b32 s98, s98, s29
	s_or_b32 s98, s98, s18
	s_lshl_b32 s18, s29, 9
	s_or_b32 s98, s98, s18
	s_and_b32 s98, s98, 0x1111
	s_mul_i32 s98, s98, 15
	s_lshl_b32 s18, s98, 16
	s_or_b32 s18, s18, s98
	s_mov_b32 s19, s18
	s_cmp_eq_u32 s14, 1
	s_cbranch_scc1 .Lbm2_Ag0_near0
	v_cndmask_b32_e64 v200, v77, v252, s[18:19]
	s_cmp_eq_u32 s35, 0
	s_cbranch_scc1 .Lbm2_Ag0_first0
	v_mfma_f32_16x16x32_fp8_fp8 v[92:95], v[12:13], v[164:165], 0
	v_mfma_f32_16x16x32_fp8_fp8 v[92:95], v[14:15], v[166:167], v[92:95]
	v_pk_fma_f32 v[84:85], v[84:85], s[16:17], v[200:201] op_sel_hi:[1,1,0]
	v_pk_fma_f32 v[86:87], v[86:87], s[16:17], v[200:201] op_sel_hi:[1,1,0]
	v_mfma_f32_16x16x32_fp8_fp8 v[96:99], v[16:17], v[164:165], 0
	v_mfma_f32_16x16x32_fp8_fp8 v[96:99], v[18:19], v[166:167], v[96:99]
	v_exp_f32_e32 v84, v84
	v_exp_f32_e32 v85, v85
	v_exp_f32_e32 v86, v86
	v_exp_f32_e32 v87, v87
	v_pk_fma_f32 v[88:89], v[88:89], s[16:17], v[200:201] op_sel_hi:[1,1,0]
	v_pk_fma_f32 v[90:91], v[90:91], s[16:17], v[200:201] op_sel_hi:[1,1,0]
	v_exp_f32_e32 v88, v88
	v_exp_f32_e32 v89, v89
	v_exp_f32_e32 v90, v90
	v_exp_f32_e32 v91, v91
	v_pk_fma_f32 v[92:93], v[92:93], s[16:17], v[200:201] op_sel_hi:[1,1,0]
	v_pk_fma_f32 v[94:95], v[94:95], s[16:17], v[200:201] op_sel_hi:[1,1,0]
	v_pk_fma_f32 v[96:97], v[96:97], s[16:17], v[200:201] op_sel_hi:[1,1,0]
	v_pk_fma_f32 v[98:99], v[98:99], s[16:17], v[200:201] op_sel_hi:[1,1,0]
	v_exp_f32_e32 v92, v92
	v_exp_f32_e32 v93, v93
	v_exp_f32_e32 v94, v94
	v_exp_f32_e32 v95, v95
	s_nop 0
	v_exp_f32_e32 v96, v96
	v_exp_f32_e32 v97, v97
	v_exp_f32_e32 v98, v98
	v_exp_f32_e32 v99, v99
	v_pk_add_f32 v[248:249], v[84:85], v[86:87]
	v_pk_add_f32 v[82:83], v[88:89], v[90:91]
	v_pk_add_f32 v[172:173], v[92:93], v[94:95]
	v_pk_add_f32 v[202:203], v[96:97], v[98:99]
	v_cvt_pk_fp8_f32 v84, v84, v85
	v_cvt_pk_fp8_f32 v85, v88, v89
	v_pk_add_f32 v[248:249], v[248:249], v[82:83]
	v_pk_add_f32 v[172:173], v[172:173], v[202:203]
	v_cvt_pk_fp8_f32 v84, v86, v87 op_sel:[0,0,1]
	v_cvt_pk_fp8_f32 v85, v90, v91 op_sel:[0,0,1]
	v_pk_add_f32 v[248:249], v[248:249], v[172:173]
	v_cvt_pk_fp8_f32 v86, v92, v93
	v_cvt_pk_fp8_f32 v87, v96, v97
	v_add_f32_e32 v248, v248, v249
	v_cvt_pk_fp8_f32 v86, v94, v95 op_sel:[0,0,1]
	v_cvt_pk_fp8_f32 v87, v98, v99 op_sel:[0,0,1]
	v_cmp_lt_f32_e32 vcc, 0x43800000, v248
	s_cbranch_vccnz .Lbm2_Ag0_redo
	s_lshr_b32 s83, s48, 4
	s_cmp_lg_u32 s83, 0
	s_cbranch_scc1 .Lbm2_Ag0_ks0
	s_lshl_b32 s83, s32, 12
	s_add_u32 s30, s46, s83
	s_addc_u32 s31, s47, 0
	global_load_dwordx4 v[2:5], v79, s[30:31]
	global_load_dwordx4 v[6:9], v79, s[30:31] offset:1024
	global_load_dwordx4 v[12:15], v79, s[30:31] offset:2048
	global_load_dwordx4 v[16:19], v79, s[30:31] offset:3072

.Lbm2_Ag0_resc:
	v_mov_b32_e32 v199, v198
	s_nop 1
	v_permlane16_swap_b32_e32 v198, v199
	s_nop 0
	v_max_f32_e32 v198, v198, v199
	v_mov_b32_e32 v199, v198
	s_nop 1
	v_permlane32_swap_b32_e32 v198, v199
	s_nop 0
	v_max_f32_e32 v198, v198, v199
	v_max_f32_e32 v248, 0, v198
	v_max_f32_e32 v249, v198, v78
	v_exp_f32_e64 v248, -v248
	v_sub_f32_e32 v190, v190, v249
	v_sub_f32_e32 v252, v252, v249
	v_sub_f32_e32 v84, v84, v249
	v_sub_f32_e32 v85, v85, v249
	v_sub_f32_e32 v86, v86, v249
	v_sub_f32_e32 v87, v87, v249
	v_sub_f32_e32 v88, v88, v249
	v_sub_f32_e32 v89, v89, v249
	v_sub_f32_e32 v90, v90, v249
	v_sub_f32_e32 v91, v91, v249
	v_sub_f32_e32 v92, v92, v249
	v_sub_f32_e32 v93, v93, v249
	v_sub_f32_e32 v94, v94, v249
	v_sub_f32_e32 v95, v95, v249
	v_sub_f32_e32 v96, v96, v249
	v_sub_f32_e32 v97, v97, v249
	v_sub_f32_e32 v98, v98, v249
	v_sub_f32_e32 v99, v99, v249
	v_mul_f32_e32 v194, v194, v248
	v_pk_mul_f32 v[100:101], v[100:101], v[248:249] op_sel_hi:[1,0]
	v_pk_mul_f32 v[102:103], v[102:103], v[248:249] op_sel_hi:[1,0]
	v_pk_mul_f32 v[104:105], v[104:105], v[248:249] op_sel_hi:[1,0]
	v_pk_mul_f32 v[106:107], v[106:107], v[248:249] op_sel_hi:[1,0]
	v_pk_mul_f32 v[108:109], v[108:109], v[248:249] op_sel_hi:[1,0]
	v_pk_mul_f32 v[110:111], v[110:111], v[248:249] op_sel_hi:[1,0]
	v_pk_mul_f32 v[112:113], v[112:113], v[248:249] op_sel_hi:[1,0]
	v_pk_mul_f32 v[114:115], v[114:115], v[248:249] op_sel_hi:[1,0]
	s_branch .Lbm2_Ag0_exp

.Lbm2_Ag0_near:
	s_lshl_b32 s13, s54, 6
	s_sub_i32 s13, s97, s13
	v_and_b32_e32 v245, 15, v181
	v_lshrrev_b32_e32 v246, 4, v181
	v_lshrrev_b32_e32 v245, 2, v245
	v_lshlrev_b32_e32 v246, 2, v246
	v_cndmask_b32_e64 v200, v77, v190, s[18:19]
	v_sub_u32_e32 v245, v245, v246
	v_add_u32_e32 v198, s13, v245
	v_min_u32_e32 v82, 0x7f, v198
	v_lshl_add_u32 v82, v82, 2, v80
	ds_read_b32 v82, v82
	v_subrev_u32_e32 v245, 1, v198
	v_min_u32_e32 v83, 0x7f, v245
	v_lshl_add_u32 v83, v83, 2, v80
	ds_read_b32 v83, v83
	v_subrev_u32_e32 v245, 2, v198
	v_min_u32_e32 v172, 0x7f, v245
	v_lshl_add_u32 v172, v172, 2, v80
	ds_read_b32 v172, v172
	v_subrev_u32_e32 v245, 3, v198
	v_min_u32_e32 v173, 0x7f, v245
	v_lshl_add_u32 v173, v173, 2, v80
	ds_read_b32 v173, v173
	v_subrev_u32_e32 v245, 16, v198
	v_min_u32_e32 v202, 0x7f, v245
	v_lshl_add_u32 v202, v202, 2, v80
	ds_read_b32 v202, v202
	v_subrev_u32_e32 v245, 17, v198
	v_min_u32_e32 v203, 0x7f, v245
	v_lshl_add_u32 v203, v203, 2, v80
	ds_read_b32 v203, v203
	v_subrev_u32_e32 v245, 18, v198
	v_min_u32_e32 v228, 0x7f, v245
	v_lshl_add_u32 v228, v228, 2, v80
	ds_read_b32 v228, v228
	v_subrev_u32_e32 v245, 19, v198
	v_min_u32_e32 v229, 0x7f, v245
	v_lshl_add_u32 v229, v229, 2, v80
	ds_read_b32 v229, v229
	s_waitcnt lgkmcnt(0)
	v_fmamk_f32 v82, v82, 0x3fb8aa3b, v200
	v_cmp_le_i32_e32 vcc, 0, v198
	v_fmamk_f32 v84, v84, 0x3e38aa3b, v82
	s_nop 0
	v_cndmask_b32_e32 v84, v77, v84, vcc
	v_fmamk_f32 v83, v83, 0x3fb8aa3b, v200
	v_cmp_le_i32_e32 vcc, 1, v198
	v_fmamk_f32 v85, v85, 0x3e38aa3b, v83
	s_nop 0
	v_cndmask_b32_e32 v85, v77, v85, vcc
	v_fmamk_f32 v172, v172, 0x3fb8aa3b, v200
	v_cmp_le_i32_e32 vcc, 2, v198
	v_fmamk_f32 v86, v86, 0x3e38aa3b, v172
	s_nop 0
	v_cndmask_b32_e32 v86, v77, v86, vcc
	v_fmamk_f32 v173, v173, 0x3fb8aa3b, v200
	v_cmp_le_i32_e32 vcc, 3, v198
	v_fmamk_f32 v87, v87, 0x3e38aa3b, v173
	s_nop 0
	v_cndmask_b32_e32 v87, v77, v87, vcc
	v_fmamk_f32 v202, v202, 0x3fb8aa3b, v200
	v_cmp_le_i32_e32 vcc, 16, v198
	v_fmamk_f32 v88, v88, 0x3e38aa3b, v202
	s_nop 0
	v_cndmask_b32_e32 v88, v77, v88, vcc
	v_fmamk_f32 v203, v203, 0x3fb8aa3b, v200
	v_cmp_le_i32_e32 vcc, 17, v198
	v_fmamk_f32 v89, v89, 0x3e38aa3b, v203
	s_nop 0
	v_cndmask_b32_e32 v89, v77, v89, vcc
	v_fmamk_f32 v228, v228, 0x3fb8aa3b, v200
	v_cmp_le_i32_e32 vcc, 18, v198
	v_fmamk_f32 v90, v90, 0x3e38aa3b, v228
	s_nop 0
	v_cndmask_b32_e32 v90, v77, v90, vcc
	v_fmamk_f32 v229, v229, 0x3fb8aa3b, v200
	v_cmp_le_i32_e32 vcc, 19, v198
	v_fmamk_f32 v91, v91, 0x3e38aa3b, v229
	s_nop 0
	v_cndmask_b32_e32 v91, v77, v91, vcc
	v_subrev_u32_e32 v245, 32, v198
	v_min_u32_e32 v82, 0x7f, v245
	v_lshl_add_u32 v82, v82, 2, v80
	ds_read_b32 v82, v82
	v_subrev_u32_e32 v245, 33, v198
	v_min_u32_e32 v83, 0x7f, v245
	v_lshl_add_u32 v83, v83, 2, v80
	ds_read_b32 v83, v83
	v_subrev_u32_e32 v245, 34, v198
	v_min_u32_e32 v172, 0x7f, v245
	v_lshl_add_u32 v172, v172, 2, v80
	ds_read_b32 v172, v172
	v_subrev_u32_e32 v245, 35, v198
	v_min_u32_e32 v173, 0x7f, v245
	v_lshl_add_u32 v173, v173, 2, v80
	ds_read_b32 v173, v173
	v_subrev_u32_e32 v245, 48, v198
	v_min_u32_e32 v202, 0x7f, v245
	v_lshl_add_u32 v202, v202, 2, v80
	ds_read_b32 v202, v202
	v_subrev_u32_e32 v245, 49, v198
	v_min_u32_e32 v203, 0x7f, v245
	v_lshl_add_u32 v203, v203, 2, v80
	ds_read_b32 v203, v203
	v_subrev_u32_e32 v245, 50, v198
	v_min_u32_e32 v228, 0x7f, v245
	v_lshl_add_u32 v228, v228, 2, v80
	ds_read_b32 v228, v228
	v_subrev_u32_e32 v245, 51, v198
	v_min_u32_e32 v229, 0x7f, v245
	v_lshl_add_u32 v229, v229, 2, v80
	ds_read_b32 v229, v229
	s_waitcnt lgkmcnt(0)
	v_fmamk_f32 v82, v82, 0x3fb8aa3b, v200
	v_cmp_le_i32_e32 vcc, 32, v198
	v_fmamk_f32 v92, v92, 0x3e38aa3b, v82
	s_nop 0
	v_cndmask_b32_e32 v92, v77, v92, vcc
	v_fmamk_f32 v83, v83, 0x3fb8aa3b, v200
	v_cmp_le_i32_e32 vcc, 33, v198
	v_fmamk_f32 v93, v93, 0x3e38aa3b, v83
	s_nop 0
	v_cndmask_b32_e32 v93, v77, v93, vcc
	v_fmamk_f32 v172, v172, 0x3fb8aa3b, v200
	v_cmp_le_i32_e32 vcc, 34, v198
	v_fmamk_f32 v94, v94, 0x3e38aa3b, v172
	s_nop 0
	v_cndmask_b32_e32 v94, v77, v94, vcc
	v_fmamk_f32 v173, v173, 0x3fb8aa3b, v200
	v_cmp_le_i32_e32 vcc, 35, v198
	v_fmamk_f32 v95, v95, 0x3e38aa3b, v173
	s_nop 0
	v_cndmask_b32_e32 v95, v77, v95, vcc
	v_fmamk_f32 v202, v202, 0x3fb8aa3b, v200
	v_cmp_le_i32_e32 vcc, 48, v198
	v_fmamk_f32 v96, v96, 0x3e38aa3b, v202
	s_nop 0
	v_cndmask_b32_e32 v96, v77, v96, vcc
	v_fmamk_f32 v203, v203, 0x3fb8aa3b, v200
	v_cmp_le_i32_e32 vcc, 49, v198
	v_fmamk_f32 v97, v97, 0x3e38aa3b, v203
	s_nop 0
	v_cndmask_b32_e32 v97, v77, v97, vcc
	v_fmamk_f32 v228, v228, 0x3fb8aa3b, v200
	v_cmp_le_i32_e32 vcc, 50, v198
	v_fmamk_f32 v98, v98, 0x3e38aa3b, v228
	s_nop 0
	v_cndmask_b32_e32 v98, v77, v98, vcc
	v_fmamk_f32 v229, v229, 0x3fb8aa3b, v200
	v_cmp_le_i32_e32 vcc, 51, v198
	v_fmamk_f32 v99, v99, 0x3e38aa3b, v229
	s_nop 0
	v_cndmask_b32_e32 v99, v77, v99, vcc
	s_branch .Lbm2_Ag0_max
.Lbm2_Ag0_skip:
	s_bfe_u32 s29, s48, 0x40004
	s_cmp_eq_u32 s29, 0
	s_cbranch_scc1 .Lbm2_Ag1_skip
	s_waitcnt vmcnt(12)
	v_mfma_f32_16x16x32_fp8_fp8 v[84:87], v[2:3], v[168:169], 0
	v_mfma_f32_16x16x32_fp8_fp8 v[84:87], v[4:5], v[170:171], v[84:87]
	v_mfma_f32_16x16x32_fp8_fp8 v[88:91], v[6:7], v[168:169], 0
	v_mfma_f32_16x16x32_fp8_fp8 v[88:91], v[8:9], v[170:171], v[88:91]
	s_lshl_b32 s98, s29, 3
	s_lshl_b32 s18, s29, 6
	s_or_b32 s98, s98, s29
	s_or_b32 s98, s98, s18
	s_lshl_b32 s18, s29, 9
	s_or_b32 s98, s98, s18
	s_and_b32 s98, s98, 0x1111
	s_mul_i32 s98, s98, 15
	s_lshl_b32 s18, s98, 16
	s_or_b32 s18, s18, s98
	s_mov_b32 s19, s18
	s_cmp_eq_u32 s14, 1
	s_cbranch_scc1 .Lbm2_Ag1_near0
	v_cndmask_b32_e64 v200, v77, v253, s[18:19]
	s_cmp_eq_u32 s35, 0
	s_cbranch_scc1 .Lbm2_Ag1_first0
	v_mfma_f32_16x16x32_fp8_fp8 v[92:95], v[12:13], v[168:169], 0
	v_mfma_f32_16x16x32_fp8_fp8 v[92:95], v[14:15], v[170:171], v[92:95]
	v_pk_fma_f32 v[84:85], v[84:85], s[16:17], v[200:201] op_sel_hi:[1,1,0]
	v_pk_fma_f32 v[86:87], v[86:87], s[16:17], v[200:201] op_sel_hi:[1,1,0]
	v_mfma_f32_16x16x32_fp8_fp8 v[96:99], v[16:17], v[168:169], 0
	v_mfma_f32_16x16x32_fp8_fp8 v[96:99], v[18:19], v[170:171], v[96:99]
	v_exp_f32_e32 v84, v84
	v_exp_f32_e32 v85, v85
	v_exp_f32_e32 v86, v86
	v_exp_f32_e32 v87, v87
	v_pk_fma_f32 v[88:89], v[88:89], s[16:17], v[200:201] op_sel_hi:[1,1,0]
	v_pk_fma_f32 v[90:91], v[90:91], s[16:17], v[200:201] op_sel_hi:[1,1,0]
	v_exp_f32_e32 v88, v88
	v_exp_f32_e32 v89, v89
	v_exp_f32_e32 v90, v90
	v_exp_f32_e32 v91, v91
	v_pk_fma_f32 v[92:93], v[92:93], s[16:17], v[200:201] op_sel_hi:[1,1,0]
	v_pk_fma_f32 v[94:95], v[94:95], s[16:17], v[200:201] op_sel_hi:[1,1,0]
	v_pk_fma_f32 v[96:97], v[96:97], s[16:17], v[200:201] op_sel_hi:[1,1,0]
	v_pk_fma_f32 v[98:99], v[98:99], s[16:17], v[200:201] op_sel_hi:[1,1,0]
	v_exp_f32_e32 v92, v92
	v_exp_f32_e32 v93, v93
	v_exp_f32_e32 v94, v94
	v_exp_f32_e32 v95, v95
	s_nop 0
	v_exp_f32_e32 v96, v96
	v_exp_f32_e32 v97, v97
	v_exp_f32_e32 v98, v98
	v_exp_f32_e32 v99, v99
	v_pk_add_f32 v[248:249], v[84:85], v[86:87]
	v_pk_add_f32 v[82:83], v[88:89], v[90:91]
	v_pk_add_f32 v[172:173], v[92:93], v[94:95]
	v_pk_add_f32 v[202:203], v[96:97], v[98:99]
	v_cvt_pk_fp8_f32 v84, v84, v85
	v_cvt_pk_fp8_f32 v85, v88, v89
	v_pk_add_f32 v[248:249], v[248:249], v[82:83]
	v_pk_add_f32 v[172:173], v[172:173], v[202:203]
	v_cvt_pk_fp8_f32 v84, v86, v87 op_sel:[0,0,1]
	v_cvt_pk_fp8_f32 v85, v90, v91 op_sel:[0,0,1]
	v_pk_add_f32 v[248:249], v[248:249], v[172:173]
	v_cvt_pk_fp8_f32 v86, v92, v93
	v_cvt_pk_fp8_f32 v87, v96, v97
	v_add_f32_e32 v248, v248, v249
	v_cvt_pk_fp8_f32 v86, v94, v95 op_sel:[0,0,1]
	v_cvt_pk_fp8_f32 v87, v98, v99 op_sel:[0,0,1]
	v_cmp_lt_f32_e32 vcc, 0x43800000, v248
	s_cbranch_vccnz .Lbm2_Ag1_redo
	s_lshr_b32 s83, s48, 8
	s_cmp_lg_u32 s83, 0
	s_cbranch_scc1 .Lbm2_Ag1_ks0
	s_lshl_b32 s83, s32, 12
	s_add_u32 s30, s46, s83
	s_addc_u32 s31, s47, 0
	global_load_dwordx4 v[2:5], v79, s[30:31]
	global_load_dwordx4 v[6:9], v79, s[30:31] offset:1024
	global_load_dwordx4 v[12:15], v79, s[30:31] offset:2048
	global_load_dwordx4 v[16:19], v79, s[30:31] offset:3072

.Lbm2_Ag1_resc:
	v_mov_b32_e32 v199, v198
	s_nop 1
	v_permlane16_swap_b32_e32 v198, v199
	s_nop 0
	v_max_f32_e32 v198, v198, v199
	v_mov_b32_e32 v199, v198
	s_nop 1
	v_permlane32_swap_b32_e32 v198, v199
	s_nop 0
	v_max_f32_e32 v198, v198, v199
	v_max_f32_e32 v248, 0, v198
	v_max_f32_e32 v249, v198, v78
	v_exp_f32_e64 v248, -v248
	v_sub_f32_e32 v191, v191, v249
	v_sub_f32_e32 v253, v253, v249
	v_sub_f32_e32 v84, v84, v249
	v_sub_f32_e32 v85, v85, v249
	v_sub_f32_e32 v86, v86, v249
	v_sub_f32_e32 v87, v87, v249
	v_sub_f32_e32 v88, v88, v249
	v_sub_f32_e32 v89, v89, v249
	v_sub_f32_e32 v90, v90, v249
	v_sub_f32_e32 v91, v91, v249
	v_sub_f32_e32 v92, v92, v249
	v_sub_f32_e32 v93, v93, v249
	v_sub_f32_e32 v94, v94, v249
	v_sub_f32_e32 v95, v95, v249
	v_sub_f32_e32 v96, v96, v249
	v_sub_f32_e32 v97, v97, v249
	v_sub_f32_e32 v98, v98, v249
	v_sub_f32_e32 v99, v99, v249
	v_mul_f32_e32 v195, v195, v248
	v_pk_mul_f32 v[116:117], v[116:117], v[248:249] op_sel_hi:[1,0]
	v_pk_mul_f32 v[118:119], v[118:119], v[248:249] op_sel_hi:[1,0]
	v_pk_mul_f32 v[120:121], v[120:121], v[248:249] op_sel_hi:[1,0]
	v_pk_mul_f32 v[122:123], v[122:123], v[248:249] op_sel_hi:[1,0]
	v_pk_mul_f32 v[124:125], v[124:125], v[248:249] op_sel_hi:[1,0]
	v_pk_mul_f32 v[126:127], v[126:127], v[248:249] op_sel_hi:[1,0]
	v_pk_mul_f32 v[128:129], v[128:129], v[248:249] op_sel_hi:[1,0]
	v_pk_mul_f32 v[130:131], v[130:131], v[248:249] op_sel_hi:[1,0]
	s_branch .Lbm2_Ag1_exp

.Lbm2_Ag1_near:
	s_lshl_b32 s13, s54, 6
	s_sub_i32 s13, s97, s13
	s_add_i32 s13, s13, 4
	v_and_b32_e32 v245, 15, v181
	v_lshrrev_b32_e32 v246, 4, v181
	v_lshrrev_b32_e32 v245, 2, v245
	v_lshlrev_b32_e32 v246, 2, v246
	v_cndmask_b32_e64 v200, v77, v191, s[18:19]
	v_sub_u32_e32 v245, v245, v246
	v_add_u32_e32 v198, s13, v245
	v_min_u32_e32 v82, 0x7f, v198
	v_lshl_add_u32 v82, v82, 2, v80
	ds_read_b32 v82, v82
	v_subrev_u32_e32 v245, 1, v198
	v_min_u32_e32 v83, 0x7f, v245
	v_lshl_add_u32 v83, v83, 2, v80
	ds_read_b32 v83, v83
	v_subrev_u32_e32 v245, 2, v198
	v_min_u32_e32 v172, 0x7f, v245
	v_lshl_add_u32 v172, v172, 2, v80
	ds_read_b32 v172, v172
	v_subrev_u32_e32 v245, 3, v198
	v_min_u32_e32 v173, 0x7f, v245
	v_lshl_add_u32 v173, v173, 2, v80
	ds_read_b32 v173, v173
	v_subrev_u32_e32 v245, 16, v198
	v_min_u32_e32 v202, 0x7f, v245
	v_lshl_add_u32 v202, v202, 2, v80
	ds_read_b32 v202, v202
	v_subrev_u32_e32 v245, 17, v198
	v_min_u32_e32 v203, 0x7f, v245
	v_lshl_add_u32 v203, v203, 2, v80
	ds_read_b32 v203, v203
	v_subrev_u32_e32 v245, 18, v198
	v_min_u32_e32 v228, 0x7f, v245
	v_lshl_add_u32 v228, v228, 2, v80
	ds_read_b32 v228, v228
	v_subrev_u32_e32 v245, 19, v198
	v_min_u32_e32 v229, 0x7f, v245
	v_lshl_add_u32 v229, v229, 2, v80
	ds_read_b32 v229, v229
	s_waitcnt lgkmcnt(0)
	v_fmamk_f32 v82, v82, 0x3fb8aa3b, v200
	v_cmp_le_i32_e32 vcc, 0, v198
	v_fmamk_f32 v84, v84, 0x3e38aa3b, v82
	s_nop 0
	v_cndmask_b32_e32 v84, v77, v84, vcc
	v_fmamk_f32 v83, v83, 0x3fb8aa3b, v200
	v_cmp_le_i32_e32 vcc, 1, v198
	v_fmamk_f32 v85, v85, 0x3e38aa3b, v83
	s_nop 0
	v_cndmask_b32_e32 v85, v77, v85, vcc
	v_fmamk_f32 v172, v172, 0x3fb8aa3b, v200
	v_cmp_le_i32_e32 vcc, 2, v198
	v_fmamk_f32 v86, v86, 0x3e38aa3b, v172
	s_nop 0
	v_cndmask_b32_e32 v86, v77, v86, vcc
	v_fmamk_f32 v173, v173, 0x3fb8aa3b, v200
	v_cmp_le_i32_e32 vcc, 3, v198
	v_fmamk_f32 v87, v87, 0x3e38aa3b, v173
	s_nop 0
	v_cndmask_b32_e32 v87, v77, v87, vcc
	v_fmamk_f32 v202, v202, 0x3fb8aa3b, v200
	v_cmp_le_i32_e32 vcc, 16, v198
	v_fmamk_f32 v88, v88, 0x3e38aa3b, v202
	s_nop 0
	v_cndmask_b32_e32 v88, v77, v88, vcc
	v_fmamk_f32 v203, v203, 0x3fb8aa3b, v200
	v_cmp_le_i32_e32 vcc, 17, v198
	v_fmamk_f32 v89, v89, 0x3e38aa3b, v203
	s_nop 0
	v_cndmask_b32_e32 v89, v77, v89, vcc
	v_fmamk_f32 v228, v228, 0x3fb8aa3b, v200
	v_cmp_le_i32_e32 vcc, 18, v198
	v_fmamk_f32 v90, v90, 0x3e38aa3b, v228
	s_nop 0
	v_cndmask_b32_e32 v90, v77, v90, vcc
	v_fmamk_f32 v229, v229, 0x3fb8aa3b, v200
	v_cmp_le_i32_e32 vcc, 19, v198
	v_fmamk_f32 v91, v91, 0x3e38aa3b, v229
	s_nop 0
	v_cndmask_b32_e32 v91, v77, v91, vcc
	v_subrev_u32_e32 v245, 32, v198
	v_min_u32_e32 v82, 0x7f, v245
	v_lshl_add_u32 v82, v82, 2, v80
	ds_read_b32 v82, v82
	v_subrev_u32_e32 v245, 33, v198
	v_min_u32_e32 v83, 0x7f, v245
	v_lshl_add_u32 v83, v83, 2, v80
	ds_read_b32 v83, v83
	v_subrev_u32_e32 v245, 34, v198
	v_min_u32_e32 v172, 0x7f, v245
	v_lshl_add_u32 v172, v172, 2, v80
	ds_read_b32 v172, v172
	v_subrev_u32_e32 v245, 35, v198
	v_min_u32_e32 v173, 0x7f, v245
	v_lshl_add_u32 v173, v173, 2, v80
	ds_read_b32 v173, v173
	v_subrev_u32_e32 v245, 48, v198
	v_min_u32_e32 v202, 0x7f, v245
	v_lshl_add_u32 v202, v202, 2, v80
	ds_read_b32 v202, v202
	v_subrev_u32_e32 v245, 49, v198
	v_min_u32_e32 v203, 0x7f, v245
	v_lshl_add_u32 v203, v203, 2, v80
	ds_read_b32 v203, v203
	v_subrev_u32_e32 v245, 50, v198
	v_min_u32_e32 v228, 0x7f, v245
	v_lshl_add_u32 v228, v228, 2, v80
	ds_read_b32 v228, v228
	v_subrev_u32_e32 v245, 51, v198
	v_min_u32_e32 v229, 0x7f, v245
	v_lshl_add_u32 v229, v229, 2, v80
	ds_read_b32 v229, v229
	s_waitcnt lgkmcnt(0)
	v_fmamk_f32 v82, v82, 0x3fb8aa3b, v200
	v_cmp_le_i32_e32 vcc, 32, v198
	v_fmamk_f32 v92, v92, 0x3e38aa3b, v82
	s_nop 0
	v_cndmask_b32_e32 v92, v77, v92, vcc
	v_fmamk_f32 v83, v83, 0x3fb8aa3b, v200
	v_cmp_le_i32_e32 vcc, 33, v198
	v_fmamk_f32 v93, v93, 0x3e38aa3b, v83
	s_nop 0
	v_cndmask_b32_e32 v93, v77, v93, vcc
	v_fmamk_f32 v172, v172, 0x3fb8aa3b, v200
	v_cmp_le_i32_e32 vcc, 34, v198
	v_fmamk_f32 v94, v94, 0x3e38aa3b, v172
	s_nop 0
	v_cndmask_b32_e32 v94, v77, v94, vcc
	v_fmamk_f32 v173, v173, 0x3fb8aa3b, v200
	v_cmp_le_i32_e32 vcc, 35, v198
	v_fmamk_f32 v95, v95, 0x3e38aa3b, v173
	s_nop 0
	v_cndmask_b32_e32 v95, v77, v95, vcc
	v_fmamk_f32 v202, v202, 0x3fb8aa3b, v200
	v_cmp_le_i32_e32 vcc, 48, v198
	v_fmamk_f32 v96, v96, 0x3e38aa3b, v202
	s_nop 0
	v_cndmask_b32_e32 v96, v77, v96, vcc
	v_fmamk_f32 v203, v203, 0x3fb8aa3b, v200
	v_cmp_le_i32_e32 vcc, 49, v198
	v_fmamk_f32 v97, v97, 0x3e38aa3b, v203
	s_nop 0
	v_cndmask_b32_e32 v97, v77, v97, vcc
	v_fmamk_f32 v228, v228, 0x3fb8aa3b, v200
	v_cmp_le_i32_e32 vcc, 50, v198
	v_fmamk_f32 v98, v98, 0x3e38aa3b, v228
	s_nop 0
	v_cndmask_b32_e32 v98, v77, v98, vcc
	v_fmamk_f32 v229, v229, 0x3fb8aa3b, v200
	v_cmp_le_i32_e32 vcc, 51, v198
	v_fmamk_f32 v99, v99, 0x3e38aa3b, v229
	s_nop 0
	v_cndmask_b32_e32 v99, v77, v99, vcc
	s_branch .Lbm2_Ag1_max
.Lbm2_Ag1_skip:
	s_bfe_u32 s29, s48, 0x40008
	s_cmp_eq_u32 s29, 0
	s_cbranch_scc1 .Lbm2_Ag2_skip
	s_waitcnt vmcnt(12)
	v_mfma_f32_16x16x32_fp8_fp8 v[84:87], v[2:3], v[182:183], 0
	v_mfma_f32_16x16x32_fp8_fp8 v[84:87], v[4:5], v[184:185], v[84:87]
	v_mfma_f32_16x16x32_fp8_fp8 v[88:91], v[6:7], v[182:183], 0
	v_mfma_f32_16x16x32_fp8_fp8 v[88:91], v[8:9], v[184:185], v[88:91]
	s_lshl_b32 s98, s29, 3
	s_lshl_b32 s18, s29, 6
	s_or_b32 s98, s98, s29
	s_or_b32 s98, s98, s18
	s_lshl_b32 s18, s29, 9
	s_or_b32 s98, s98, s18
	s_and_b32 s98, s98, 0x1111
	s_mul_i32 s98, s98, 15
	s_lshl_b32 s18, s98, 16
	s_or_b32 s18, s18, s98
	s_mov_b32 s19, s18
	s_cmp_eq_u32 s14, 1
	s_cbranch_scc1 .Lbm2_Ag2_near0
	v_cndmask_b32_e64 v200, v77, v254, s[18:19]
	s_cmp_eq_u32 s35, 0
	s_cbranch_scc1 .Lbm2_Ag2_first0
	v_mfma_f32_16x16x32_fp8_fp8 v[92:95], v[12:13], v[182:183], 0
	v_mfma_f32_16x16x32_fp8_fp8 v[92:95], v[14:15], v[184:185], v[92:95]
	v_pk_fma_f32 v[84:85], v[84:85], s[16:17], v[200:201] op_sel_hi:[1,1,0]
	v_pk_fma_f32 v[86:87], v[86:87], s[16:17], v[200:201] op_sel_hi:[1,1,0]
	v_mfma_f32_16x16x32_fp8_fp8 v[96:99], v[16:17], v[182:183], 0
	v_mfma_f32_16x16x32_fp8_fp8 v[96:99], v[18:19], v[184:185], v[96:99]
	v_exp_f32_e32 v84, v84
	v_exp_f32_e32 v85, v85
	v_exp_f32_e32 v86, v86
	v_exp_f32_e32 v87, v87
	v_pk_fma_f32 v[88:89], v[88:89], s[16:17], v[200:201] op_sel_hi:[1,1,0]
	v_pk_fma_f32 v[90:91], v[90:91], s[16:17], v[200:201] op_sel_hi:[1,1,0]
	v_exp_f32_e32 v88, v88
	v_exp_f32_e32 v89, v89
	v_exp_f32_e32 v90, v90
	v_exp_f32_e32 v91, v91
	v_pk_fma_f32 v[92:93], v[92:93], s[16:17], v[200:201] op_sel_hi:[1,1,0]
	v_pk_fma_f32 v[94:95], v[94:95], s[16:17], v[200:201] op_sel_hi:[1,1,0]
	v_pk_fma_f32 v[96:97], v[96:97], s[16:17], v[200:201] op_sel_hi:[1,1,0]
	v_pk_fma_f32 v[98:99], v[98:99], s[16:17], v[200:201] op_sel_hi:[1,1,0]
	v_exp_f32_e32 v92, v92
	v_exp_f32_e32 v93, v93
	v_exp_f32_e32 v94, v94
	v_exp_f32_e32 v95, v95
	s_nop 0
	v_exp_f32_e32 v96, v96
	v_exp_f32_e32 v97, v97
	v_exp_f32_e32 v98, v98
	v_exp_f32_e32 v99, v99
	v_pk_add_f32 v[248:249], v[84:85], v[86:87]
	v_pk_add_f32 v[82:83], v[88:89], v[90:91]
	v_pk_add_f32 v[172:173], v[92:93], v[94:95]
	v_pk_add_f32 v[202:203], v[96:97], v[98:99]
	v_cvt_pk_fp8_f32 v84, v84, v85
	v_cvt_pk_fp8_f32 v85, v88, v89
	v_pk_add_f32 v[248:249], v[248:249], v[82:83]
	v_pk_add_f32 v[172:173], v[172:173], v[202:203]
	v_cvt_pk_fp8_f32 v84, v86, v87 op_sel:[0,0,1]
	v_cvt_pk_fp8_f32 v85, v90, v91 op_sel:[0,0,1]
	v_pk_add_f32 v[248:249], v[248:249], v[172:173]
	v_cvt_pk_fp8_f32 v86, v92, v93
	v_cvt_pk_fp8_f32 v87, v96, v97
	v_add_f32_e32 v248, v248, v249
	v_cvt_pk_fp8_f32 v86, v94, v95 op_sel:[0,0,1]
	v_cvt_pk_fp8_f32 v87, v98, v99 op_sel:[0,0,1]
	v_cmp_lt_f32_e32 vcc, 0x43800000, v248
	s_cbranch_vccnz .Lbm2_Ag2_redo
	s_lshr_b32 s83, s48, 12
	s_cmp_lg_u32 s83, 0
	s_cbranch_scc1 .Lbm2_Ag2_ks0
	s_lshl_b32 s83, s32, 12
	s_add_u32 s30, s46, s83
	s_addc_u32 s31, s47, 0
	global_load_dwordx4 v[2:5], v79, s[30:31]
	global_load_dwordx4 v[6:9], v79, s[30:31] offset:1024
	global_load_dwordx4 v[12:15], v79, s[30:31] offset:2048
	global_load_dwordx4 v[16:19], v79, s[30:31] offset:3072

.Lbm2_Ag2_resc:
	v_mov_b32_e32 v199, v198
	s_nop 1
	v_permlane16_swap_b32_e32 v198, v199
	s_nop 0
	v_max_f32_e32 v198, v198, v199
	v_mov_b32_e32 v199, v198
	s_nop 1
	v_permlane32_swap_b32_e32 v198, v199
	s_nop 0
	v_max_f32_e32 v198, v198, v199
	v_max_f32_e32 v248, 0, v198
	v_max_f32_e32 v249, v198, v78
	v_exp_f32_e64 v248, -v248
	v_sub_f32_e32 v192, v192, v249
	v_sub_f32_e32 v254, v254, v249
	v_sub_f32_e32 v84, v84, v249
	v_sub_f32_e32 v85, v85, v249
	v_sub_f32_e32 v86, v86, v249
	v_sub_f32_e32 v87, v87, v249
	v_sub_f32_e32 v88, v88, v249
	v_sub_f32_e32 v89, v89, v249
	v_sub_f32_e32 v90, v90, v249
	v_sub_f32_e32 v91, v91, v249
	v_sub_f32_e32 v92, v92, v249
	v_sub_f32_e32 v93, v93, v249
	v_sub_f32_e32 v94, v94, v249
	v_sub_f32_e32 v95, v95, v249
	v_sub_f32_e32 v96, v96, v249
	v_sub_f32_e32 v97, v97, v249
	v_sub_f32_e32 v98, v98, v249
	v_sub_f32_e32 v99, v99, v249
	v_mul_f32_e32 v196, v196, v248
	v_pk_mul_f32 v[132:133], v[132:133], v[248:249] op_sel_hi:[1,0]
	v_pk_mul_f32 v[134:135], v[134:135], v[248:249] op_sel_hi:[1,0]
	v_pk_mul_f32 v[136:137], v[136:137], v[248:249] op_sel_hi:[1,0]
	v_pk_mul_f32 v[138:139], v[138:139], v[248:249] op_sel_hi:[1,0]
	v_pk_mul_f32 v[140:141], v[140:141], v[248:249] op_sel_hi:[1,0]
	v_pk_mul_f32 v[142:143], v[142:143], v[248:249] op_sel_hi:[1,0]
	v_pk_mul_f32 v[144:145], v[144:145], v[248:249] op_sel_hi:[1,0]
	v_pk_mul_f32 v[146:147], v[146:147], v[248:249] op_sel_hi:[1,0]
	s_branch .Lbm2_Ag2_exp

.Lbm2_Ag2_near:
	s_lshl_b32 s13, s54, 6
	s_sub_i32 s13, s97, s13
	s_add_i32 s13, s13, 8
	v_and_b32_e32 v245, 15, v181
	v_lshrrev_b32_e32 v246, 4, v181
	v_lshrrev_b32_e32 v245, 2, v245
	v_lshlrev_b32_e32 v246, 2, v246
	v_cndmask_b32_e64 v200, v77, v192, s[18:19]
	v_sub_u32_e32 v245, v245, v246
	v_add_u32_e32 v198, s13, v245
	v_min_u32_e32 v82, 0x7f, v198
	v_lshl_add_u32 v82, v82, 2, v80
	ds_read_b32 v82, v82
	v_subrev_u32_e32 v245, 1, v198
	v_min_u32_e32 v83, 0x7f, v245
	v_lshl_add_u32 v83, v83, 2, v80
	ds_read_b32 v83, v83
	v_subrev_u32_e32 v245, 2, v198
	v_min_u32_e32 v172, 0x7f, v245
	v_lshl_add_u32 v172, v172, 2, v80
	ds_read_b32 v172, v172
	v_subrev_u32_e32 v245, 3, v198
	v_min_u32_e32 v173, 0x7f, v245
	v_lshl_add_u32 v173, v173, 2, v80
	ds_read_b32 v173, v173
	v_subrev_u32_e32 v245, 16, v198
	v_min_u32_e32 v202, 0x7f, v245
	v_lshl_add_u32 v202, v202, 2, v80
	ds_read_b32 v202, v202
	v_subrev_u32_e32 v245, 17, v198
	v_min_u32_e32 v203, 0x7f, v245
	v_lshl_add_u32 v203, v203, 2, v80
	ds_read_b32 v203, v203
	v_subrev_u32_e32 v245, 18, v198
	v_min_u32_e32 v228, 0x7f, v245
	v_lshl_add_u32 v228, v228, 2, v80
	ds_read_b32 v228, v228
	v_subrev_u32_e32 v245, 19, v198
	v_min_u32_e32 v229, 0x7f, v245
	v_lshl_add_u32 v229, v229, 2, v80
	ds_read_b32 v229, v229
	s_waitcnt lgkmcnt(0)
	v_fmamk_f32 v82, v82, 0x3fb8aa3b, v200
	v_cmp_le_i32_e32 vcc, 0, v198
	v_fmamk_f32 v84, v84, 0x3e38aa3b, v82
	s_nop 0
	v_cndmask_b32_e32 v84, v77, v84, vcc
	v_fmamk_f32 v83, v83, 0x3fb8aa3b, v200
	v_cmp_le_i32_e32 vcc, 1, v198
	v_fmamk_f32 v85, v85, 0x3e38aa3b, v83
	s_nop 0
	v_cndmask_b32_e32 v85, v77, v85, vcc
	v_fmamk_f32 v172, v172, 0x3fb8aa3b, v200
	v_cmp_le_i32_e32 vcc, 2, v198
	v_fmamk_f32 v86, v86, 0x3e38aa3b, v172
	s_nop 0
	v_cndmask_b32_e32 v86, v77, v86, vcc
	v_fmamk_f32 v173, v173, 0x3fb8aa3b, v200
	v_cmp_le_i32_e32 vcc, 3, v198
	v_fmamk_f32 v87, v87, 0x3e38aa3b, v173
	s_nop 0
	v_cndmask_b32_e32 v87, v77, v87, vcc
	v_fmamk_f32 v202, v202, 0x3fb8aa3b, v200
	v_cmp_le_i32_e32 vcc, 16, v198
	v_fmamk_f32 v88, v88, 0x3e38aa3b, v202
	s_nop 0
	v_cndmask_b32_e32 v88, v77, v88, vcc
	v_fmamk_f32 v203, v203, 0x3fb8aa3b, v200
	v_cmp_le_i32_e32 vcc, 17, v198
	v_fmamk_f32 v89, v89, 0x3e38aa3b, v203
	s_nop 0
	v_cndmask_b32_e32 v89, v77, v89, vcc
	v_fmamk_f32 v228, v228, 0x3fb8aa3b, v200
	v_cmp_le_i32_e32 vcc, 18, v198
	v_fmamk_f32 v90, v90, 0x3e38aa3b, v228
	s_nop 0
	v_cndmask_b32_e32 v90, v77, v90, vcc
	v_fmamk_f32 v229, v229, 0x3fb8aa3b, v200
	v_cmp_le_i32_e32 vcc, 19, v198
	v_fmamk_f32 v91, v91, 0x3e38aa3b, v229
	s_nop 0
	v_cndmask_b32_e32 v91, v77, v91, vcc
	v_subrev_u32_e32 v245, 32, v198
	v_min_u32_e32 v82, 0x7f, v245
	v_lshl_add_u32 v82, v82, 2, v80
	ds_read_b32 v82, v82
	v_subrev_u32_e32 v245, 33, v198
	v_min_u32_e32 v83, 0x7f, v245
	v_lshl_add_u32 v83, v83, 2, v80
	ds_read_b32 v83, v83
	v_subrev_u32_e32 v245, 34, v198
	v_min_u32_e32 v172, 0x7f, v245
	v_lshl_add_u32 v172, v172, 2, v80
	ds_read_b32 v172, v172
	v_subrev_u32_e32 v245, 35, v198
	v_min_u32_e32 v173, 0x7f, v245
	v_lshl_add_u32 v173, v173, 2, v80
	ds_read_b32 v173, v173
	v_subrev_u32_e32 v245, 48, v198
	v_min_u32_e32 v202, 0x7f, v245
	v_lshl_add_u32 v202, v202, 2, v80
	ds_read_b32 v202, v202
	v_subrev_u32_e32 v245, 49, v198
	v_min_u32_e32 v203, 0x7f, v245
	v_lshl_add_u32 v203, v203, 2, v80
	ds_read_b32 v203, v203
	v_subrev_u32_e32 v245, 50, v198
	v_min_u32_e32 v228, 0x7f, v245
	v_lshl_add_u32 v228, v228, 2, v80
	ds_read_b32 v228, v228
	v_subrev_u32_e32 v245, 51, v198
	v_min_u32_e32 v229, 0x7f, v245
	v_lshl_add_u32 v229, v229, 2, v80
	ds_read_b32 v229, v229
	s_waitcnt lgkmcnt(0)
	v_fmamk_f32 v82, v82, 0x3fb8aa3b, v200
	v_cmp_le_i32_e32 vcc, 32, v198
	v_fmamk_f32 v92, v92, 0x3e38aa3b, v82
	s_nop 0
	v_cndmask_b32_e32 v92, v77, v92, vcc
	v_fmamk_f32 v83, v83, 0x3fb8aa3b, v200
	v_cmp_le_i32_e32 vcc, 33, v198
	v_fmamk_f32 v93, v93, 0x3e38aa3b, v83
	s_nop 0
	v_cndmask_b32_e32 v93, v77, v93, vcc
	v_fmamk_f32 v172, v172, 0x3fb8aa3b, v200
	v_cmp_le_i32_e32 vcc, 34, v198
	v_fmamk_f32 v94, v94, 0x3e38aa3b, v172
	s_nop 0
	v_cndmask_b32_e32 v94, v77, v94, vcc
	v_fmamk_f32 v173, v173, 0x3fb8aa3b, v200
	v_cmp_le_i32_e32 vcc, 35, v198
	v_fmamk_f32 v95, v95, 0x3e38aa3b, v173
	s_nop 0
	v_cndmask_b32_e32 v95, v77, v95, vcc
	v_fmamk_f32 v202, v202, 0x3fb8aa3b, v200
	v_cmp_le_i32_e32 vcc, 48, v198
	v_fmamk_f32 v96, v96, 0x3e38aa3b, v202
	s_nop 0
	v_cndmask_b32_e32 v96, v77, v96, vcc
	v_fmamk_f32 v203, v203, 0x3fb8aa3b, v200
	v_cmp_le_i32_e32 vcc, 49, v198
	v_fmamk_f32 v97, v97, 0x3e38aa3b, v203
	s_nop 0
	v_cndmask_b32_e32 v97, v77, v97, vcc
	v_fmamk_f32 v228, v228, 0x3fb8aa3b, v200
	v_cmp_le_i32_e32 vcc, 50, v198
	v_fmamk_f32 v98, v98, 0x3e38aa3b, v228
	s_nop 0
	v_cndmask_b32_e32 v98, v77, v98, vcc
	v_fmamk_f32 v229, v229, 0x3fb8aa3b, v200
	v_cmp_le_i32_e32 vcc, 51, v198
	v_fmamk_f32 v99, v99, 0x3e38aa3b, v229
	s_nop 0
	v_cndmask_b32_e32 v99, v77, v99, vcc
	s_branch .Lbm2_Ag2_max
.Lbm2_Ag2_skip:
	s_bfe_u32 s29, s48, 0x4000c
	s_cmp_eq_u32 s29, 0
	s_cbranch_scc1 .Lbm2_Ag3_skip
	s_waitcnt vmcnt(12)
	v_mfma_f32_16x16x32_fp8_fp8 v[84:87], v[2:3], v[186:187], 0
	v_mfma_f32_16x16x32_fp8_fp8 v[84:87], v[4:5], v[188:189], v[84:87]
	v_mfma_f32_16x16x32_fp8_fp8 v[88:91], v[6:7], v[186:187], 0
	v_mfma_f32_16x16x32_fp8_fp8 v[88:91], v[8:9], v[188:189], v[88:91]
	s_lshl_b32 s98, s29, 3
	s_lshl_b32 s18, s29, 6
	s_or_b32 s98, s98, s29
	s_or_b32 s98, s98, s18
	s_lshl_b32 s18, s29, 9
	s_or_b32 s98, s98, s18
	s_and_b32 s98, s98, 0x1111
	s_mul_i32 s98, s98, 15
	s_lshl_b32 s18, s98, 16
	s_or_b32 s18, s18, s98
	s_mov_b32 s19, s18
	s_cmp_eq_u32 s14, 1
	s_cbranch_scc1 .Lbm2_Ag3_near0
	v_cndmask_b32_e64 v200, v77, v255, s[18:19]
	s_cmp_eq_u32 s35, 0
	s_cbranch_scc1 .Lbm2_Ag3_first0
	v_mfma_f32_16x16x32_fp8_fp8 v[92:95], v[12:13], v[186:187], 0
	v_mfma_f32_16x16x32_fp8_fp8 v[92:95], v[14:15], v[188:189], v[92:95]
	v_pk_fma_f32 v[84:85], v[84:85], s[16:17], v[200:201] op_sel_hi:[1,1,0]
	v_pk_fma_f32 v[86:87], v[86:87], s[16:17], v[200:201] op_sel_hi:[1,1,0]
	v_mfma_f32_16x16x32_fp8_fp8 v[96:99], v[16:17], v[186:187], 0
	v_mfma_f32_16x16x32_fp8_fp8 v[96:99], v[18:19], v[188:189], v[96:99]
	v_exp_f32_e32 v84, v84
	v_exp_f32_e32 v85, v85
	v_exp_f32_e32 v86, v86
	v_exp_f32_e32 v87, v87
	v_pk_fma_f32 v[88:89], v[88:89], s[16:17], v[200:201] op_sel_hi:[1,1,0]
	v_pk_fma_f32 v[90:91], v[90:91], s[16:17], v[200:201] op_sel_hi:[1,1,0]
	v_exp_f32_e32 v88, v88
	v_exp_f32_e32 v89, v89
	v_exp_f32_e32 v90, v90
	v_exp_f32_e32 v91, v91
	v_pk_fma_f32 v[92:93], v[92:93], s[16:17], v[200:201] op_sel_hi:[1,1,0]
	v_pk_fma_f32 v[94:95], v[94:95], s[16:17], v[200:201] op_sel_hi:[1,1,0]
	v_pk_fma_f32 v[96:97], v[96:97], s[16:17], v[200:201] op_sel_hi:[1,1,0]
	v_pk_fma_f32 v[98:99], v[98:99], s[16:17], v[200:201] op_sel_hi:[1,1,0]
	v_exp_f32_e32 v92, v92
	v_exp_f32_e32 v93, v93
	v_exp_f32_e32 v94, v94
	v_exp_f32_e32 v95, v95
	s_nop 0
	v_exp_f32_e32 v96, v96
	v_exp_f32_e32 v97, v97
	v_exp_f32_e32 v98, v98
	v_exp_f32_e32 v99, v99
	v_pk_add_f32 v[248:249], v[84:85], v[86:87]
	v_pk_add_f32 v[82:83], v[88:89], v[90:91]
	v_pk_add_f32 v[172:173], v[92:93], v[94:95]
	v_pk_add_f32 v[202:203], v[96:97], v[98:99]
	v_cvt_pk_fp8_f32 v84, v84, v85
	v_cvt_pk_fp8_f32 v85, v88, v89
	v_pk_add_f32 v[248:249], v[248:249], v[82:83]
	v_pk_add_f32 v[172:173], v[172:173], v[202:203]
	v_cvt_pk_fp8_f32 v84, v86, v87 op_sel:[0,0,1]
	v_cvt_pk_fp8_f32 v85, v90, v91 op_sel:[0,0,1]
	v_pk_add_f32 v[248:249], v[248:249], v[172:173]
	v_cvt_pk_fp8_f32 v86, v92, v93
	v_cvt_pk_fp8_f32 v87, v96, v97
	v_add_f32_e32 v248, v248, v249
	v_cvt_pk_fp8_f32 v86, v94, v95 op_sel:[0,0,1]
	v_cvt_pk_fp8_f32 v87, v98, v99 op_sel:[0,0,1]
	v_cmp_lt_f32_e32 vcc, 0x43800000, v248
	s_cbranch_vccnz .Lbm2_Ag3_redo
	s_lshl_b32 s83, s32, 12
	s_add_u32 s30, s46, s83
	s_addc_u32 s31, s47, 0
	global_load_dwordx4 v[2:5], v79, s[30:31]
	global_load_dwordx4 v[6:9], v79, s[30:31] offset:1024
	global_load_dwordx4 v[12:15], v79, s[30:31] offset:2048
	global_load_dwordx4 v[16:19], v79, s[30:31] offset:3072
	v_add_f32_e32 v197, v197, v248
	s_waitcnt vmcnt(8)
	v_mfma_f32_16x16x32_fp8_fp8 v[148:151], v[36:37], v[84:85], v[148:151]
	v_mfma_f32_16x16x32_fp8_fp8 v[152:155], v[38:39], v[84:85], v[152:155]
	v_mfma_f32_16x16x32_fp8_fp8 v[156:159], v[40:41], v[84:85], v[156:159]
	v_mfma_f32_16x16x32_fp8_fp8 v[160:163], v[42:43], v[84:85], v[160:163]
	v_mfma_f32_16x16x32_fp8_fp8 v[148:151], v[44:45], v[86:87], v[148:151]
	v_mfma_f32_16x16x32_fp8_fp8 v[152:155], v[46:47], v[86:87], v[152:155]
	v_mfma_f32_16x16x32_fp8_fp8 v[156:159], v[48:49], v[86:87], v[156:159]
	v_mfma_f32_16x16x32_fp8_fp8 v[160:163], v[50:51], v[86:87], v[160:163]
	s_branch .Lbm2_Ag3_skip

.Lbm2_Ag3_resc:
	v_mov_b32_e32 v199, v198
	s_nop 1
	v_permlane16_swap_b32_e32 v198, v199
	s_nop 0
	v_max_f32_e32 v198, v198, v199
	v_mov_b32_e32 v199, v198
	s_nop 1
	v_permlane32_swap_b32_e32 v198, v199
	s_nop 0
	v_max_f32_e32 v198, v198, v199
	v_max_f32_e32 v248, 0, v198
	v_max_f32_e32 v249, v198, v78
	v_exp_f32_e64 v248, -v248
	v_sub_f32_e32 v193, v193, v249
	v_sub_f32_e32 v255, v255, v249
	v_sub_f32_e32 v84, v84, v249
	v_sub_f32_e32 v85, v85, v249
	v_sub_f32_e32 v86, v86, v249
	v_sub_f32_e32 v87, v87, v249
	v_sub_f32_e32 v88, v88, v249
	v_sub_f32_e32 v89, v89, v249
	v_sub_f32_e32 v90, v90, v249
	v_sub_f32_e32 v91, v91, v249
	v_sub_f32_e32 v92, v92, v249
	v_sub_f32_e32 v93, v93, v249
	v_sub_f32_e32 v94, v94, v249
	v_sub_f32_e32 v95, v95, v249
	v_sub_f32_e32 v96, v96, v249
	v_sub_f32_e32 v97, v97, v249
	v_sub_f32_e32 v98, v98, v249
	v_sub_f32_e32 v99, v99, v249
	v_mul_f32_e32 v197, v197, v248
	v_pk_mul_f32 v[148:149], v[148:149], v[248:249] op_sel_hi:[1,0]
	v_pk_mul_f32 v[150:151], v[150:151], v[248:249] op_sel_hi:[1,0]
	v_pk_mul_f32 v[152:153], v[152:153], v[248:249] op_sel_hi:[1,0]
	v_pk_mul_f32 v[154:155], v[154:155], v[248:249] op_sel_hi:[1,0]
	v_pk_mul_f32 v[156:157], v[156:157], v[248:249] op_sel_hi:[1,0]
	v_pk_mul_f32 v[158:159], v[158:159], v[248:249] op_sel_hi:[1,0]
	v_pk_mul_f32 v[160:161], v[160:161], v[248:249] op_sel_hi:[1,0]
	v_pk_mul_f32 v[162:163], v[162:163], v[248:249] op_sel_hi:[1,0]
	s_branch .Lbm2_Ag3_exp

.Lbm2_Ag3_near:
	s_lshl_b32 s13, s54, 6
	s_sub_i32 s13, s97, s13
	s_add_i32 s13, s13, 12
	v_and_b32_e32 v245, 15, v181
	v_lshrrev_b32_e32 v246, 4, v181
	v_lshrrev_b32_e32 v245, 2, v245
	v_lshlrev_b32_e32 v246, 2, v246
	v_cndmask_b32_e64 v200, v77, v193, s[18:19]
	v_sub_u32_e32 v245, v245, v246
	v_add_u32_e32 v198, s13, v245
	v_min_u32_e32 v82, 0x7f, v198
	v_lshl_add_u32 v82, v82, 2, v80
	ds_read_b32 v82, v82
	v_subrev_u32_e32 v245, 1, v198
	v_min_u32_e32 v83, 0x7f, v245
	v_lshl_add_u32 v83, v83, 2, v80
	ds_read_b32 v83, v83
	v_subrev_u32_e32 v245, 2, v198
	v_min_u32_e32 v172, 0x7f, v245
	v_lshl_add_u32 v172, v172, 2, v80
	ds_read_b32 v172, v172
	v_subrev_u32_e32 v245, 3, v198
	v_min_u32_e32 v173, 0x7f, v245
	v_lshl_add_u32 v173, v173, 2, v80
	ds_read_b32 v173, v173
	v_subrev_u32_e32 v245, 16, v198
	v_min_u32_e32 v202, 0x7f, v245
	v_lshl_add_u32 v202, v202, 2, v80
	ds_read_b32 v202, v202
	v_subrev_u32_e32 v245, 17, v198
	v_min_u32_e32 v203, 0x7f, v245
	v_lshl_add_u32 v203, v203, 2, v80
	ds_read_b32 v203, v203
	v_subrev_u32_e32 v245, 18, v198
	v_min_u32_e32 v228, 0x7f, v245
	v_lshl_add_u32 v228, v228, 2, v80
	ds_read_b32 v228, v228
	v_subrev_u32_e32 v245, 19, v198
	v_min_u32_e32 v229, 0x7f, v245
	v_lshl_add_u32 v229, v229, 2, v80
	ds_read_b32 v229, v229
	s_waitcnt lgkmcnt(0)
	v_fmamk_f32 v82, v82, 0x3fb8aa3b, v200
	v_cmp_le_i32_e32 vcc, 0, v198
	v_fmamk_f32 v84, v84, 0x3e38aa3b, v82
	s_nop 0
	v_cndmask_b32_e32 v84, v77, v84, vcc
	v_fmamk_f32 v83, v83, 0x3fb8aa3b, v200
	v_cmp_le_i32_e32 vcc, 1, v198
	v_fmamk_f32 v85, v85, 0x3e38aa3b, v83
	s_nop 0
	v_cndmask_b32_e32 v85, v77, v85, vcc
	v_fmamk_f32 v172, v172, 0x3fb8aa3b, v200
	v_cmp_le_i32_e32 vcc, 2, v198
	v_fmamk_f32 v86, v86, 0x3e38aa3b, v172
	s_nop 0
	v_cndmask_b32_e32 v86, v77, v86, vcc
	v_fmamk_f32 v173, v173, 0x3fb8aa3b, v200
	v_cmp_le_i32_e32 vcc, 3, v198
	v_fmamk_f32 v87, v87, 0x3e38aa3b, v173
	s_nop 0
	v_cndmask_b32_e32 v87, v77, v87, vcc
	v_fmamk_f32 v202, v202, 0x3fb8aa3b, v200
	v_cmp_le_i32_e32 vcc, 16, v198
	v_fmamk_f32 v88, v88, 0x3e38aa3b, v202
	s_nop 0
	v_cndmask_b32_e32 v88, v77, v88, vcc
	v_fmamk_f32 v203, v203, 0x3fb8aa3b, v200
	v_cmp_le_i32_e32 vcc, 17, v198
	v_fmamk_f32 v89, v89, 0x3e38aa3b, v203
	s_nop 0
	v_cndmask_b32_e32 v89, v77, v89, vcc
	v_fmamk_f32 v228, v228, 0x3fb8aa3b, v200
	v_cmp_le_i32_e32 vcc, 18, v198
	v_fmamk_f32 v90, v90, 0x3e38aa3b, v228
	s_nop 0
	v_cndmask_b32_e32 v90, v77, v90, vcc
	v_fmamk_f32 v229, v229, 0x3fb8aa3b, v200
	v_cmp_le_i32_e32 vcc, 19, v198
	v_fmamk_f32 v91, v91, 0x3e38aa3b, v229
	s_nop 0
	v_cndmask_b32_e32 v91, v77, v91, vcc
	v_subrev_u32_e32 v245, 32, v198
	v_min_u32_e32 v82, 0x7f, v245
	v_lshl_add_u32 v82, v82, 2, v80
	ds_read_b32 v82, v82
	v_subrev_u32_e32 v245, 33, v198
	v_min_u32_e32 v83, 0x7f, v245
	v_lshl_add_u32 v83, v83, 2, v80
	ds_read_b32 v83, v83
	v_subrev_u32_e32 v245, 34, v198
	v_min_u32_e32 v172, 0x7f, v245
	v_lshl_add_u32 v172, v172, 2, v80
	ds_read_b32 v172, v172
	v_subrev_u32_e32 v245, 35, v198
	v_min_u32_e32 v173, 0x7f, v245
	v_lshl_add_u32 v173, v173, 2, v80
	ds_read_b32 v173, v173
	v_subrev_u32_e32 v245, 48, v198
	v_min_u32_e32 v202, 0x7f, v245
	v_lshl_add_u32 v202, v202, 2, v80
	ds_read_b32 v202, v202
	v_subrev_u32_e32 v245, 49, v198
	v_min_u32_e32 v203, 0x7f, v245
	v_lshl_add_u32 v203, v203, 2, v80
	ds_read_b32 v203, v203
	v_subrev_u32_e32 v245, 50, v198
	v_min_u32_e32 v228, 0x7f, v245
	v_lshl_add_u32 v228, v228, 2, v80
	ds_read_b32 v228, v228
	v_subrev_u32_e32 v245, 51, v198
	v_min_u32_e32 v229, 0x7f, v245
	v_lshl_add_u32 v229, v229, 2, v80
	ds_read_b32 v229, v229
	s_waitcnt lgkmcnt(0)
	v_fmamk_f32 v82, v82, 0x3fb8aa3b, v200
	v_cmp_le_i32_e32 vcc, 32, v198
	v_fmamk_f32 v92, v92, 0x3e38aa3b, v82
	s_nop 0
	v_cndmask_b32_e32 v92, v77, v92, vcc
	v_fmamk_f32 v83, v83, 0x3fb8aa3b, v200
	v_cmp_le_i32_e32 vcc, 33, v198
	v_fmamk_f32 v93, v93, 0x3e38aa3b, v83
	s_nop 0
	v_cndmask_b32_e32 v93, v77, v93, vcc
	v_fmamk_f32 v172, v172, 0x3fb8aa3b, v200
	v_cmp_le_i32_e32 vcc, 34, v198
	v_fmamk_f32 v94, v94, 0x3e38aa3b, v172
	s_nop 0
	v_cndmask_b32_e32 v94, v77, v94, vcc
	v_fmamk_f32 v173, v173, 0x3fb8aa3b, v200
	v_cmp_le_i32_e32 vcc, 35, v198
	v_fmamk_f32 v95, v95, 0x3e38aa3b, v173
	s_nop 0
	v_cndmask_b32_e32 v95, v77, v95, vcc
	v_fmamk_f32 v202, v202, 0x3fb8aa3b, v200
	v_cmp_le_i32_e32 vcc, 48, v198
	v_fmamk_f32 v96, v96, 0x3e38aa3b, v202
	s_nop 0
	v_cndmask_b32_e32 v96, v77, v96, vcc
	v_fmamk_f32 v203, v203, 0x3fb8aa3b, v200
	v_cmp_le_i32_e32 vcc, 49, v198
	v_fmamk_f32 v97, v97, 0x3e38aa3b, v203
	s_nop 0
	v_cndmask_b32_e32 v97, v77, v97, vcc
	v_fmamk_f32 v228, v228, 0x3fb8aa3b, v200
	v_cmp_le_i32_e32 vcc, 50, v198
	v_fmamk_f32 v98, v98, 0x3e38aa3b, v228
	s_nop 0
	v_cndmask_b32_e32 v98, v77, v98, vcc
	v_fmamk_f32 v229, v229, 0x3fb8aa3b, v200
	v_cmp_le_i32_e32 vcc, 51, v198
	v_fmamk_f32 v99, v99, 0x3e38aa3b, v229
	s_nop 0
	v_cndmask_b32_e32 v99, v77, v99, vcc
	s_branch .Lbm2_Ag3_max

.Lbm2_blkB:
	s_lshl_b32 s12, s15, 12
	s_add_u32 s30, s62, s12
	s_addc_u32 s31, s63, 0
	global_load_dwordx4 v[36:39], v79, s[30:31]
	global_load_dwordx4 v[40:43], v79, s[30:31] offset:1024
	global_load_dwordx4 v[44:47], v79, s[30:31] offset:2048
	global_load_dwordx4 v[48:51], v79, s[30:31] offset:3072
	s_add_i32 s14, s35, 3
	s_add_i32 s13, s25, -1
	s_min_i32 s14, s14, s13
	s_lshl_b32 s13, s14, 2
	s_add_i32 s13, s13, s96
	v_mov_b32_e32 v76, s13
	ds_read_b32 v76, v76 offset:16384
	s_cmp_ge_i32 s54, s21
	s_cselect_b32 s14, 1, 0
	s_bfe_u32 s29, s48, 0x40000
	s_cmp_eq_u32 s29, 0
	s_cbranch_scc1 .Lbm2_Bg0_skip
	s_waitcnt vmcnt(12)
	v_mfma_f32_16x16x32_fp8_fp8 v[84:87], v[20:21], v[164:165], 0
	v_mfma_f32_16x16x32_fp8_fp8 v[84:87], v[22:23], v[166:167], v[84:87]
	v_mfma_f32_16x16x32_fp8_fp8 v[88:91], v[24:25], v[164:165], 0
	v_mfma_f32_16x16x32_fp8_fp8 v[88:91], v[26:27], v[166:167], v[88:91]
	s_lshl_b32 s98, s29, 3
	s_lshl_b32 s18, s29, 6
	s_or_b32 s98, s98, s29
	s_or_b32 s98, s98, s18
	s_lshl_b32 s18, s29, 9
	s_or_b32 s98, s98, s18
	s_and_b32 s98, s98, 0x1111
	s_mul_i32 s98, s98, 15
	s_lshl_b32 s18, s98, 16
	s_or_b32 s18, s18, s98
	s_mov_b32 s19, s18
	s_cmp_eq_u32 s14, 1
	s_cbranch_scc1 .Lbm2_Bg0_near0
	v_cndmask_b32_e64 v200, v77, v252, s[18:19]
	s_cmp_eq_u32 s35, 0
	s_cbranch_scc1 .Lbm2_Bg0_first0
	v_mfma_f32_16x16x32_fp8_fp8 v[92:95], v[28:29], v[164:165], 0
	v_mfma_f32_16x16x32_fp8_fp8 v[92:95], v[30:31], v[166:167], v[92:95]
	v_pk_fma_f32 v[84:85], v[84:85], s[16:17], v[200:201] op_sel_hi:[1,1,0]
	v_pk_fma_f32 v[86:87], v[86:87], s[16:17], v[200:201] op_sel_hi:[1,1,0]
	v_mfma_f32_16x16x32_fp8_fp8 v[96:99], v[32:33], v[164:165], 0
	v_mfma_f32_16x16x32_fp8_fp8 v[96:99], v[34:35], v[166:167], v[96:99]
	v_exp_f32_e32 v84, v84
	v_exp_f32_e32 v85, v85
	v_exp_f32_e32 v86, v86
	v_exp_f32_e32 v87, v87
	v_pk_fma_f32 v[88:89], v[88:89], s[16:17], v[200:201] op_sel_hi:[1,1,0]
	v_pk_fma_f32 v[90:91], v[90:91], s[16:17], v[200:201] op_sel_hi:[1,1,0]
	v_exp_f32_e32 v88, v88
	v_exp_f32_e32 v89, v89
	v_exp_f32_e32 v90, v90
	v_exp_f32_e32 v91, v91
	v_pk_fma_f32 v[92:93], v[92:93], s[16:17], v[200:201] op_sel_hi:[1,1,0]
	v_pk_fma_f32 v[94:95], v[94:95], s[16:17], v[200:201] op_sel_hi:[1,1,0]
	v_pk_fma_f32 v[96:97], v[96:97], s[16:17], v[200:201] op_sel_hi:[1,1,0]
	v_pk_fma_f32 v[98:99], v[98:99], s[16:17], v[200:201] op_sel_hi:[1,1,0]
	v_exp_f32_e32 v92, v92
	v_exp_f32_e32 v93, v93
	v_exp_f32_e32 v94, v94
	v_exp_f32_e32 v95, v95
	s_nop 0
	v_exp_f32_e32 v96, v96
	v_exp_f32_e32 v97, v97
	v_exp_f32_e32 v98, v98
	v_exp_f32_e32 v99, v99
	v_pk_add_f32 v[248:249], v[84:85], v[86:87]
	v_pk_add_f32 v[82:83], v[88:89], v[90:91]
	v_pk_add_f32 v[172:173], v[92:93], v[94:95]
	v_pk_add_f32 v[202:203], v[96:97], v[98:99]
	v_cvt_pk_fp8_f32 v84, v84, v85
	v_cvt_pk_fp8_f32 v85, v88, v89
	v_pk_add_f32 v[248:249], v[248:249], v[82:83]
	v_pk_add_f32 v[172:173], v[172:173], v[202:203]
	v_cvt_pk_fp8_f32 v84, v86, v87 op_sel:[0,0,1]
	v_cvt_pk_fp8_f32 v85, v90, v91 op_sel:[0,0,1]
	v_pk_add_f32 v[248:249], v[248:249], v[172:173]
	v_cvt_pk_fp8_f32 v86, v92, v93
	v_cvt_pk_fp8_f32 v87, v96, v97
	v_add_f32_e32 v248, v248, v249
	v_cvt_pk_fp8_f32 v86, v94, v95 op_sel:[0,0,1]
	v_cvt_pk_fp8_f32 v87, v98, v99 op_sel:[0,0,1]
	v_cmp_lt_f32_e32 vcc, 0x43800000, v248
	s_cbranch_vccnz .Lbm2_Bg0_redo
	s_lshr_b32 s83, s48, 4
	s_cmp_lg_u32 s83, 0
	s_cbranch_scc1 .Lbm2_Bg0_ks0
	s_lshl_b32 s83, s32, 12
	s_add_u32 s30, s46, s83
	s_addc_u32 s31, s47, 0
	global_load_dwordx4 v[20:23], v79, s[30:31]
	global_load_dwordx4 v[24:27], v79, s[30:31] offset:1024
	global_load_dwordx4 v[28:31], v79, s[30:31] offset:2048
	global_load_dwordx4 v[32:35], v79, s[30:31] offset:3072

.Lbm2_Bg0_skip:
	s_bfe_u32 s29, s48, 0x40004
	s_cmp_eq_u32 s29, 0
	s_cbranch_scc1 .Lbm2_Bg1_skip
	s_waitcnt vmcnt(12)
	v_mfma_f32_16x16x32_fp8_fp8 v[84:87], v[20:21], v[168:169], 0
	v_mfma_f32_16x16x32_fp8_fp8 v[84:87], v[22:23], v[170:171], v[84:87]
	v_mfma_f32_16x16x32_fp8_fp8 v[88:91], v[24:25], v[168:169], 0
	v_mfma_f32_16x16x32_fp8_fp8 v[88:91], v[26:27], v[170:171], v[88:91]
	s_lshl_b32 s98, s29, 3
	s_lshl_b32 s18, s29, 6
	s_or_b32 s98, s98, s29
	s_or_b32 s98, s98, s18
	s_lshl_b32 s18, s29, 9
	s_or_b32 s98, s98, s18
	s_and_b32 s98, s98, 0x1111
	s_mul_i32 s98, s98, 15
	s_lshl_b32 s18, s98, 16
	s_or_b32 s18, s18, s98
	s_mov_b32 s19, s18
	s_cmp_eq_u32 s14, 1
	s_cbranch_scc1 .Lbm2_Bg1_near0
	v_cndmask_b32_e64 v200, v77, v253, s[18:19]
	s_cmp_eq_u32 s35, 0
	s_cbranch_scc1 .Lbm2_Bg1_first0
	v_mfma_f32_16x16x32_fp8_fp8 v[92:95], v[28:29], v[168:169], 0
	v_mfma_f32_16x16x32_fp8_fp8 v[92:95], v[30:31], v[170:171], v[92:95]
	v_pk_fma_f32 v[84:85], v[84:85], s[16:17], v[200:201] op_sel_hi:[1,1,0]
	v_pk_fma_f32 v[86:87], v[86:87], s[16:17], v[200:201] op_sel_hi:[1,1,0]
	v_mfma_f32_16x16x32_fp8_fp8 v[96:99], v[32:33], v[168:169], 0
	v_mfma_f32_16x16x32_fp8_fp8 v[96:99], v[34:35], v[170:171], v[96:99]
	v_exp_f32_e32 v84, v84
	v_exp_f32_e32 v85, v85
	v_exp_f32_e32 v86, v86
	v_exp_f32_e32 v87, v87
	v_pk_fma_f32 v[88:89], v[88:89], s[16:17], v[200:201] op_sel_hi:[1,1,0]
	v_pk_fma_f32 v[90:91], v[90:91], s[16:17], v[200:201] op_sel_hi:[1,1,0]
	v_exp_f32_e32 v88, v88
	v_exp_f32_e32 v89, v89
	v_exp_f32_e32 v90, v90
	v_exp_f32_e32 v91, v91
	v_pk_fma_f32 v[92:93], v[92:93], s[16:17], v[200:201] op_sel_hi:[1,1,0]
	v_pk_fma_f32 v[94:95], v[94:95], s[16:17], v[200:201] op_sel_hi:[1,1,0]
	v_pk_fma_f32 v[96:97], v[96:97], s[16:17], v[200:201] op_sel_hi:[1,1,0]
	v_pk_fma_f32 v[98:99], v[98:99], s[16:17], v[200:201] op_sel_hi:[1,1,0]
	v_exp_f32_e32 v92, v92
	v_exp_f32_e32 v93, v93
	v_exp_f32_e32 v94, v94
	v_exp_f32_e32 v95, v95
	s_nop 0
	v_exp_f32_e32 v96, v96
	v_exp_f32_e32 v97, v97
	v_exp_f32_e32 v98, v98
	v_exp_f32_e32 v99, v99
	v_pk_add_f32 v[248:249], v[84:85], v[86:87]
	v_pk_add_f32 v[82:83], v[88:89], v[90:91]
	v_pk_add_f32 v[172:173], v[92:93], v[94:95]
	v_pk_add_f32 v[202:203], v[96:97], v[98:99]
	v_cvt_pk_fp8_f32 v84, v84, v85
	v_cvt_pk_fp8_f32 v85, v88, v89
	v_pk_add_f32 v[248:249], v[248:249], v[82:83]
	v_pk_add_f32 v[172:173], v[172:173], v[202:203]
	v_cvt_pk_fp8_f32 v84, v86, v87 op_sel:[0,0,1]
	v_cvt_pk_fp8_f32 v85, v90, v91 op_sel:[0,0,1]
	v_pk_add_f32 v[248:249], v[248:249], v[172:173]
	v_cvt_pk_fp8_f32 v86, v92, v93
	v_cvt_pk_fp8_f32 v87, v96, v97
	v_add_f32_e32 v248, v248, v249
	v_cvt_pk_fp8_f32 v86, v94, v95 op_sel:[0,0,1]
	v_cvt_pk_fp8_f32 v87, v98, v99 op_sel:[0,0,1]
	v_cmp_lt_f32_e32 vcc, 0x43800000, v248
	s_cbranch_vccnz .Lbm2_Bg1_redo
	s_lshr_b32 s83, s48, 8
	s_cmp_lg_u32 s83, 0
	s_cbranch_scc1 .Lbm2_Bg1_ks0
	s_lshl_b32 s83, s32, 12
	s_add_u32 s30, s46, s83
	s_addc_u32 s31, s47, 0
	global_load_dwordx4 v[20:23], v79, s[30:31]
	global_load_dwordx4 v[24:27], v79, s[30:31] offset:1024
	global_load_dwordx4 v[28:31], v79, s[30:31] offset:2048
	global_load_dwordx4 v[32:35], v79, s[30:31] offset:3072

.Lbm2_Bg1_skip:
	s_bfe_u32 s29, s48, 0x40008
	s_cmp_eq_u32 s29, 0
	s_cbranch_scc1 .Lbm2_Bg2_skip
	s_waitcnt vmcnt(12)
	v_mfma_f32_16x16x32_fp8_fp8 v[84:87], v[20:21], v[182:183], 0
	v_mfma_f32_16x16x32_fp8_fp8 v[84:87], v[22:23], v[184:185], v[84:87]
	v_mfma_f32_16x16x32_fp8_fp8 v[88:91], v[24:25], v[182:183], 0
	v_mfma_f32_16x16x32_fp8_fp8 v[88:91], v[26:27], v[184:185], v[88:91]
	s_lshl_b32 s98, s29, 3
	s_lshl_b32 s18, s29, 6
	s_or_b32 s98, s98, s29
	s_or_b32 s98, s98, s18
	s_lshl_b32 s18, s29, 9
	s_or_b32 s98, s98, s18
	s_and_b32 s98, s98, 0x1111
	s_mul_i32 s98, s98, 15
	s_lshl_b32 s18, s98, 16
	s_or_b32 s18, s18, s98
	s_mov_b32 s19, s18
	s_cmp_eq_u32 s14, 1
	s_cbranch_scc1 .Lbm2_Bg2_near0
	v_cndmask_b32_e64 v200, v77, v254, s[18:19]
	s_cmp_eq_u32 s35, 0
	s_cbranch_scc1 .Lbm2_Bg2_first0
	v_mfma_f32_16x16x32_fp8_fp8 v[92:95], v[28:29], v[182:183], 0
	v_mfma_f32_16x16x32_fp8_fp8 v[92:95], v[30:31], v[184:185], v[92:95]
	v_pk_fma_f32 v[84:85], v[84:85], s[16:17], v[200:201] op_sel_hi:[1,1,0]
	v_pk_fma_f32 v[86:87], v[86:87], s[16:17], v[200:201] op_sel_hi:[1,1,0]
	v_mfma_f32_16x16x32_fp8_fp8 v[96:99], v[32:33], v[182:183], 0
	v_mfma_f32_16x16x32_fp8_fp8 v[96:99], v[34:35], v[184:185], v[96:99]
	v_exp_f32_e32 v84, v84
	v_exp_f32_e32 v85, v85
	v_exp_f32_e32 v86, v86
	v_exp_f32_e32 v87, v87
	v_pk_fma_f32 v[88:89], v[88:89], s[16:17], v[200:201] op_sel_hi:[1,1,0]
	v_pk_fma_f32 v[90:91], v[90:91], s[16:17], v[200:201] op_sel_hi:[1,1,0]
	v_exp_f32_e32 v88, v88
	v_exp_f32_e32 v89, v89
	v_exp_f32_e32 v90, v90
	v_exp_f32_e32 v91, v91
	v_pk_fma_f32 v[92:93], v[92:93], s[16:17], v[200:201] op_sel_hi:[1,1,0]
	v_pk_fma_f32 v[94:95], v[94:95], s[16:17], v[200:201] op_sel_hi:[1,1,0]
	v_pk_fma_f32 v[96:97], v[96:97], s[16:17], v[200:201] op_sel_hi:[1,1,0]
	v_pk_fma_f32 v[98:99], v[98:99], s[16:17], v[200:201] op_sel_hi:[1,1,0]
	v_exp_f32_e32 v92, v92
	v_exp_f32_e32 v93, v93
	v_exp_f32_e32 v94, v94
	v_exp_f32_e32 v95, v95
	s_nop 0
	v_exp_f32_e32 v96, v96
	v_exp_f32_e32 v97, v97
	v_exp_f32_e32 v98, v98
	v_exp_f32_e32 v99, v99
	v_pk_add_f32 v[248:249], v[84:85], v[86:87]
	v_pk_add_f32 v[82:83], v[88:89], v[90:91]
	v_pk_add_f32 v[172:173], v[92:93], v[94:95]
	v_pk_add_f32 v[202:203], v[96:97], v[98:99]
	v_cvt_pk_fp8_f32 v84, v84, v85
	v_cvt_pk_fp8_f32 v85, v88, v89
	v_pk_add_f32 v[248:249], v[248:249], v[82:83]
	v_pk_add_f32 v[172:173], v[172:173], v[202:203]
	v_cvt_pk_fp8_f32 v84, v86, v87 op_sel:[0,0,1]
	v_cvt_pk_fp8_f32 v85, v90, v91 op_sel:[0,0,1]
	v_pk_add_f32 v[248:249], v[248:249], v[172:173]
	v_cvt_pk_fp8_f32 v86, v92, v93
	v_cvt_pk_fp8_f32 v87, v96, v97
	v_add_f32_e32 v248, v248, v249
	v_cvt_pk_fp8_f32 v86, v94, v95 op_sel:[0,0,1]
	v_cvt_pk_fp8_f32 v87, v98, v99 op_sel:[0,0,1]
	v_cmp_lt_f32_e32 vcc, 0x43800000, v248
	s_cbranch_vccnz .Lbm2_Bg2_redo
	s_lshr_b32 s83, s48, 12
	s_cmp_lg_u32 s83, 0
	s_cbranch_scc1 .Lbm2_Bg2_ks0
	s_lshl_b32 s83, s32, 12
	s_add_u32 s30, s46, s83
	s_addc_u32 s31, s47, 0
	global_load_dwordx4 v[20:23], v79, s[30:31]
	global_load_dwordx4 v[24:27], v79, s[30:31] offset:1024
	global_load_dwordx4 v[28:31], v79, s[30:31] offset:2048
	global_load_dwordx4 v[32:35], v79, s[30:31] offset:3072

.Lbm2_Bg2_skip:
	s_bfe_u32 s29, s48, 0x4000c
	s_cmp_eq_u32 s29, 0
	s_cbranch_scc1 .Lbm2_Bg3_skip
	s_waitcnt vmcnt(12)
	v_mfma_f32_16x16x32_fp8_fp8 v[84:87], v[20:21], v[186:187], 0
	v_mfma_f32_16x16x32_fp8_fp8 v[84:87], v[22:23], v[188:189], v[84:87]
	v_mfma_f32_16x16x32_fp8_fp8 v[88:91], v[24:25], v[186:187], 0
	v_mfma_f32_16x16x32_fp8_fp8 v[88:91], v[26:27], v[188:189], v[88:91]
	s_lshl_b32 s98, s29, 3
	s_lshl_b32 s18, s29, 6
	s_or_b32 s98, s98, s29
	s_or_b32 s98, s98, s18
	s_lshl_b32 s18, s29, 9
	s_or_b32 s98, s98, s18
	s_and_b32 s98, s98, 0x1111
	s_mul_i32 s98, s98, 15
	s_lshl_b32 s18, s98, 16
	s_or_b32 s18, s18, s98
	s_mov_b32 s19, s18
	s_cmp_eq_u32 s14, 1
	s_cbranch_scc1 .Lbm2_Bg3_near0
	v_cndmask_b32_e64 v200, v77, v255, s[18:19]
	s_cmp_eq_u32 s35, 0
	s_cbranch_scc1 .Lbm2_Bg3_first0
	v_mfma_f32_16x16x32_fp8_fp8 v[92:95], v[28:29], v[186:187], 0
	v_mfma_f32_16x16x32_fp8_fp8 v[92:95], v[30:31], v[188:189], v[92:95]
	v_pk_fma_f32 v[84:85], v[84:85], s[16:17], v[200:201] op_sel_hi:[1,1,0]
	v_pk_fma_f32 v[86:87], v[86:87], s[16:17], v[200:201] op_sel_hi:[1,1,0]
	v_mfma_f32_16x16x32_fp8_fp8 v[96:99], v[32:33], v[186:187], 0
	v_mfma_f32_16x16x32_fp8_fp8 v[96:99], v[34:35], v[188:189], v[96:99]
	v_exp_f32_e32 v84, v84
	v_exp_f32_e32 v85, v85
	v_exp_f32_e32 v86, v86
	v_exp_f32_e32 v87, v87
	v_pk_fma_f32 v[88:89], v[88:89], s[16:17], v[200:201] op_sel_hi:[1,1,0]
	v_pk_fma_f32 v[90:91], v[90:91], s[16:17], v[200:201] op_sel_hi:[1,1,0]
	v_exp_f32_e32 v88, v88
	v_exp_f32_e32 v89, v89
	v_exp_f32_e32 v90, v90
	v_exp_f32_e32 v91, v91
	v_pk_fma_f32 v[92:93], v[92:93], s[16:17], v[200:201] op_sel_hi:[1,1,0]
	v_pk_fma_f32 v[94:95], v[94:95], s[16:17], v[200:201] op_sel_hi:[1,1,0]
	v_pk_fma_f32 v[96:97], v[96:97], s[16:17], v[200:201] op_sel_hi:[1,1,0]
	v_pk_fma_f32 v[98:99], v[98:99], s[16:17], v[200:201] op_sel_hi:[1,1,0]
	v_exp_f32_e32 v92, v92
	v_exp_f32_e32 v93, v93
	v_exp_f32_e32 v94, v94
	v_exp_f32_e32 v95, v95
	s_nop 0
	v_exp_f32_e32 v96, v96
	v_exp_f32_e32 v97, v97
	v_exp_f32_e32 v98, v98
	v_exp_f32_e32 v99, v99
	v_pk_add_f32 v[248:249], v[84:85], v[86:87]
	v_pk_add_f32 v[82:83], v[88:89], v[90:91]
	v_pk_add_f32 v[172:173], v[92:93], v[94:95]
	v_pk_add_f32 v[202:203], v[96:97], v[98:99]
	v_cvt_pk_fp8_f32 v84, v84, v85
	v_cvt_pk_fp8_f32 v85, v88, v89
	v_pk_add_f32 v[248:249], v[248:249], v[82:83]
	v_pk_add_f32 v[172:173], v[172:173], v[202:203]
	v_cvt_pk_fp8_f32 v84, v86, v87 op_sel:[0,0,1]
	v_cvt_pk_fp8_f32 v85, v90, v91 op_sel:[0,0,1]
	v_pk_add_f32 v[248:249], v[248:249], v[172:173]
	v_cvt_pk_fp8_f32 v86, v92, v93
	v_cvt_pk_fp8_f32 v87, v96, v97
	v_add_f32_e32 v248, v248, v249
	v_cvt_pk_fp8_f32 v86, v94, v95 op_sel:[0,0,1]
	v_cvt_pk_fp8_f32 v87, v98, v99 op_sel:[0,0,1]
	v_cmp_lt_f32_e32 vcc, 0x43800000, v248
	s_cbranch_vccnz .Lbm2_Bg3_redo
	s_lshl_b32 s83, s32, 12
	s_add_u32 s30, s46, s83
	s_addc_u32 s31, s47, 0
	global_load_dwordx4 v[20:23], v79, s[30:31]
	global_load_dwordx4 v[24:27], v79, s[30:31] offset:1024
	global_load_dwordx4 v[28:31], v79, s[30:31] offset:2048
	global_load_dwordx4 v[32:35], v79, s[30:31] offset:3072
	v_add_f32_e32 v197, v197, v248
	s_waitcnt vmcnt(8)
	v_mfma_f32_16x16x32_fp8_fp8 v[148:151], v[52:53], v[84:85], v[148:151]
	v_mfma_f32_16x16x32_fp8_fp8 v[152:155], v[54:55], v[84:85], v[152:155]
	v_mfma_f32_16x16x32_fp8_fp8 v[156:159], v[56:57], v[84:85], v[156:159]
	v_mfma_f32_16x16x32_fp8_fp8 v[160:163], v[58:59], v[84:85], v[160:163]
	v_mfma_f32_16x16x32_fp8_fp8 v[148:151], v[60:61], v[86:87], v[148:151]
	v_mfma_f32_16x16x32_fp8_fp8 v[152:155], v[62:63], v[86:87], v[152:155]
	v_mfma_f32_16x16x32_fp8_fp8 v[156:159], v[64:65], v[86:87], v[156:159]
	v_mfma_f32_16x16x32_fp8_fp8 v[160:163], v[66:67], v[86:87], v[160:163]
	s_branch .Lbm2_Bg3_skip

.LBB0_2049:
.LBB0_2050:
	v_readfirstlane_b32 s40, v70
	v_readfirstlane_b32 s41, v71
	v_readfirstlane_b32 s62, v72
	v_readfirstlane_b32 s63, v73
	v_and_b32_e32 v248, 15, v181
	v_lshrrev_b32_e32 v249, 4, v181
	v_lshrrev_b32_e32 v248, 2, v248
	v_lshlrev_b32_e32 v249, 2, v249
	v_readlane_b32 s23, v243, 32
	v_mov_b32_e32 v244, 1
	v_lshlrev_b32_e32 v244, v248, v244
	s_mov_b32 s10, 0x3e38aa3b
	s_mov_b32 s11, 0x3e38aa3b
	v_lshlrev_b32_e32 v79, 4, v181
	s_add_i32 s23, s23, s47
	v_add_u32_e32 v247, s23, v248
	v_mad_u64_u32 v[250:251], s[6:7], v247, v212, v[68:69]
	global_load_dwordx4 v[100:103], v[250:251], off
	global_load_dwordx4 v[104:107], v[250:251], off offset:64
	v_add_u32_e32 v249, 4, v247
	v_mad_u64_u32 v[250:251], s[6:7], v249, v212, v[68:69]
	global_load_dwordx4 v[108:111], v[250:251], off
	global_load_dwordx4 v[112:115], v[250:251], off offset:64
	v_add_u32_e32 v249, 8, v247
	v_mad_u64_u32 v[250:251], s[6:7], v249, v212, v[68:69]
	global_load_dwordx4 v[116:119], v[250:251], off
	global_load_dwordx4 v[120:123], v[250:251], off offset:64
	v_add_u32_e32 v249, 12, v247
	v_mad_u64_u32 v[250:251], s[6:7], v249, v212, v[68:69]
	global_load_dwordx4 v[124:127], v[250:251], off
	global_load_dwordx4 v[128:131], v[250:251], off offset:64
	v_and_b32_e32 v248, 15, v181
	v_lshrrev_b32_e32 v249, 4, v181
	v_lshlrev_b32_e32 v198, 6, v248
	v_lshl_add_u32 v198, v249, 2, v198
	v_add_u32_e32 v198, s46, v198
	v_lshl_add_u32 v199, v248, 2, s46
	ds_read_b32 v12, v198 offset:16384
	ds_read_b32 v13, v198 offset:16400
	ds_read_b32 v14, v198 offset:16416
	ds_read_b32 v15, v198 offset:16432
	ds_read_b32 v16, v199 offset:17408
	v_lshl_add_u32 v199, v181, 2, s46
	v_mov_b32_e32 v17, 1
	v_lshlrev_b32_e32 v17, v248, v17
	s_waitcnt lgkmcnt(0)
	v_mul_f32_e32 v81, 0x3fb8aa3b, v81
	ds_write_b32 v199, v11 offset:16384
	ds_write_b32 v199, v11 offset:16640
	ds_write_b32 v199, v11 offset:16896
	ds_write_b32 v199, v11 offset:17152
	v_cmp_lt_i32_e32 vcc, v249, v16
	v_and_b32_e32 v12, 0xff, v12
	v_lshl_add_u32 v12, v12, 2, s46
	v_cndmask_b32_e32 v18, 0, v17, vcc
	ds_or_b32 v12, v18 offset:16384
	v_add_u32_e32 v18, 4, v249
	v_cmp_lt_i32_e32 vcc, v18, v16
	v_and_b32_e32 v13, 0xff, v13
	v_lshl_add_u32 v13, v13, 2, s46
	v_cndmask_b32_e32 v18, 0, v17, vcc
	ds_or_b32 v13, v18 offset:16384
	v_add_u32_e32 v18, 8, v249
	v_cmp_lt_i32_e32 vcc, v18, v16
	v_and_b32_e32 v14, 0xff, v14
	v_lshl_add_u32 v14, v14, 2, s46
	v_cndmask_b32_e32 v18, 0, v17, vcc
	ds_or_b32 v14, v18 offset:16384
	v_add_u32_e32 v18, 12, v249
	v_cmp_lt_i32_e32 vcc, v18, v16
	v_and_b32_e32 v15, 0xff, v15
	v_lshl_add_u32 v15, v15, 2, s46
	v_cndmask_b32_e32 v18, 0, v17, vcc
	ds_or_b32 v15, v18 offset:16384
	s_waitcnt lgkmcnt(0)
	ds_read_b32 v12, v199 offset:16384
	ds_read_b32 v13, v199 offset:16640
	ds_read_b32 v14, v199 offset:16896
	ds_read_b32 v15, v199 offset:17152
	s_mov_b32 s25, 0
	s_waitcnt lgkmcnt(0)
	v_cmp_ne_u32_e64 s[4:5], 0, v12
	v_lshlrev_b32_e32 v16, 16, v12
	v_add_u32_e32 v17, 0, v181
	v_or_b32_e32 v16, v16, v17
	v_mbcnt_lo_u32_b32 v17, s4, 0
	v_mbcnt_hi_u32_b32 v17, s5, v17
	v_add_u32_e32 v17, s25, v17
	v_lshl_add_u32 v17, v17, 2, s46
	v_add_u32_e32 v17, 0x4000, v17
	v_add_u32_e32 v18, 0x4400, v199
	s_bcnt1_i32_b64 s9, s[4:5]
	v_cndmask_b32_e64 v17, v18, v17, s[4:5]
	s_add_i32 s25, s25, s9
	ds_write_b32 v17, v16
	v_cmp_ne_u32_e64 s[4:5], 0, v13
	v_lshlrev_b32_e32 v16, 16, v13
	v_add_u32_e32 v17, 64, v181
	v_or_b32_e32 v16, v16, v17
	v_mbcnt_lo_u32_b32 v17, s4, 0
	v_mbcnt_hi_u32_b32 v17, s5, v17
	v_add_u32_e32 v17, s25, v17
	v_lshl_add_u32 v17, v17, 2, s46
	v_add_u32_e32 v17, 0x4000, v17
	v_add_u32_e32 v18, 0x4400, v199
	s_bcnt1_i32_b64 s9, s[4:5]
	v_cndmask_b32_e64 v17, v18, v17, s[4:5]
	s_add_i32 s25, s25, s9
	ds_write_b32 v17, v16
	v_cmp_ne_u32_e64 s[4:5], 0, v14
	v_lshlrev_b32_e32 v16, 16, v14
	v_add_u32_e32 v17, 128, v181
	v_or_b32_e32 v16, v16, v17
	v_mbcnt_lo_u32_b32 v17, s4, 0
	v_mbcnt_hi_u32_b32 v17, s5, v17
	v_add_u32_e32 v17, s25, v17
	v_lshl_add_u32 v17, v17, 2, s46
	v_add_u32_e32 v17, 0x4000, v17
	v_add_u32_e32 v18, 0x4400, v199
	s_bcnt1_i32_b64 s9, s[4:5]
	v_cndmask_b32_e64 v17, v18, v17, s[4:5]
	s_add_i32 s25, s25, s9
	ds_write_b32 v17, v16
	v_cmp_ne_u32_e64 s[4:5], 0, v15
	v_lshlrev_b32_e32 v16, 16, v15
	v_add_u32_e32 v17, 192, v181
	v_or_b32_e32 v16, v16, v17
	v_mbcnt_lo_u32_b32 v17, s4, 0
	v_mbcnt_hi_u32_b32 v17, s5, v17
	v_add_u32_e32 v17, s25, v17
	v_lshl_add_u32 v17, v17, 2, s46
	v_add_u32_e32 v17, 0x4000, v17
	v_add_u32_e32 v18, 0x4400, v199
	s_bcnt1_i32_b64 s9, s[4:5]
	v_cndmask_b32_e64 v17, v18, v17, s[4:5]
	s_add_i32 s25, s25, s9
	ds_write_b32 v17, v16
	s_waitcnt vmcnt(0)
	v_lshlrev_b32_e32 v245, 16, v100
	v_and_b32_e32 v246, 0xffff0000, v100
	v_mul_f32_e32 v245, 0x41000000, v245
	v_mul_f32_e32 v246, 0x41000000, v246
	v_lshlrev_b32_e32 v248, 16, v101
	v_and_b32_e32 v249, 0xffff0000, v101
	v_cvt_pk_fp8_f32 v164, v245, v246
	v_mul_f32_e32 v248, 0x41000000, v248
	v_mul_f32_e32 v249, 0x41000000, v249
	s_nop 0
	v_cvt_pk_fp8_f32 v164, v248, v249 op_sel:[0,0,1]
	v_lshlrev_b32_e32 v245, 16, v102
	v_and_b32_e32 v246, 0xffff0000, v102
	v_mul_f32_e32 v245, 0x41000000, v245
	v_mul_f32_e32 v246, 0x41000000, v246
	v_lshlrev_b32_e32 v248, 16, v103
	v_and_b32_e32 v249, 0xffff0000, v103
	v_cvt_pk_fp8_f32 v165, v245, v246
	v_mul_f32_e32 v248, 0x41000000, v248
	v_mul_f32_e32 v249, 0x41000000, v249
	s_nop 0
	v_cvt_pk_fp8_f32 v165, v248, v249 op_sel:[0,0,1]
	v_lshlrev_b32_e32 v245, 16, v104
	v_and_b32_e32 v246, 0xffff0000, v104
	v_mul_f32_e32 v245, 0x41000000, v245
	v_mul_f32_e32 v246, 0x41000000, v246
	v_lshlrev_b32_e32 v248, 16, v105
	v_and_b32_e32 v249, 0xffff0000, v105
	v_cvt_pk_fp8_f32 v166, v245, v246
	v_mul_f32_e32 v248, 0x41000000, v248
	v_mul_f32_e32 v249, 0x41000000, v249
	s_nop 0
	v_cvt_pk_fp8_f32 v166, v248, v249 op_sel:[0,0,1]
	v_lshlrev_b32_e32 v245, 16, v106
	v_and_b32_e32 v246, 0xffff0000, v106
	v_mul_f32_e32 v245, 0x41000000, v245
	v_mul_f32_e32 v246, 0x41000000, v246
	v_lshlrev_b32_e32 v248, 16, v107
	v_and_b32_e32 v249, 0xffff0000, v107
	v_cvt_pk_fp8_f32 v167, v245, v246
	v_mul_f32_e32 v248, 0x41000000, v248
	v_mul_f32_e32 v249, 0x41000000, v249
	s_nop 0
	v_cvt_pk_fp8_f32 v167, v248, v249 op_sel:[0,0,1]
	v_lshlrev_b32_e32 v245, 16, v108
	v_and_b32_e32 v246, 0xffff0000, v108
	v_mul_f32_e32 v245, 0x41000000, v245
	v_mul_f32_e32 v246, 0x41000000, v246
	v_lshlrev_b32_e32 v248, 16, v109
	v_and_b32_e32 v249, 0xffff0000, v109
	v_cvt_pk_fp8_f32 v168, v245, v246
	v_mul_f32_e32 v248, 0x41000000, v248
	v_mul_f32_e32 v249, 0x41000000, v249
	s_nop 0
	v_cvt_pk_fp8_f32 v168, v248, v249 op_sel:[0,0,1]
	v_lshlrev_b32_e32 v245, 16, v110
	v_and_b32_e32 v246, 0xffff0000, v110
	v_mul_f32_e32 v245, 0x41000000, v245
	v_mul_f32_e32 v246, 0x41000000, v246
	v_lshlrev_b32_e32 v248, 16, v111
	v_and_b32_e32 v249, 0xffff0000, v111
	v_cvt_pk_fp8_f32 v169, v245, v246
	v_mul_f32_e32 v248, 0x41000000, v248
	v_mul_f32_e32 v249, 0x41000000, v249
	s_nop 0
	v_cvt_pk_fp8_f32 v169, v248, v249 op_sel:[0,0,1]
	v_lshlrev_b32_e32 v245, 16, v112
	v_and_b32_e32 v246, 0xffff0000, v112
	v_mul_f32_e32 v245, 0x41000000, v245
	v_mul_f32_e32 v246, 0x41000000, v246
	v_lshlrev_b32_e32 v248, 16, v113
	v_and_b32_e32 v249, 0xffff0000, v113
	v_cvt_pk_fp8_f32 v170, v245, v246
	v_mul_f32_e32 v248, 0x41000000, v248
	v_mul_f32_e32 v249, 0x41000000, v249
	s_nop 0
	v_cvt_pk_fp8_f32 v170, v248, v249 op_sel:[0,0,1]
	v_lshlrev_b32_e32 v245, 16, v114
	v_and_b32_e32 v246, 0xffff0000, v114
	v_mul_f32_e32 v245, 0x41000000, v245
	v_mul_f32_e32 v246, 0x41000000, v246
	v_lshlrev_b32_e32 v248, 16, v115
	v_and_b32_e32 v249, 0xffff0000, v115
	v_cvt_pk_fp8_f32 v171, v245, v246
	v_mul_f32_e32 v248, 0x41000000, v248
	v_mul_f32_e32 v249, 0x41000000, v249
	s_nop 0
	v_cvt_pk_fp8_f32 v171, v248, v249 op_sel:[0,0,1]
	v_lshlrev_b32_e32 v245, 16, v116
	v_and_b32_e32 v246, 0xffff0000, v116
	v_mul_f32_e32 v245, 0x41000000, v245
	v_mul_f32_e32 v246, 0x41000000, v246
	v_lshlrev_b32_e32 v248, 16, v117
	v_and_b32_e32 v249, 0xffff0000, v117
	v_cvt_pk_fp8_f32 v182, v245, v246
	v_mul_f32_e32 v248, 0x41000000, v248
	v_mul_f32_e32 v249, 0x41000000, v249
	s_nop 0
	v_cvt_pk_fp8_f32 v182, v248, v249 op_sel:[0,0,1]
	v_lshlrev_b32_e32 v245, 16, v118
	v_and_b32_e32 v246, 0xffff0000, v118
	v_mul_f32_e32 v245, 0x41000000, v245
	v_mul_f32_e32 v246, 0x41000000, v246
	v_lshlrev_b32_e32 v248, 16, v119
	v_and_b32_e32 v249, 0xffff0000, v119
	v_cvt_pk_fp8_f32 v183, v245, v246
	v_mul_f32_e32 v248, 0x41000000, v248
	v_mul_f32_e32 v249, 0x41000000, v249
	s_nop 0
	v_cvt_pk_fp8_f32 v183, v248, v249 op_sel:[0,0,1]
	v_lshlrev_b32_e32 v245, 16, v120
	v_and_b32_e32 v246, 0xffff0000, v120
	v_mul_f32_e32 v245, 0x41000000, v245
	v_mul_f32_e32 v246, 0x41000000, v246
	v_lshlrev_b32_e32 v248, 16, v121
	v_and_b32_e32 v249, 0xffff0000, v121
	v_cvt_pk_fp8_f32 v184, v245, v246
	v_mul_f32_e32 v248, 0x41000000, v248
	v_mul_f32_e32 v249, 0x41000000, v249
	s_nop 0
	v_cvt_pk_fp8_f32 v184, v248, v249 op_sel:[0,0,1]
	v_lshlrev_b32_e32 v245, 16, v122
	v_and_b32_e32 v246, 0xffff0000, v122
	v_mul_f32_e32 v245, 0x41000000, v245
	v_mul_f32_e32 v246, 0x41000000, v246
	v_lshlrev_b32_e32 v248, 16, v123
	v_and_b32_e32 v249, 0xffff0000, v123
	v_cvt_pk_fp8_f32 v185, v245, v246
	v_mul_f32_e32 v248, 0x41000000, v248
	v_mul_f32_e32 v249, 0x41000000, v249
	s_nop 0
	v_cvt_pk_fp8_f32 v185, v248, v249 op_sel:[0,0,1]
	v_lshlrev_b32_e32 v245, 16, v124
	v_and_b32_e32 v246, 0xffff0000, v124
	v_mul_f32_e32 v245, 0x41000000, v245
	v_mul_f32_e32 v246, 0x41000000, v246
	v_lshlrev_b32_e32 v248, 16, v125
	v_and_b32_e32 v249, 0xffff0000, v125
	v_cvt_pk_fp8_f32 v186, v245, v246
	v_mul_f32_e32 v248, 0x41000000, v248
	v_mul_f32_e32 v249, 0x41000000, v249
	s_nop 0
	v_cvt_pk_fp8_f32 v186, v248, v249 op_sel:[0,0,1]
	v_lshlrev_b32_e32 v245, 16, v126
	v_and_b32_e32 v246, 0xffff0000, v126
	v_mul_f32_e32 v245, 0x41000000, v245
	v_mul_f32_e32 v246, 0x41000000, v246
	v_lshlrev_b32_e32 v248, 16, v127
	v_and_b32_e32 v249, 0xffff0000, v127
	v_cvt_pk_fp8_f32 v187, v245, v246
	v_mul_f32_e32 v248, 0x41000000, v248
	v_mul_f32_e32 v249, 0x41000000, v249
	s_nop 0
	v_cvt_pk_fp8_f32 v187, v248, v249 op_sel:[0,0,1]
	v_lshlrev_b32_e32 v245, 16, v128
	v_and_b32_e32 v246, 0xffff0000, v128
	v_mul_f32_e32 v245, 0x41000000, v245
	v_mul_f32_e32 v246, 0x41000000, v246
	v_lshlrev_b32_e32 v248, 16, v129
	v_and_b32_e32 v249, 0xffff0000, v129
	v_cvt_pk_fp8_f32 v188, v245, v246
	v_mul_f32_e32 v248, 0x41000000, v248
	v_mul_f32_e32 v249, 0x41000000, v249
	s_nop 0
	v_cvt_pk_fp8_f32 v188, v248, v249 op_sel:[0,0,1]
	v_lshlrev_b32_e32 v245, 16, v130
	v_and_b32_e32 v246, 0xffff0000, v130
	v_mul_f32_e32 v245, 0x41000000, v245
	v_mul_f32_e32 v246, 0x41000000, v246
	v_lshlrev_b32_e32 v248, 16, v131
	v_and_b32_e32 v249, 0xffff0000, v131
	v_cvt_pk_fp8_f32 v189, v245, v246
	v_mul_f32_e32 v248, 0x41000000, v248
	v_mul_f32_e32 v249, 0x41000000, v249
	s_nop 0
	v_cvt_pk_fp8_f32 v189, v248, v249 op_sel:[0,0,1]
	v_mov_b64_e32 v[100:101], 0
	v_mov_b64_e32 v[102:103], 0
	v_mov_b64_e32 v[104:105], 0
	v_mov_b64_e32 v[106:107], 0
	v_mov_b64_e32 v[108:109], 0
	v_mov_b64_e32 v[110:111], 0
	v_mov_b64_e32 v[112:113], 0
	v_mov_b64_e32 v[114:115], 0
	v_mov_b32_e32 v190, 0
	v_mov_b32_e32 v252, v81
	v_mov_b32_e32 v194, 0
	v_mov_b64_e32 v[116:117], 0
	v_mov_b64_e32 v[118:119], 0
	v_mov_b64_e32 v[120:121], 0
	v_mov_b64_e32 v[122:123], 0
	v_mov_b64_e32 v[124:125], 0
	v_mov_b64_e32 v[126:127], 0
	v_mov_b64_e32 v[128:129], 0
	v_mov_b64_e32 v[130:131], 0
	v_mov_b32_e32 v191, 0
	v_mov_b32_e32 v253, v81
	v_mov_b32_e32 v195, 0
	v_mov_b64_e32 v[132:133], 0
	v_mov_b64_e32 v[134:135], 0
	v_mov_b64_e32 v[136:137], 0
	v_mov_b64_e32 v[138:139], 0
	v_mov_b64_e32 v[140:141], 0
	v_mov_b64_e32 v[142:143], 0
	v_mov_b64_e32 v[144:145], 0
	v_mov_b64_e32 v[146:147], 0
	v_mov_b32_e32 v192, 0
	v_mov_b32_e32 v254, v81
	v_mov_b32_e32 v196, 0
	v_mov_b64_e32 v[148:149], 0
	v_mov_b64_e32 v[150:151], 0
	v_mov_b64_e32 v[152:153], 0
	v_mov_b64_e32 v[154:155], 0
	v_mov_b64_e32 v[156:157], 0
	v_mov_b64_e32 v[158:159], 0
	v_mov_b64_e32 v[160:161], 0
	v_mov_b64_e32 v[162:163], 0
	v_mov_b32_e32 v193, 0
	v_mov_b32_e32 v255, v81
	v_mov_b32_e32 v197, 0
	v_mov_b32_e32 v77, 0xff800000
	v_mov_b32_e32 v78, 0xff800000
	s_waitcnt lgkmcnt(0)
	s_mov_b32 s35, 0
	s_lshl_b32 s9, s35, 2
	s_add_i32 s9, s9, s46
	v_mov_b32_e32 v76, s9
	ds_read_b32 v76, v76 offset:16384
	s_add_i32 s50, s25, -1
	s_min_i32 s50, s50, 1
	s_waitcnt lgkmcnt(0)
	v_readfirstlane_b32 s9, v76
	s_and_b32 s38, s9, 0xffff
	s_lshr_b32 s48, s9, 16
	s_lshl_b32 s9, s50, 2
	s_add_i32 s9, s9, s46
	v_mov_b32_e32 v76, s9
	ds_read_b32 v76, v76 offset:16384
	s_lshl_b32 s29, s38, 12
	s_add_u32 s30, s40, s29
	s_addc_u32 s31, s41, 0
	global_load_dwordx4 v[2:5], v79, s[30:31]
	global_load_dwordx4 v[6:9], v79, s[30:31] offset:1024
	global_load_dwordx4 v[12:15], v79, s[30:31] offset:2048
	global_load_dwordx4 v[16:19], v79, s[30:31] offset:3072
	s_lshl_b32 s29, s38, 12
	s_add_u32 s30, s62, s29
	s_addc_u32 s31, s63, 0
	global_load_dwordx4 v[36:39], v79, s[30:31]
	global_load_dwordx4 v[40:43], v79, s[30:31] offset:1024
	global_load_dwordx4 v[44:47], v79, s[30:31] offset:2048
	global_load_dwordx4 v[48:51], v79, s[30:31] offset:3072
	s_waitcnt lgkmcnt(0)
	v_readfirstlane_b32 s9, v76
	s_and_b32 s27, s9, 0xffff
	s_lshr_b32 s8, s9, 16
	s_add_i32 s83, s25, -1
	s_min_i32 s83, s83, 2
	s_lshl_b32 s83, s83, 2
	s_add_i32 s83, s83, s46
	v_mov_b32_e32 v76, s83
	ds_read_b32 v76, v76 offset:16384
	s_lshl_b32 s83, s27, 12
	s_add_u32 s30, s40, s83
	s_addc_u32 s31, s41, 0
	global_load_dwordx4 v[20:23], v79, s[30:31]
	global_load_dwordx4 v[24:27], v79, s[30:31] offset:1024
	global_load_dwordx4 v[28:31], v79, s[30:31] offset:2048
	global_load_dwordx4 v[32:35], v79, s[30:31] offset:3072
	s_waitcnt lgkmcnt(0)
	v_readfirstlane_b32 s9, v76
	s_and_b32 s32, s9, 0xffff
	s_lshr_b32 s55, s9, 16
	v_readfirstlane_b32 s83, v1
	s_bitcmp1_b32 s83, 8
	s_cbranch_scc0 .Lbm3_nostag
	s_sleep 4
.Lbm3_nostag:
.Lbm3_blkA:
	s_lshl_b32 s29, s27, 12
	s_add_u32 s30, s62, s29
	s_addc_u32 s31, s63, 0
	global_load_dwordx4 v[52:55], v79, s[30:31]
	global_load_dwordx4 v[56:59], v79, s[30:31] offset:1024
	global_load_dwordx4 v[60:63], v79, s[30:31] offset:2048
	global_load_dwordx4 v[64:67], v79, s[30:31] offset:3072
	s_add_i32 s50, s35, 3
	s_add_i32 s9, s25, -1
	s_min_i32 s50, s50, s9
	s_lshl_b32 s9, s50, 2
	s_add_i32 s9, s9, s46
	v_mov_b32_e32 v76, s9
	ds_read_b32 v76, v76 offset:16384
	s_cmp_ge_i32 s38, s21
	s_cselect_b32 s50, 1, 0
	s_bfe_u32 s29, s48, 0x40000
	s_cmp_eq_u32 s29, 0
	s_cbranch_scc1 .Lbm3_Ag0_skip
	s_waitcnt vmcnt(12)
	v_mfma_f32_16x16x32_fp8_fp8 v[84:87], v[2:3], v[164:165], 0
	v_mfma_f32_16x16x32_fp8_fp8 v[84:87], v[4:5], v[166:167], v[84:87]
	v_mfma_f32_16x16x32_fp8_fp8 v[88:91], v[6:7], v[164:165], 0
	v_mfma_f32_16x16x32_fp8_fp8 v[88:91], v[8:9], v[166:167], v[88:91]
	s_lshl_b32 s98, s29, 3
	s_lshl_b32 s12, s29, 6
	s_or_b32 s98, s98, s29
	s_or_b32 s98, s98, s12
	s_lshl_b32 s12, s29, 9
	s_or_b32 s98, s98, s12
	s_and_b32 s98, s98, 0x1111
	s_mul_i32 s98, s98, 15
	s_lshl_b32 s12, s98, 16
	s_or_b32 s12, s12, s98
	s_mov_b32 s13, s12
	s_cmp_eq_u32 s50, 1
	s_cbranch_scc1 .Lbm3_Ag0_near0
	v_cndmask_b32_e64 v200, v77, v252, s[12:13]
	s_cmp_eq_u32 s35, 0
	s_cbranch_scc1 .Lbm3_Ag0_first0
	v_mfma_f32_16x16x32_fp8_fp8 v[92:95], v[12:13], v[164:165], 0
	v_mfma_f32_16x16x32_fp8_fp8 v[92:95], v[14:15], v[166:167], v[92:95]
	v_pk_fma_f32 v[84:85], v[84:85], s[10:11], v[200:201] op_sel_hi:[1,1,0]
	v_pk_fma_f32 v[86:87], v[86:87], s[10:11], v[200:201] op_sel_hi:[1,1,0]
	v_mfma_f32_16x16x32_fp8_fp8 v[96:99], v[16:17], v[164:165], 0
	v_mfma_f32_16x16x32_fp8_fp8 v[96:99], v[18:19], v[166:167], v[96:99]
	v_exp_f32_e32 v84, v84
	v_exp_f32_e32 v85, v85
	v_exp_f32_e32 v86, v86
	v_exp_f32_e32 v87, v87
	v_pk_fma_f32 v[88:89], v[88:89], s[10:11], v[200:201] op_sel_hi:[1,1,0]
	v_pk_fma_f32 v[90:91], v[90:91], s[10:11], v[200:201] op_sel_hi:[1,1,0]
	v_exp_f32_e32 v88, v88
	v_exp_f32_e32 v89, v89
	v_exp_f32_e32 v90, v90
	v_exp_f32_e32 v91, v91
	v_pk_fma_f32 v[92:93], v[92:93], s[10:11], v[200:201] op_sel_hi:[1,1,0]
	v_pk_fma_f32 v[94:95], v[94:95], s[10:11], v[200:201] op_sel_hi:[1,1,0]
	v_pk_fma_f32 v[96:97], v[96:97], s[10:11], v[200:201] op_sel_hi:[1,1,0]
	v_pk_fma_f32 v[98:99], v[98:99], s[10:11], v[200:201] op_sel_hi:[1,1,0]
	v_exp_f32_e32 v92, v92
	v_exp_f32_e32 v93, v93
	v_exp_f32_e32 v94, v94
	v_exp_f32_e32 v95, v95
	s_nop 0
	v_exp_f32_e32 v96, v96
	v_exp_f32_e32 v97, v97
	v_exp_f32_e32 v98, v98
	v_exp_f32_e32 v99, v99
	v_pk_add_f32 v[248:249], v[84:85], v[86:87]
	v_pk_add_f32 v[82:83], v[88:89], v[90:91]
	v_pk_add_f32 v[172:173], v[92:93], v[94:95]
	v_pk_add_f32 v[202:203], v[96:97], v[98:99]
	v_cvt_pk_fp8_f32 v84, v84, v85
	v_cvt_pk_fp8_f32 v85, v88, v89
	v_pk_add_f32 v[248:249], v[248:249], v[82:83]
	v_pk_add_f32 v[172:173], v[172:173], v[202:203]
	v_cvt_pk_fp8_f32 v84, v86, v87 op_sel:[0,0,1]
	v_cvt_pk_fp8_f32 v85, v90, v91 op_sel:[0,0,1]
	v_pk_add_f32 v[248:249], v[248:249], v[172:173]
	v_cvt_pk_fp8_f32 v86, v92, v93
	v_cvt_pk_fp8_f32 v87, v96, v97
	v_add_f32_e32 v248, v248, v249
	v_cvt_pk_fp8_f32 v86, v94, v95 op_sel:[0,0,1]
	v_cvt_pk_fp8_f32 v87, v98, v99 op_sel:[0,0,1]
	v_cmp_lt_f32_e32 vcc, 0x43800000, v248
	s_cbranch_vccnz .Lbm3_Ag0_redo
	s_lshr_b32 s83, s48, 4
	s_cmp_lg_u32 s83, 0
	s_cbranch_scc1 .Lbm3_Ag0_ks0
	s_lshl_b32 s83, s32, 12
	s_add_u32 s30, s40, s83
	s_addc_u32 s31, s41, 0
	global_load_dwordx4 v[2:5], v79, s[30:31]
	global_load_dwordx4 v[6:9], v79, s[30:31] offset:1024
	global_load_dwordx4 v[12:15], v79, s[30:31] offset:2048
	global_load_dwordx4 v[16:19], v79, s[30:31] offset:3072

.Lbm3_Ag0_near:
	s_lshl_b32 s9, s38, 6
	s_sub_i32 s9, s47, s9
	v_and_b32_e32 v245, 15, v181
	v_lshrrev_b32_e32 v246, 4, v181
	v_lshrrev_b32_e32 v245, 2, v245
	v_lshlrev_b32_e32 v246, 2, v246
	v_cndmask_b32_e64 v200, v77, v190, s[12:13]
	v_sub_u32_e32 v245, v245, v246
	v_add_u32_e32 v198, s9, v245
	v_min_u32_e32 v82, 0x7f, v198
	v_lshl_add_u32 v82, v82, 2, v80
	ds_read_b32 v82, v82
	v_subrev_u32_e32 v245, 1, v198
	v_min_u32_e32 v83, 0x7f, v245
	v_lshl_add_u32 v83, v83, 2, v80
	ds_read_b32 v83, v83
	v_subrev_u32_e32 v245, 2, v198
	v_min_u32_e32 v172, 0x7f, v245
	v_lshl_add_u32 v172, v172, 2, v80
	ds_read_b32 v172, v172
	v_subrev_u32_e32 v245, 3, v198
	v_min_u32_e32 v173, 0x7f, v245
	v_lshl_add_u32 v173, v173, 2, v80
	ds_read_b32 v173, v173
	v_subrev_u32_e32 v245, 16, v198
	v_min_u32_e32 v202, 0x7f, v245
	v_lshl_add_u32 v202, v202, 2, v80
	ds_read_b32 v202, v202
	v_subrev_u32_e32 v245, 17, v198
	v_min_u32_e32 v203, 0x7f, v245
	v_lshl_add_u32 v203, v203, 2, v80
	ds_read_b32 v203, v203
	v_subrev_u32_e32 v245, 18, v198
	v_min_u32_e32 v228, 0x7f, v245
	v_lshl_add_u32 v228, v228, 2, v80
	ds_read_b32 v228, v228
	v_subrev_u32_e32 v245, 19, v198
	v_min_u32_e32 v229, 0x7f, v245
	v_lshl_add_u32 v229, v229, 2, v80
	ds_read_b32 v229, v229
	s_waitcnt lgkmcnt(0)
	v_fmamk_f32 v82, v82, 0x3fb8aa3b, v200
	v_cmp_le_i32_e32 vcc, 0, v198
	v_fmamk_f32 v84, v84, 0x3e38aa3b, v82
	s_nop 0
	v_cndmask_b32_e32 v84, v77, v84, vcc
	v_fmamk_f32 v83, v83, 0x3fb8aa3b, v200
	v_cmp_le_i32_e32 vcc, 1, v198
	v_fmamk_f32 v85, v85, 0x3e38aa3b, v83
	s_nop 0
	v_cndmask_b32_e32 v85, v77, v85, vcc
	v_fmamk_f32 v172, v172, 0x3fb8aa3b, v200
	v_cmp_le_i32_e32 vcc, 2, v198
	v_fmamk_f32 v86, v86, 0x3e38aa3b, v172
	s_nop 0
	v_cndmask_b32_e32 v86, v77, v86, vcc
	v_fmamk_f32 v173, v173, 0x3fb8aa3b, v200
	v_cmp_le_i32_e32 vcc, 3, v198
	v_fmamk_f32 v87, v87, 0x3e38aa3b, v173
	s_nop 0
	v_cndmask_b32_e32 v87, v77, v87, vcc
	v_fmamk_f32 v202, v202, 0x3fb8aa3b, v200
	v_cmp_le_i32_e32 vcc, 16, v198
	v_fmamk_f32 v88, v88, 0x3e38aa3b, v202
	s_nop 0
	v_cndmask_b32_e32 v88, v77, v88, vcc
	v_fmamk_f32 v203, v203, 0x3fb8aa3b, v200
	v_cmp_le_i32_e32 vcc, 17, v198
	v_fmamk_f32 v89, v89, 0x3e38aa3b, v203
	s_nop 0
	v_cndmask_b32_e32 v89, v77, v89, vcc
	v_fmamk_f32 v228, v228, 0x3fb8aa3b, v200
	v_cmp_le_i32_e32 vcc, 18, v198
	v_fmamk_f32 v90, v90, 0x3e38aa3b, v228
	s_nop 0
	v_cndmask_b32_e32 v90, v77, v90, vcc
	v_fmamk_f32 v229, v229, 0x3fb8aa3b, v200
	v_cmp_le_i32_e32 vcc, 19, v198
	v_fmamk_f32 v91, v91, 0x3e38aa3b, v229
	s_nop 0
	v_cndmask_b32_e32 v91, v77, v91, vcc
	v_subrev_u32_e32 v245, 32, v198
	v_min_u32_e32 v82, 0x7f, v245
	v_lshl_add_u32 v82, v82, 2, v80
	ds_read_b32 v82, v82
	v_subrev_u32_e32 v245, 33, v198
	v_min_u32_e32 v83, 0x7f, v245
	v_lshl_add_u32 v83, v83, 2, v80
	ds_read_b32 v83, v83
	v_subrev_u32_e32 v245, 34, v198
	v_min_u32_e32 v172, 0x7f, v245
	v_lshl_add_u32 v172, v172, 2, v80
	ds_read_b32 v172, v172
	v_subrev_u32_e32 v245, 35, v198
	v_min_u32_e32 v173, 0x7f, v245
	v_lshl_add_u32 v173, v173, 2, v80
	ds_read_b32 v173, v173
	v_subrev_u32_e32 v245, 48, v198
	v_min_u32_e32 v202, 0x7f, v245
	v_lshl_add_u32 v202, v202, 2, v80
	ds_read_b32 v202, v202
	v_subrev_u32_e32 v245, 49, v198
	v_min_u32_e32 v203, 0x7f, v245
	v_lshl_add_u32 v203, v203, 2, v80
	ds_read_b32 v203, v203
	v_subrev_u32_e32 v245, 50, v198
	v_min_u32_e32 v228, 0x7f, v245
	v_lshl_add_u32 v228, v228, 2, v80
	ds_read_b32 v228, v228
	v_subrev_u32_e32 v245, 51, v198
	v_min_u32_e32 v229, 0x7f, v245
	v_lshl_add_u32 v229, v229, 2, v80
	ds_read_b32 v229, v229
	s_waitcnt lgkmcnt(0)
	v_fmamk_f32 v82, v82, 0x3fb8aa3b, v200
	v_cmp_le_i32_e32 vcc, 32, v198
	v_fmamk_f32 v92, v92, 0x3e38aa3b, v82
	s_nop 0
	v_cndmask_b32_e32 v92, v77, v92, vcc
	v_fmamk_f32 v83, v83, 0x3fb8aa3b, v200
	v_cmp_le_i32_e32 vcc, 33, v198
	v_fmamk_f32 v93, v93, 0x3e38aa3b, v83
	s_nop 0
	v_cndmask_b32_e32 v93, v77, v93, vcc
	v_fmamk_f32 v172, v172, 0x3fb8aa3b, v200
	v_cmp_le_i32_e32 vcc, 34, v198
	v_fmamk_f32 v94, v94, 0x3e38aa3b, v172
	s_nop 0
	v_cndmask_b32_e32 v94, v77, v94, vcc
	v_fmamk_f32 v173, v173, 0x3fb8aa3b, v200
	v_cmp_le_i32_e32 vcc, 35, v198
	v_fmamk_f32 v95, v95, 0x3e38aa3b, v173
	s_nop 0
	v_cndmask_b32_e32 v95, v77, v95, vcc
	v_fmamk_f32 v202, v202, 0x3fb8aa3b, v200
	v_cmp_le_i32_e32 vcc, 48, v198
	v_fmamk_f32 v96, v96, 0x3e38aa3b, v202
	s_nop 0
	v_cndmask_b32_e32 v96, v77, v96, vcc
	v_fmamk_f32 v203, v203, 0x3fb8aa3b, v200
	v_cmp_le_i32_e32 vcc, 49, v198
	v_fmamk_f32 v97, v97, 0x3e38aa3b, v203
	s_nop 0
	v_cndmask_b32_e32 v97, v77, v97, vcc
	v_fmamk_f32 v228, v228, 0x3fb8aa3b, v200
	v_cmp_le_i32_e32 vcc, 50, v198
	v_fmamk_f32 v98, v98, 0x3e38aa3b, v228
	s_nop 0
	v_cndmask_b32_e32 v98, v77, v98, vcc
	v_fmamk_f32 v229, v229, 0x3fb8aa3b, v200
	v_cmp_le_i32_e32 vcc, 51, v198
	v_fmamk_f32 v99, v99, 0x3e38aa3b, v229
	s_nop 0
	v_cndmask_b32_e32 v99, v77, v99, vcc
	s_branch .Lbm3_Ag0_max
.Lbm3_Ag0_skip:
	s_bfe_u32 s29, s48, 0x40004
	s_cmp_eq_u32 s29, 0
	s_cbranch_scc1 .Lbm3_Ag1_skip
	s_waitcnt vmcnt(12)
	v_mfma_f32_16x16x32_fp8_fp8 v[84:87], v[2:3], v[168:169], 0
	v_mfma_f32_16x16x32_fp8_fp8 v[84:87], v[4:5], v[170:171], v[84:87]
	v_mfma_f32_16x16x32_fp8_fp8 v[88:91], v[6:7], v[168:169], 0
	v_mfma_f32_16x16x32_fp8_fp8 v[88:91], v[8:9], v[170:171], v[88:91]
	s_lshl_b32 s98, s29, 3
	s_lshl_b32 s12, s29, 6
	s_or_b32 s98, s98, s29
	s_or_b32 s98, s98, s12
	s_lshl_b32 s12, s29, 9
	s_or_b32 s98, s98, s12
	s_and_b32 s98, s98, 0x1111
	s_mul_i32 s98, s98, 15
	s_lshl_b32 s12, s98, 16
	s_or_b32 s12, s12, s98
	s_mov_b32 s13, s12
	s_cmp_eq_u32 s50, 1
	s_cbranch_scc1 .Lbm3_Ag1_near0
	v_cndmask_b32_e64 v200, v77, v253, s[12:13]
	s_cmp_eq_u32 s35, 0
	s_cbranch_scc1 .Lbm3_Ag1_first0
	v_mfma_f32_16x16x32_fp8_fp8 v[92:95], v[12:13], v[168:169], 0
	v_mfma_f32_16x16x32_fp8_fp8 v[92:95], v[14:15], v[170:171], v[92:95]
	v_pk_fma_f32 v[84:85], v[84:85], s[10:11], v[200:201] op_sel_hi:[1,1,0]
	v_pk_fma_f32 v[86:87], v[86:87], s[10:11], v[200:201] op_sel_hi:[1,1,0]
	v_mfma_f32_16x16x32_fp8_fp8 v[96:99], v[16:17], v[168:169], 0
	v_mfma_f32_16x16x32_fp8_fp8 v[96:99], v[18:19], v[170:171], v[96:99]
	v_exp_f32_e32 v84, v84
	v_exp_f32_e32 v85, v85
	v_exp_f32_e32 v86, v86
	v_exp_f32_e32 v87, v87
	v_pk_fma_f32 v[88:89], v[88:89], s[10:11], v[200:201] op_sel_hi:[1,1,0]
	v_pk_fma_f32 v[90:91], v[90:91], s[10:11], v[200:201] op_sel_hi:[1,1,0]
	v_exp_f32_e32 v88, v88
	v_exp_f32_e32 v89, v89
	v_exp_f32_e32 v90, v90
	v_exp_f32_e32 v91, v91
	v_pk_fma_f32 v[92:93], v[92:93], s[10:11], v[200:201] op_sel_hi:[1,1,0]
	v_pk_fma_f32 v[94:95], v[94:95], s[10:11], v[200:201] op_sel_hi:[1,1,0]
	v_pk_fma_f32 v[96:97], v[96:97], s[10:11], v[200:201] op_sel_hi:[1,1,0]
	v_pk_fma_f32 v[98:99], v[98:99], s[10:11], v[200:201] op_sel_hi:[1,1,0]
	v_exp_f32_e32 v92, v92
	v_exp_f32_e32 v93, v93
	v_exp_f32_e32 v94, v94
	v_exp_f32_e32 v95, v95
	s_nop 0
	v_exp_f32_e32 v96, v96
	v_exp_f32_e32 v97, v97
	v_exp_f32_e32 v98, v98
	v_exp_f32_e32 v99, v99
	v_pk_add_f32 v[248:249], v[84:85], v[86:87]
	v_pk_add_f32 v[82:83], v[88:89], v[90:91]
	v_pk_add_f32 v[172:173], v[92:93], v[94:95]
	v_pk_add_f32 v[202:203], v[96:97], v[98:99]
	v_cvt_pk_fp8_f32 v84, v84, v85
	v_cvt_pk_fp8_f32 v85, v88, v89
	v_pk_add_f32 v[248:249], v[248:249], v[82:83]
	v_pk_add_f32 v[172:173], v[172:173], v[202:203]
	v_cvt_pk_fp8_f32 v84, v86, v87 op_sel:[0,0,1]
	v_cvt_pk_fp8_f32 v85, v90, v91 op_sel:[0,0,1]
	v_pk_add_f32 v[248:249], v[248:249], v[172:173]
	v_cvt_pk_fp8_f32 v86, v92, v93
	v_cvt_pk_fp8_f32 v87, v96, v97
	v_add_f32_e32 v248, v248, v249
	v_cvt_pk_fp8_f32 v86, v94, v95 op_sel:[0,0,1]
	v_cvt_pk_fp8_f32 v87, v98, v99 op_sel:[0,0,1]
	v_cmp_lt_f32_e32 vcc, 0x43800000, v248
	s_cbranch_vccnz .Lbm3_Ag1_redo
	s_lshr_b32 s83, s48, 8
	s_cmp_lg_u32 s83, 0
	s_cbranch_scc1 .Lbm3_Ag1_ks0
	s_lshl_b32 s83, s32, 12
	s_add_u32 s30, s40, s83
	s_addc_u32 s31, s41, 0
	global_load_dwordx4 v[2:5], v79, s[30:31]
	global_load_dwordx4 v[6:9], v79, s[30:31] offset:1024
	global_load_dwordx4 v[12:15], v79, s[30:31] offset:2048
	global_load_dwordx4 v[16:19], v79, s[30:31] offset:3072

.Lbm3_Ag1_near:
	s_lshl_b32 s9, s38, 6
	s_sub_i32 s9, s47, s9
	s_add_i32 s9, s9, 4
	v_and_b32_e32 v245, 15, v181
	v_lshrrev_b32_e32 v246, 4, v181
	v_lshrrev_b32_e32 v245, 2, v245
	v_lshlrev_b32_e32 v246, 2, v246
	v_cndmask_b32_e64 v200, v77, v191, s[12:13]
	v_sub_u32_e32 v245, v245, v246
	v_add_u32_e32 v198, s9, v245
	v_min_u32_e32 v82, 0x7f, v198
	v_lshl_add_u32 v82, v82, 2, v80
	ds_read_b32 v82, v82
	v_subrev_u32_e32 v245, 1, v198
	v_min_u32_e32 v83, 0x7f, v245
	v_lshl_add_u32 v83, v83, 2, v80
	ds_read_b32 v83, v83
	v_subrev_u32_e32 v245, 2, v198
	v_min_u32_e32 v172, 0x7f, v245
	v_lshl_add_u32 v172, v172, 2, v80
	ds_read_b32 v172, v172
	v_subrev_u32_e32 v245, 3, v198
	v_min_u32_e32 v173, 0x7f, v245
	v_lshl_add_u32 v173, v173, 2, v80
	ds_read_b32 v173, v173
	v_subrev_u32_e32 v245, 16, v198
	v_min_u32_e32 v202, 0x7f, v245
	v_lshl_add_u32 v202, v202, 2, v80
	ds_read_b32 v202, v202
	v_subrev_u32_e32 v245, 17, v198
	v_min_u32_e32 v203, 0x7f, v245
	v_lshl_add_u32 v203, v203, 2, v80
	ds_read_b32 v203, v203
	v_subrev_u32_e32 v245, 18, v198
	v_min_u32_e32 v228, 0x7f, v245
	v_lshl_add_u32 v228, v228, 2, v80
	ds_read_b32 v228, v228
	v_subrev_u32_e32 v245, 19, v198
	v_min_u32_e32 v229, 0x7f, v245
	v_lshl_add_u32 v229, v229, 2, v80
	ds_read_b32 v229, v229
	s_waitcnt lgkmcnt(0)
	v_fmamk_f32 v82, v82, 0x3fb8aa3b, v200
	v_cmp_le_i32_e32 vcc, 0, v198
	v_fmamk_f32 v84, v84, 0x3e38aa3b, v82
	s_nop 0
	v_cndmask_b32_e32 v84, v77, v84, vcc
	v_fmamk_f32 v83, v83, 0x3fb8aa3b, v200
	v_cmp_le_i32_e32 vcc, 1, v198
	v_fmamk_f32 v85, v85, 0x3e38aa3b, v83
	s_nop 0
	v_cndmask_b32_e32 v85, v77, v85, vcc
	v_fmamk_f32 v172, v172, 0x3fb8aa3b, v200
	v_cmp_le_i32_e32 vcc, 2, v198
	v_fmamk_f32 v86, v86, 0x3e38aa3b, v172
	s_nop 0
	v_cndmask_b32_e32 v86, v77, v86, vcc
	v_fmamk_f32 v173, v173, 0x3fb8aa3b, v200
	v_cmp_le_i32_e32 vcc, 3, v198
	v_fmamk_f32 v87, v87, 0x3e38aa3b, v173
	s_nop 0
	v_cndmask_b32_e32 v87, v77, v87, vcc
	v_fmamk_f32 v202, v202, 0x3fb8aa3b, v200
	v_cmp_le_i32_e32 vcc, 16, v198
	v_fmamk_f32 v88, v88, 0x3e38aa3b, v202
	s_nop 0
	v_cndmask_b32_e32 v88, v77, v88, vcc
	v_fmamk_f32 v203, v203, 0x3fb8aa3b, v200
	v_cmp_le_i32_e32 vcc, 17, v198
	v_fmamk_f32 v89, v89, 0x3e38aa3b, v203
	s_nop 0
	v_cndmask_b32_e32 v89, v77, v89, vcc
	v_fmamk_f32 v228, v228, 0x3fb8aa3b, v200
	v_cmp_le_i32_e32 vcc, 18, v198
	v_fmamk_f32 v90, v90, 0x3e38aa3b, v228
	s_nop 0
	v_cndmask_b32_e32 v90, v77, v90, vcc
	v_fmamk_f32 v229, v229, 0x3fb8aa3b, v200
	v_cmp_le_i32_e32 vcc, 19, v198
	v_fmamk_f32 v91, v91, 0x3e38aa3b, v229
	s_nop 0
	v_cndmask_b32_e32 v91, v77, v91, vcc
	v_subrev_u32_e32 v245, 32, v198
	v_min_u32_e32 v82, 0x7f, v245
	v_lshl_add_u32 v82, v82, 2, v80
	ds_read_b32 v82, v82
	v_subrev_u32_e32 v245, 33, v198
	v_min_u32_e32 v83, 0x7f, v245
	v_lshl_add_u32 v83, v83, 2, v80
	ds_read_b32 v83, v83
	v_subrev_u32_e32 v245, 34, v198
	v_min_u32_e32 v172, 0x7f, v245
	v_lshl_add_u32 v172, v172, 2, v80
	ds_read_b32 v172, v172
	v_subrev_u32_e32 v245, 35, v198
	v_min_u32_e32 v173, 0x7f, v245
	v_lshl_add_u32 v173, v173, 2, v80
	ds_read_b32 v173, v173
	v_subrev_u32_e32 v245, 48, v198
	v_min_u32_e32 v202, 0x7f, v245
	v_lshl_add_u32 v202, v202, 2, v80
	ds_read_b32 v202, v202
	v_subrev_u32_e32 v245, 49, v198
	v_min_u32_e32 v203, 0x7f, v245
	v_lshl_add_u32 v203, v203, 2, v80
	ds_read_b32 v203, v203
	v_subrev_u32_e32 v245, 50, v198
	v_min_u32_e32 v228, 0x7f, v245
	v_lshl_add_u32 v228, v228, 2, v80
	ds_read_b32 v228, v228
	v_subrev_u32_e32 v245, 51, v198
	v_min_u32_e32 v229, 0x7f, v245
	v_lshl_add_u32 v229, v229, 2, v80
	ds_read_b32 v229, v229
	s_waitcnt lgkmcnt(0)
	v_fmamk_f32 v82, v82, 0x3fb8aa3b, v200
	v_cmp_le_i32_e32 vcc, 32, v198
	v_fmamk_f32 v92, v92, 0x3e38aa3b, v82
	s_nop 0
	v_cndmask_b32_e32 v92, v77, v92, vcc
	v_fmamk_f32 v83, v83, 0x3fb8aa3b, v200
	v_cmp_le_i32_e32 vcc, 33, v198
	v_fmamk_f32 v93, v93, 0x3e38aa3b, v83
	s_nop 0
	v_cndmask_b32_e32 v93, v77, v93, vcc
	v_fmamk_f32 v172, v172, 0x3fb8aa3b, v200
	v_cmp_le_i32_e32 vcc, 34, v198
	v_fmamk_f32 v94, v94, 0x3e38aa3b, v172
	s_nop 0
	v_cndmask_b32_e32 v94, v77, v94, vcc
	v_fmamk_f32 v173, v173, 0x3fb8aa3b, v200
	v_cmp_le_i32_e32 vcc, 35, v198
	v_fmamk_f32 v95, v95, 0x3e38aa3b, v173
	s_nop 0
	v_cndmask_b32_e32 v95, v77, v95, vcc
	v_fmamk_f32 v202, v202, 0x3fb8aa3b, v200
	v_cmp_le_i32_e32 vcc, 48, v198
	v_fmamk_f32 v96, v96, 0x3e38aa3b, v202
	s_nop 0
	v_cndmask_b32_e32 v96, v77, v96, vcc
	v_fmamk_f32 v203, v203, 0x3fb8aa3b, v200
	v_cmp_le_i32_e32 vcc, 49, v198
	v_fmamk_f32 v97, v97, 0x3e38aa3b, v203
	s_nop 0
	v_cndmask_b32_e32 v97, v77, v97, vcc
	v_fmamk_f32 v228, v228, 0x3fb8aa3b, v200
	v_cmp_le_i32_e32 vcc, 50, v198
	v_fmamk_f32 v98, v98, 0x3e38aa3b, v228
	s_nop 0
	v_cndmask_b32_e32 v98, v77, v98, vcc
	v_fmamk_f32 v229, v229, 0x3fb8aa3b, v200
	v_cmp_le_i32_e32 vcc, 51, v198
	v_fmamk_f32 v99, v99, 0x3e38aa3b, v229
	s_nop 0
	v_cndmask_b32_e32 v99, v77, v99, vcc
	s_branch .Lbm3_Ag1_max
.Lbm3_Ag1_skip:
	s_bfe_u32 s29, s48, 0x40008
	s_cmp_eq_u32 s29, 0
	s_cbranch_scc1 .Lbm3_Ag2_skip
	s_waitcnt vmcnt(12)
	v_mfma_f32_16x16x32_fp8_fp8 v[84:87], v[2:3], v[182:183], 0
	v_mfma_f32_16x16x32_fp8_fp8 v[84:87], v[4:5], v[184:185], v[84:87]
	v_mfma_f32_16x16x32_fp8_fp8 v[88:91], v[6:7], v[182:183], 0
	v_mfma_f32_16x16x32_fp8_fp8 v[88:91], v[8:9], v[184:185], v[88:91]
	s_lshl_b32 s98, s29, 3
	s_lshl_b32 s12, s29, 6
	s_or_b32 s98, s98, s29
	s_or_b32 s98, s98, s12
	s_lshl_b32 s12, s29, 9
	s_or_b32 s98, s98, s12
	s_and_b32 s98, s98, 0x1111
	s_mul_i32 s98, s98, 15
	s_lshl_b32 s12, s98, 16
	s_or_b32 s12, s12, s98
	s_mov_b32 s13, s12
	s_cmp_eq_u32 s50, 1
	s_cbranch_scc1 .Lbm3_Ag2_near0
	v_cndmask_b32_e64 v200, v77, v254, s[12:13]
	s_cmp_eq_u32 s35, 0
	s_cbranch_scc1 .Lbm3_Ag2_first0
	v_mfma_f32_16x16x32_fp8_fp8 v[92:95], v[12:13], v[182:183], 0
	v_mfma_f32_16x16x32_fp8_fp8 v[92:95], v[14:15], v[184:185], v[92:95]
	v_pk_fma_f32 v[84:85], v[84:85], s[10:11], v[200:201] op_sel_hi:[1,1,0]
	v_pk_fma_f32 v[86:87], v[86:87], s[10:11], v[200:201] op_sel_hi:[1,1,0]
	v_mfma_f32_16x16x32_fp8_fp8 v[96:99], v[16:17], v[182:183], 0
	v_mfma_f32_16x16x32_fp8_fp8 v[96:99], v[18:19], v[184:185], v[96:99]
	v_exp_f32_e32 v84, v84
	v_exp_f32_e32 v85, v85
	v_exp_f32_e32 v86, v86
	v_exp_f32_e32 v87, v87
	v_pk_fma_f32 v[88:89], v[88:89], s[10:11], v[200:201] op_sel_hi:[1,1,0]
	v_pk_fma_f32 v[90:91], v[90:91], s[10:11], v[200:201] op_sel_hi:[1,1,0]
	v_exp_f32_e32 v88, v88
	v_exp_f32_e32 v89, v89
	v_exp_f32_e32 v90, v90
	v_exp_f32_e32 v91, v91
	v_pk_fma_f32 v[92:93], v[92:93], s[10:11], v[200:201] op_sel_hi:[1,1,0]
	v_pk_fma_f32 v[94:95], v[94:95], s[10:11], v[200:201] op_sel_hi:[1,1,0]
	v_pk_fma_f32 v[96:97], v[96:97], s[10:11], v[200:201] op_sel_hi:[1,1,0]
	v_pk_fma_f32 v[98:99], v[98:99], s[10:11], v[200:201] op_sel_hi:[1,1,0]
	v_exp_f32_e32 v92, v92
	v_exp_f32_e32 v93, v93
	v_exp_f32_e32 v94, v94
	v_exp_f32_e32 v95, v95
	s_nop 0
	v_exp_f32_e32 v96, v96
	v_exp_f32_e32 v97, v97
	v_exp_f32_e32 v98, v98
	v_exp_f32_e32 v99, v99
	v_pk_add_f32 v[248:249], v[84:85], v[86:87]
	v_pk_add_f32 v[82:83], v[88:89], v[90:91]
	v_pk_add_f32 v[172:173], v[92:93], v[94:95]
	v_pk_add_f32 v[202:203], v[96:97], v[98:99]
	v_cvt_pk_fp8_f32 v84, v84, v85
	v_cvt_pk_fp8_f32 v85, v88, v89
	v_pk_add_f32 v[248:249], v[248:249], v[82:83]
	v_pk_add_f32 v[172:173], v[172:173], v[202:203]
	v_cvt_pk_fp8_f32 v84, v86, v87 op_sel:[0,0,1]
	v_cvt_pk_fp8_f32 v85, v90, v91 op_sel:[0,0,1]
	v_pk_add_f32 v[248:249], v[248:249], v[172:173]
	v_cvt_pk_fp8_f32 v86, v92, v93
	v_cvt_pk_fp8_f32 v87, v96, v97
	v_add_f32_e32 v248, v248, v249
	v_cvt_pk_fp8_f32 v86, v94, v95 op_sel:[0,0,1]
	v_cvt_pk_fp8_f32 v87, v98, v99 op_sel:[0,0,1]
	v_cmp_lt_f32_e32 vcc, 0x43800000, v248
	s_cbranch_vccnz .Lbm3_Ag2_redo
	s_lshr_b32 s83, s48, 12
	s_cmp_lg_u32 s83, 0
	s_cbranch_scc1 .Lbm3_Ag2_ks0
	s_lshl_b32 s83, s32, 12
	s_add_u32 s30, s40, s83
	s_addc_u32 s31, s41, 0
	global_load_dwordx4 v[2:5], v79, s[30:31]
	global_load_dwordx4 v[6:9], v79, s[30:31] offset:1024
	global_load_dwordx4 v[12:15], v79, s[30:31] offset:2048
	global_load_dwordx4 v[16:19], v79, s[30:31] offset:3072

.Lbm3_Ag2_near:
	s_lshl_b32 s9, s38, 6
	s_sub_i32 s9, s47, s9
	s_add_i32 s9, s9, 8
	v_and_b32_e32 v245, 15, v181
	v_lshrrev_b32_e32 v246, 4, v181
	v_lshrrev_b32_e32 v245, 2, v245
	v_lshlrev_b32_e32 v246, 2, v246
	v_cndmask_b32_e64 v200, v77, v192, s[12:13]
	v_sub_u32_e32 v245, v245, v246
	v_add_u32_e32 v198, s9, v245
	v_min_u32_e32 v82, 0x7f, v198
	v_lshl_add_u32 v82, v82, 2, v80
	ds_read_b32 v82, v82
	v_subrev_u32_e32 v245, 1, v198
	v_min_u32_e32 v83, 0x7f, v245
	v_lshl_add_u32 v83, v83, 2, v80
	ds_read_b32 v83, v83
	v_subrev_u32_e32 v245, 2, v198
	v_min_u32_e32 v172, 0x7f, v245
	v_lshl_add_u32 v172, v172, 2, v80
	ds_read_b32 v172, v172
	v_subrev_u32_e32 v245, 3, v198
	v_min_u32_e32 v173, 0x7f, v245
	v_lshl_add_u32 v173, v173, 2, v80
	ds_read_b32 v173, v173
	v_subrev_u32_e32 v245, 16, v198
	v_min_u32_e32 v202, 0x7f, v245
	v_lshl_add_u32 v202, v202, 2, v80
	ds_read_b32 v202, v202
	v_subrev_u32_e32 v245, 17, v198
	v_min_u32_e32 v203, 0x7f, v245
	v_lshl_add_u32 v203, v203, 2, v80
	ds_read_b32 v203, v203
	v_subrev_u32_e32 v245, 18, v198
	v_min_u32_e32 v228, 0x7f, v245
	v_lshl_add_u32 v228, v228, 2, v80
	ds_read_b32 v228, v228
	v_subrev_u32_e32 v245, 19, v198
	v_min_u32_e32 v229, 0x7f, v245
	v_lshl_add_u32 v229, v229, 2, v80
	ds_read_b32 v229, v229
	s_waitcnt lgkmcnt(0)
	v_fmamk_f32 v82, v82, 0x3fb8aa3b, v200
	v_cmp_le_i32_e32 vcc, 0, v198
	v_fmamk_f32 v84, v84, 0x3e38aa3b, v82
	s_nop 0
	v_cndmask_b32_e32 v84, v77, v84, vcc
	v_fmamk_f32 v83, v83, 0x3fb8aa3b, v200
	v_cmp_le_i32_e32 vcc, 1, v198
	v_fmamk_f32 v85, v85, 0x3e38aa3b, v83
	s_nop 0
	v_cndmask_b32_e32 v85, v77, v85, vcc
	v_fmamk_f32 v172, v172, 0x3fb8aa3b, v200
	v_cmp_le_i32_e32 vcc, 2, v198
	v_fmamk_f32 v86, v86, 0x3e38aa3b, v172
	s_nop 0
	v_cndmask_b32_e32 v86, v77, v86, vcc
	v_fmamk_f32 v173, v173, 0x3fb8aa3b, v200
	v_cmp_le_i32_e32 vcc, 3, v198
	v_fmamk_f32 v87, v87, 0x3e38aa3b, v173
	s_nop 0
	v_cndmask_b32_e32 v87, v77, v87, vcc
	v_fmamk_f32 v202, v202, 0x3fb8aa3b, v200
	v_cmp_le_i32_e32 vcc, 16, v198
	v_fmamk_f32 v88, v88, 0x3e38aa3b, v202
	s_nop 0
	v_cndmask_b32_e32 v88, v77, v88, vcc
	v_fmamk_f32 v203, v203, 0x3fb8aa3b, v200
	v_cmp_le_i32_e32 vcc, 17, v198
	v_fmamk_f32 v89, v89, 0x3e38aa3b, v203
	s_nop 0
	v_cndmask_b32_e32 v89, v77, v89, vcc
	v_fmamk_f32 v228, v228, 0x3fb8aa3b, v200
	v_cmp_le_i32_e32 vcc, 18, v198
	v_fmamk_f32 v90, v90, 0x3e38aa3b, v228
	s_nop 0
	v_cndmask_b32_e32 v90, v77, v90, vcc
	v_fmamk_f32 v229, v229, 0x3fb8aa3b, v200
	v_cmp_le_i32_e32 vcc, 19, v198
	v_fmamk_f32 v91, v91, 0x3e38aa3b, v229
	s_nop 0
	v_cndmask_b32_e32 v91, v77, v91, vcc
	v_subrev_u32_e32 v245, 32, v198
	v_min_u32_e32 v82, 0x7f, v245
	v_lshl_add_u32 v82, v82, 2, v80
	ds_read_b32 v82, v82
	v_subrev_u32_e32 v245, 33, v198
	v_min_u32_e32 v83, 0x7f, v245
	v_lshl_add_u32 v83, v83, 2, v80
	ds_read_b32 v83, v83
	v_subrev_u32_e32 v245, 34, v198
	v_min_u32_e32 v172, 0x7f, v245
	v_lshl_add_u32 v172, v172, 2, v80
	ds_read_b32 v172, v172
	v_subrev_u32_e32 v245, 35, v198
	v_min_u32_e32 v173, 0x7f, v245
	v_lshl_add_u32 v173, v173, 2, v80
	ds_read_b32 v173, v173
	v_subrev_u32_e32 v245, 48, v198
	v_min_u32_e32 v202, 0x7f, v245
	v_lshl_add_u32 v202, v202, 2, v80
	ds_read_b32 v202, v202
	v_subrev_u32_e32 v245, 49, v198
	v_min_u32_e32 v203, 0x7f, v245
	v_lshl_add_u32 v203, v203, 2, v80
	ds_read_b32 v203, v203
	v_subrev_u32_e32 v245, 50, v198
	v_min_u32_e32 v228, 0x7f, v245
	v_lshl_add_u32 v228, v228, 2, v80
	ds_read_b32 v228, v228
	v_subrev_u32_e32 v245, 51, v198
	v_min_u32_e32 v229, 0x7f, v245
	v_lshl_add_u32 v229, v229, 2, v80
	ds_read_b32 v229, v229
	s_waitcnt lgkmcnt(0)
	v_fmamk_f32 v82, v82, 0x3fb8aa3b, v200
	v_cmp_le_i32_e32 vcc, 32, v198
	v_fmamk_f32 v92, v92, 0x3e38aa3b, v82
	s_nop 0
	v_cndmask_b32_e32 v92, v77, v92, vcc
	v_fmamk_f32 v83, v83, 0x3fb8aa3b, v200
	v_cmp_le_i32_e32 vcc, 33, v198
	v_fmamk_f32 v93, v93, 0x3e38aa3b, v83
	s_nop 0
	v_cndmask_b32_e32 v93, v77, v93, vcc
	v_fmamk_f32 v172, v172, 0x3fb8aa3b, v200
	v_cmp_le_i32_e32 vcc, 34, v198
	v_fmamk_f32 v94, v94, 0x3e38aa3b, v172
	s_nop 0
	v_cndmask_b32_e32 v94, v77, v94, vcc
	v_fmamk_f32 v173, v173, 0x3fb8aa3b, v200
	v_cmp_le_i32_e32 vcc, 35, v198
	v_fmamk_f32 v95, v95, 0x3e38aa3b, v173
	s_nop 0
	v_cndmask_b32_e32 v95, v77, v95, vcc
	v_fmamk_f32 v202, v202, 0x3fb8aa3b, v200
	v_cmp_le_i32_e32 vcc, 48, v198
	v_fmamk_f32 v96, v96, 0x3e38aa3b, v202
	s_nop 0
	v_cndmask_b32_e32 v96, v77, v96, vcc
	v_fmamk_f32 v203, v203, 0x3fb8aa3b, v200
	v_cmp_le_i32_e32 vcc, 49, v198
	v_fmamk_f32 v97, v97, 0x3e38aa3b, v203
	s_nop 0
	v_cndmask_b32_e32 v97, v77, v97, vcc
	v_fmamk_f32 v228, v228, 0x3fb8aa3b, v200
	v_cmp_le_i32_e32 vcc, 50, v198
	v_fmamk_f32 v98, v98, 0x3e38aa3b, v228
	s_nop 0
	v_cndmask_b32_e32 v98, v77, v98, vcc
	v_fmamk_f32 v229, v229, 0x3fb8aa3b, v200
	v_cmp_le_i32_e32 vcc, 51, v198
	v_fmamk_f32 v99, v99, 0x3e38aa3b, v229
	s_nop 0
	v_cndmask_b32_e32 v99, v77, v99, vcc
	s_branch .Lbm3_Ag2_max
.Lbm3_Ag2_skip:
	s_bfe_u32 s29, s48, 0x4000c
	s_cmp_eq_u32 s29, 0
	s_cbranch_scc1 .Lbm3_Ag3_skip
	s_waitcnt vmcnt(12)
	v_mfma_f32_16x16x32_fp8_fp8 v[84:87], v[2:3], v[186:187], 0
	v_mfma_f32_16x16x32_fp8_fp8 v[84:87], v[4:5], v[188:189], v[84:87]
	v_mfma_f32_16x16x32_fp8_fp8 v[88:91], v[6:7], v[186:187], 0
	v_mfma_f32_16x16x32_fp8_fp8 v[88:91], v[8:9], v[188:189], v[88:91]
	s_lshl_b32 s98, s29, 3
	s_lshl_b32 s12, s29, 6
	s_or_b32 s98, s98, s29
	s_or_b32 s98, s98, s12
	s_lshl_b32 s12, s29, 9
	s_or_b32 s98, s98, s12
	s_and_b32 s98, s98, 0x1111
	s_mul_i32 s98, s98, 15
	s_lshl_b32 s12, s98, 16
	s_or_b32 s12, s12, s98
	s_mov_b32 s13, s12
	s_cmp_eq_u32 s50, 1
	s_cbranch_scc1 .Lbm3_Ag3_near0
	v_cndmask_b32_e64 v200, v77, v255, s[12:13]
	s_cmp_eq_u32 s35, 0
	s_cbranch_scc1 .Lbm3_Ag3_first0
	v_mfma_f32_16x16x32_fp8_fp8 v[92:95], v[12:13], v[186:187], 0
	v_mfma_f32_16x16x32_fp8_fp8 v[92:95], v[14:15], v[188:189], v[92:95]
	v_pk_fma_f32 v[84:85], v[84:85], s[10:11], v[200:201] op_sel_hi:[1,1,0]
	v_pk_fma_f32 v[86:87], v[86:87], s[10:11], v[200:201] op_sel_hi:[1,1,0]
	v_mfma_f32_16x16x32_fp8_fp8 v[96:99], v[16:17], v[186:187], 0
	v_mfma_f32_16x16x32_fp8_fp8 v[96:99], v[18:19], v[188:189], v[96:99]
	v_exp_f32_e32 v84, v84
	v_exp_f32_e32 v85, v85
	v_exp_f32_e32 v86, v86
	v_exp_f32_e32 v87, v87
	v_pk_fma_f32 v[88:89], v[88:89], s[10:11], v[200:201] op_sel_hi:[1,1,0]
	v_pk_fma_f32 v[90:91], v[90:91], s[10:11], v[200:201] op_sel_hi:[1,1,0]
	v_exp_f32_e32 v88, v88
	v_exp_f32_e32 v89, v89
	v_exp_f32_e32 v90, v90
	v_exp_f32_e32 v91, v91
	v_pk_fma_f32 v[92:93], v[92:93], s[10:11], v[200:201] op_sel_hi:[1,1,0]
	v_pk_fma_f32 v[94:95], v[94:95], s[10:11], v[200:201] op_sel_hi:[1,1,0]
	v_pk_fma_f32 v[96:97], v[96:97], s[10:11], v[200:201] op_sel_hi:[1,1,0]
	v_pk_fma_f32 v[98:99], v[98:99], s[10:11], v[200:201] op_sel_hi:[1,1,0]
	v_exp_f32_e32 v92, v92
	v_exp_f32_e32 v93, v93
	v_exp_f32_e32 v94, v94
	v_exp_f32_e32 v95, v95
	s_nop 0
	v_exp_f32_e32 v96, v96
	v_exp_f32_e32 v97, v97
	v_exp_f32_e32 v98, v98
	v_exp_f32_e32 v99, v99
	v_pk_add_f32 v[248:249], v[84:85], v[86:87]
	v_pk_add_f32 v[82:83], v[88:89], v[90:91]
	v_pk_add_f32 v[172:173], v[92:93], v[94:95]
	v_pk_add_f32 v[202:203], v[96:97], v[98:99]
	v_cvt_pk_fp8_f32 v84, v84, v85
	v_cvt_pk_fp8_f32 v85, v88, v89
	v_pk_add_f32 v[248:249], v[248:249], v[82:83]
	v_pk_add_f32 v[172:173], v[172:173], v[202:203]
	v_cvt_pk_fp8_f32 v84, v86, v87 op_sel:[0,0,1]
	v_cvt_pk_fp8_f32 v85, v90, v91 op_sel:[0,0,1]
	v_pk_add_f32 v[248:249], v[248:249], v[172:173]
	v_cvt_pk_fp8_f32 v86, v92, v93
	v_cvt_pk_fp8_f32 v87, v96, v97
	v_add_f32_e32 v248, v248, v249
	v_cvt_pk_fp8_f32 v86, v94, v95 op_sel:[0,0,1]
	v_cvt_pk_fp8_f32 v87, v98, v99 op_sel:[0,0,1]
	v_cmp_lt_f32_e32 vcc, 0x43800000, v248
	s_cbranch_vccnz .Lbm3_Ag3_redo
	s_lshl_b32 s83, s32, 12
	s_add_u32 s30, s40, s83
	s_addc_u32 s31, s41, 0
	global_load_dwordx4 v[2:5], v79, s[30:31]
	global_load_dwordx4 v[6:9], v79, s[30:31] offset:1024
	global_load_dwordx4 v[12:15], v79, s[30:31] offset:2048
	global_load_dwordx4 v[16:19], v79, s[30:31] offset:3072
	v_add_f32_e32 v197, v197, v248
	s_waitcnt vmcnt(8)
	v_mfma_f32_16x16x32_fp8_fp8 v[148:151], v[36:37], v[84:85], v[148:151]
	v_mfma_f32_16x16x32_fp8_fp8 v[152:155], v[38:39], v[84:85], v[152:155]
	v_mfma_f32_16x16x32_fp8_fp8 v[156:159], v[40:41], v[84:85], v[156:159]
	v_mfma_f32_16x16x32_fp8_fp8 v[160:163], v[42:43], v[84:85], v[160:163]
	v_mfma_f32_16x16x32_fp8_fp8 v[148:151], v[44:45], v[86:87], v[148:151]
	v_mfma_f32_16x16x32_fp8_fp8 v[152:155], v[46:47], v[86:87], v[152:155]
	v_mfma_f32_16x16x32_fp8_fp8 v[156:159], v[48:49], v[86:87], v[156:159]
	v_mfma_f32_16x16x32_fp8_fp8 v[160:163], v[50:51], v[86:87], v[160:163]
	s_branch .Lbm3_Ag3_skip

.Lbm3_Ag3_near:
	s_lshl_b32 s9, s38, 6
	s_sub_i32 s9, s47, s9
	s_add_i32 s9, s9, 12
	v_and_b32_e32 v245, 15, v181
	v_lshrrev_b32_e32 v246, 4, v181
	v_lshrrev_b32_e32 v245, 2, v245
	v_lshlrev_b32_e32 v246, 2, v246
	v_cndmask_b32_e64 v200, v77, v193, s[12:13]
	v_sub_u32_e32 v245, v245, v246
	v_add_u32_e32 v198, s9, v245
	v_min_u32_e32 v82, 0x7f, v198
	v_lshl_add_u32 v82, v82, 2, v80
	ds_read_b32 v82, v82
	v_subrev_u32_e32 v245, 1, v198
	v_min_u32_e32 v83, 0x7f, v245
	v_lshl_add_u32 v83, v83, 2, v80
	ds_read_b32 v83, v83
	v_subrev_u32_e32 v245, 2, v198
	v_min_u32_e32 v172, 0x7f, v245
	v_lshl_add_u32 v172, v172, 2, v80
	ds_read_b32 v172, v172
	v_subrev_u32_e32 v245, 3, v198
	v_min_u32_e32 v173, 0x7f, v245
	v_lshl_add_u32 v173, v173, 2, v80
	ds_read_b32 v173, v173
	v_subrev_u32_e32 v245, 16, v198
	v_min_u32_e32 v202, 0x7f, v245
	v_lshl_add_u32 v202, v202, 2, v80
	ds_read_b32 v202, v202
	v_subrev_u32_e32 v245, 17, v198
	v_min_u32_e32 v203, 0x7f, v245
	v_lshl_add_u32 v203, v203, 2, v80
	ds_read_b32 v203, v203
	v_subrev_u32_e32 v245, 18, v198
	v_min_u32_e32 v228, 0x7f, v245
	v_lshl_add_u32 v228, v228, 2, v80
	ds_read_b32 v228, v228
	v_subrev_u32_e32 v245, 19, v198
	v_min_u32_e32 v229, 0x7f, v245
	v_lshl_add_u32 v229, v229, 2, v80
	ds_read_b32 v229, v229
	s_waitcnt lgkmcnt(0)
	v_fmamk_f32 v82, v82, 0x3fb8aa3b, v200
	v_cmp_le_i32_e32 vcc, 0, v198
	v_fmamk_f32 v84, v84, 0x3e38aa3b, v82
	s_nop 0
	v_cndmask_b32_e32 v84, v77, v84, vcc
	v_fmamk_f32 v83, v83, 0x3fb8aa3b, v200
	v_cmp_le_i32_e32 vcc, 1, v198
	v_fmamk_f32 v85, v85, 0x3e38aa3b, v83
	s_nop 0
	v_cndmask_b32_e32 v85, v77, v85, vcc
	v_fmamk_f32 v172, v172, 0x3fb8aa3b, v200
	v_cmp_le_i32_e32 vcc, 2, v198
	v_fmamk_f32 v86, v86, 0x3e38aa3b, v172
	s_nop 0
	v_cndmask_b32_e32 v86, v77, v86, vcc
	v_fmamk_f32 v173, v173, 0x3fb8aa3b, v200
	v_cmp_le_i32_e32 vcc, 3, v198
	v_fmamk_f32 v87, v87, 0x3e38aa3b, v173
	s_nop 0
	v_cndmask_b32_e32 v87, v77, v87, vcc
	v_fmamk_f32 v202, v202, 0x3fb8aa3b, v200
	v_cmp_le_i32_e32 vcc, 16, v198
	v_fmamk_f32 v88, v88, 0x3e38aa3b, v202
	s_nop 0
	v_cndmask_b32_e32 v88, v77, v88, vcc
	v_fmamk_f32 v203, v203, 0x3fb8aa3b, v200
	v_cmp_le_i32_e32 vcc, 17, v198
	v_fmamk_f32 v89, v89, 0x3e38aa3b, v203
	s_nop 0
	v_cndmask_b32_e32 v89, v77, v89, vcc
	v_fmamk_f32 v228, v228, 0x3fb8aa3b, v200
	v_cmp_le_i32_e32 vcc, 18, v198
	v_fmamk_f32 v90, v90, 0x3e38aa3b, v228
	s_nop 0
	v_cndmask_b32_e32 v90, v77, v90, vcc
	v_fmamk_f32 v229, v229, 0x3fb8aa3b, v200
	v_cmp_le_i32_e32 vcc, 19, v198
	v_fmamk_f32 v91, v91, 0x3e38aa3b, v229
	s_nop 0
	v_cndmask_b32_e32 v91, v77, v91, vcc
	v_subrev_u32_e32 v245, 32, v198
	v_min_u32_e32 v82, 0x7f, v245
	v_lshl_add_u32 v82, v82, 2, v80
	ds_read_b32 v82, v82
	v_subrev_u32_e32 v245, 33, v198
	v_min_u32_e32 v83, 0x7f, v245
	v_lshl_add_u32 v83, v83, 2, v80
	ds_read_b32 v83, v83
	v_subrev_u32_e32 v245, 34, v198
	v_min_u32_e32 v172, 0x7f, v245
	v_lshl_add_u32 v172, v172, 2, v80
	ds_read_b32 v172, v172
	v_subrev_u32_e32 v245, 35, v198
	v_min_u32_e32 v173, 0x7f, v245
	v_lshl_add_u32 v173, v173, 2, v80
	ds_read_b32 v173, v173
	v_subrev_u32_e32 v245, 48, v198
	v_min_u32_e32 v202, 0x7f, v245
	v_lshl_add_u32 v202, v202, 2, v80
	ds_read_b32 v202, v202
	v_subrev_u32_e32 v245, 49, v198
	v_min_u32_e32 v203, 0x7f, v245
	v_lshl_add_u32 v203, v203, 2, v80
	ds_read_b32 v203, v203
	v_subrev_u32_e32 v245, 50, v198
	v_min_u32_e32 v228, 0x7f, v245
	v_lshl_add_u32 v228, v228, 2, v80
	ds_read_b32 v228, v228
	v_subrev_u32_e32 v245, 51, v198
	v_min_u32_e32 v229, 0x7f, v245
	v_lshl_add_u32 v229, v229, 2, v80
	ds_read_b32 v229, v229
	s_waitcnt lgkmcnt(0)
	v_fmamk_f32 v82, v82, 0x3fb8aa3b, v200
	v_cmp_le_i32_e32 vcc, 32, v198
	v_fmamk_f32 v92, v92, 0x3e38aa3b, v82
	s_nop 0
	v_cndmask_b32_e32 v92, v77, v92, vcc
	v_fmamk_f32 v83, v83, 0x3fb8aa3b, v200
	v_cmp_le_i32_e32 vcc, 33, v198
	v_fmamk_f32 v93, v93, 0x3e38aa3b, v83
	s_nop 0
	v_cndmask_b32_e32 v93, v77, v93, vcc
	v_fmamk_f32 v172, v172, 0x3fb8aa3b, v200
	v_cmp_le_i32_e32 vcc, 34, v198
	v_fmamk_f32 v94, v94, 0x3e38aa3b, v172
	s_nop 0
	v_cndmask_b32_e32 v94, v77, v94, vcc
	v_fmamk_f32 v173, v173, 0x3fb8aa3b, v200
	v_cmp_le_i32_e32 vcc, 35, v198
	v_fmamk_f32 v95, v95, 0x3e38aa3b, v173
	s_nop 0
	v_cndmask_b32_e32 v95, v77, v95, vcc
	v_fmamk_f32 v202, v202, 0x3fb8aa3b, v200
	v_cmp_le_i32_e32 vcc, 48, v198
	v_fmamk_f32 v96, v96, 0x3e38aa3b, v202
	s_nop 0
	v_cndmask_b32_e32 v96, v77, v96, vcc
	v_fmamk_f32 v203, v203, 0x3fb8aa3b, v200
	v_cmp_le_i32_e32 vcc, 49, v198
	v_fmamk_f32 v97, v97, 0x3e38aa3b, v203
	s_nop 0
	v_cndmask_b32_e32 v97, v77, v97, vcc
	v_fmamk_f32 v228, v228, 0x3fb8aa3b, v200
	v_cmp_le_i32_e32 vcc, 50, v198
	v_fmamk_f32 v98, v98, 0x3e38aa3b, v228
	s_nop 0
	v_cndmask_b32_e32 v98, v77, v98, vcc
	v_fmamk_f32 v229, v229, 0x3fb8aa3b, v200
	v_cmp_le_i32_e32 vcc, 51, v198
	v_fmamk_f32 v99, v99, 0x3e38aa3b, v229
	s_nop 0
	v_cndmask_b32_e32 v99, v77, v99, vcc
	s_branch .Lbm3_Ag3_max

.Lbm3_blkB:
	s_lshl_b32 s29, s27, 12
	s_add_u32 s30, s62, s29
	s_addc_u32 s31, s63, 0
	global_load_dwordx4 v[36:39], v79, s[30:31]
	global_load_dwordx4 v[40:43], v79, s[30:31] offset:1024
	global_load_dwordx4 v[44:47], v79, s[30:31] offset:2048
	global_load_dwordx4 v[48:51], v79, s[30:31] offset:3072
	s_add_i32 s50, s35, 3
	s_add_i32 s9, s25, -1
	s_min_i32 s50, s50, s9
	s_lshl_b32 s9, s50, 2
	s_add_i32 s9, s9, s46
	v_mov_b32_e32 v76, s9
	ds_read_b32 v76, v76 offset:16384
	s_cmp_ge_i32 s38, s21
	s_cselect_b32 s50, 1, 0
	s_bfe_u32 s29, s48, 0x40000
	s_cmp_eq_u32 s29, 0
	s_cbranch_scc1 .Lbm3_Bg0_skip
	s_waitcnt vmcnt(12)
	v_mfma_f32_16x16x32_fp8_fp8 v[84:87], v[20:21], v[164:165], 0
	v_mfma_f32_16x16x32_fp8_fp8 v[84:87], v[22:23], v[166:167], v[84:87]
	v_mfma_f32_16x16x32_fp8_fp8 v[88:91], v[24:25], v[164:165], 0
	v_mfma_f32_16x16x32_fp8_fp8 v[88:91], v[26:27], v[166:167], v[88:91]
	s_lshl_b32 s98, s29, 3
	s_lshl_b32 s12, s29, 6
	s_or_b32 s98, s98, s29
	s_or_b32 s98, s98, s12
	s_lshl_b32 s12, s29, 9
	s_or_b32 s98, s98, s12
	s_and_b32 s98, s98, 0x1111
	s_mul_i32 s98, s98, 15
	s_lshl_b32 s12, s98, 16
	s_or_b32 s12, s12, s98
	s_mov_b32 s13, s12
	s_cmp_eq_u32 s50, 1
	s_cbranch_scc1 .Lbm3_Bg0_near0
	v_cndmask_b32_e64 v200, v77, v252, s[12:13]
	s_cmp_eq_u32 s35, 0
	s_cbranch_scc1 .Lbm3_Bg0_first0
	v_mfma_f32_16x16x32_fp8_fp8 v[92:95], v[28:29], v[164:165], 0
	v_mfma_f32_16x16x32_fp8_fp8 v[92:95], v[30:31], v[166:167], v[92:95]
	v_pk_fma_f32 v[84:85], v[84:85], s[10:11], v[200:201] op_sel_hi:[1,1,0]
	v_pk_fma_f32 v[86:87], v[86:87], s[10:11], v[200:201] op_sel_hi:[1,1,0]
	v_mfma_f32_16x16x32_fp8_fp8 v[96:99], v[32:33], v[164:165], 0
	v_mfma_f32_16x16x32_fp8_fp8 v[96:99], v[34:35], v[166:167], v[96:99]
	v_exp_f32_e32 v84, v84
	v_exp_f32_e32 v85, v85
	v_exp_f32_e32 v86, v86
	v_exp_f32_e32 v87, v87
	v_pk_fma_f32 v[88:89], v[88:89], s[10:11], v[200:201] op_sel_hi:[1,1,0]
	v_pk_fma_f32 v[90:91], v[90:91], s[10:11], v[200:201] op_sel_hi:[1,1,0]
	v_exp_f32_e32 v88, v88
	v_exp_f32_e32 v89, v89
	v_exp_f32_e32 v90, v90
	v_exp_f32_e32 v91, v91
	v_pk_fma_f32 v[92:93], v[92:93], s[10:11], v[200:201] op_sel_hi:[1,1,0]
	v_pk_fma_f32 v[94:95], v[94:95], s[10:11], v[200:201] op_sel_hi:[1,1,0]
	v_pk_fma_f32 v[96:97], v[96:97], s[10:11], v[200:201] op_sel_hi:[1,1,0]
	v_pk_fma_f32 v[98:99], v[98:99], s[10:11], v[200:201] op_sel_hi:[1,1,0]
	v_exp_f32_e32 v92, v92
	v_exp_f32_e32 v93, v93
	v_exp_f32_e32 v94, v94
	v_exp_f32_e32 v95, v95
	s_nop 0
	v_exp_f32_e32 v96, v96
	v_exp_f32_e32 v97, v97
	v_exp_f32_e32 v98, v98
	v_exp_f32_e32 v99, v99
	v_pk_add_f32 v[248:249], v[84:85], v[86:87]
	v_pk_add_f32 v[82:83], v[88:89], v[90:91]
	v_pk_add_f32 v[172:173], v[92:93], v[94:95]
	v_pk_add_f32 v[202:203], v[96:97], v[98:99]
	v_cvt_pk_fp8_f32 v84, v84, v85
	v_cvt_pk_fp8_f32 v85, v88, v89
	v_pk_add_f32 v[248:249], v[248:249], v[82:83]
	v_pk_add_f32 v[172:173], v[172:173], v[202:203]
	v_cvt_pk_fp8_f32 v84, v86, v87 op_sel:[0,0,1]
	v_cvt_pk_fp8_f32 v85, v90, v91 op_sel:[0,0,1]
	v_pk_add_f32 v[248:249], v[248:249], v[172:173]
	v_cvt_pk_fp8_f32 v86, v92, v93
	v_cvt_pk_fp8_f32 v87, v96, v97
	v_add_f32_e32 v248, v248, v249
	v_cvt_pk_fp8_f32 v86, v94, v95 op_sel:[0,0,1]
	v_cvt_pk_fp8_f32 v87, v98, v99 op_sel:[0,0,1]
	v_cmp_lt_f32_e32 vcc, 0x43800000, v248
	s_cbranch_vccnz .Lbm3_Bg0_redo
	s_lshr_b32 s83, s48, 4
	s_cmp_lg_u32 s83, 0
	s_cbranch_scc1 .Lbm3_Bg0_ks0
	s_lshl_b32 s83, s32, 12
	s_add_u32 s30, s40, s83
	s_addc_u32 s31, s41, 0
	global_load_dwordx4 v[20:23], v79, s[30:31]
	global_load_dwordx4 v[24:27], v79, s[30:31] offset:1024
	global_load_dwordx4 v[28:31], v79, s[30:31] offset:2048
	global_load_dwordx4 v[32:35], v79, s[30:31] offset:3072

.Lbm3_Bg0_skip:
	s_bfe_u32 s29, s48, 0x40004
	s_cmp_eq_u32 s29, 0
	s_cbranch_scc1 .Lbm3_Bg1_skip
	s_waitcnt vmcnt(12)
	v_mfma_f32_16x16x32_fp8_fp8 v[84:87], v[20:21], v[168:169], 0
	v_mfma_f32_16x16x32_fp8_fp8 v[84:87], v[22:23], v[170:171], v[84:87]
	v_mfma_f32_16x16x32_fp8_fp8 v[88:91], v[24:25], v[168:169], 0
	v_mfma_f32_16x16x32_fp8_fp8 v[88:91], v[26:27], v[170:171], v[88:91]
	s_lshl_b32 s98, s29, 3
	s_lshl_b32 s12, s29, 6
	s_or_b32 s98, s98, s29
	s_or_b32 s98, s98, s12
	s_lshl_b32 s12, s29, 9
	s_or_b32 s98, s98, s12
	s_and_b32 s98, s98, 0x1111
	s_mul_i32 s98, s98, 15
	s_lshl_b32 s12, s98, 16
	s_or_b32 s12, s12, s98
	s_mov_b32 s13, s12
	s_cmp_eq_u32 s50, 1
	s_cbranch_scc1 .Lbm3_Bg1_near0
	v_cndmask_b32_e64 v200, v77, v253, s[12:13]
	s_cmp_eq_u32 s35, 0
	s_cbranch_scc1 .Lbm3_Bg1_first0
	v_mfma_f32_16x16x32_fp8_fp8 v[92:95], v[28:29], v[168:169], 0
	v_mfma_f32_16x16x32_fp8_fp8 v[92:95], v[30:31], v[170:171], v[92:95]
	v_pk_fma_f32 v[84:85], v[84:85], s[10:11], v[200:201] op_sel_hi:[1,1,0]
	v_pk_fma_f32 v[86:87], v[86:87], s[10:11], v[200:201] op_sel_hi:[1,1,0]
	v_mfma_f32_16x16x32_fp8_fp8 v[96:99], v[32:33], v[168:169], 0
	v_mfma_f32_16x16x32_fp8_fp8 v[96:99], v[34:35], v[170:171], v[96:99]
	v_exp_f32_e32 v84, v84
	v_exp_f32_e32 v85, v85
	v_exp_f32_e32 v86, v86
	v_exp_f32_e32 v87, v87
	v_pk_fma_f32 v[88:89], v[88:89], s[10:11], v[200:201] op_sel_hi:[1,1,0]
	v_pk_fma_f32 v[90:91], v[90:91], s[10:11], v[200:201] op_sel_hi:[1,1,0]
	v_exp_f32_e32 v88, v88
	v_exp_f32_e32 v89, v89
	v_exp_f32_e32 v90, v90
	v_exp_f32_e32 v91, v91
	v_pk_fma_f32 v[92:93], v[92:93], s[10:11], v[200:201] op_sel_hi:[1,1,0]
	v_pk_fma_f32 v[94:95], v[94:95], s[10:11], v[200:201] op_sel_hi:[1,1,0]
	v_pk_fma_f32 v[96:97], v[96:97], s[10:11], v[200:201] op_sel_hi:[1,1,0]
	v_pk_fma_f32 v[98:99], v[98:99], s[10:11], v[200:201] op_sel_hi:[1,1,0]
	v_exp_f32_e32 v92, v92
	v_exp_f32_e32 v93, v93
	v_exp_f32_e32 v94, v94
	v_exp_f32_e32 v95, v95
	s_nop 0
	v_exp_f32_e32 v96, v96
	v_exp_f32_e32 v97, v97
	v_exp_f32_e32 v98, v98
	v_exp_f32_e32 v99, v99
	v_pk_add_f32 v[248:249], v[84:85], v[86:87]
	v_pk_add_f32 v[82:83], v[88:89], v[90:91]
	v_pk_add_f32 v[172:173], v[92:93], v[94:95]
	v_pk_add_f32 v[202:203], v[96:97], v[98:99]
	v_cvt_pk_fp8_f32 v84, v84, v85
	v_cvt_pk_fp8_f32 v85, v88, v89
	v_pk_add_f32 v[248:249], v[248:249], v[82:83]
	v_pk_add_f32 v[172:173], v[172:173], v[202:203]
	v_cvt_pk_fp8_f32 v84, v86, v87 op_sel:[0,0,1]
	v_cvt_pk_fp8_f32 v85, v90, v91 op_sel:[0,0,1]
	v_pk_add_f32 v[248:249], v[248:249], v[172:173]
	v_cvt_pk_fp8_f32 v86, v92, v93
	v_cvt_pk_fp8_f32 v87, v96, v97
	v_add_f32_e32 v248, v248, v249
	v_cvt_pk_fp8_f32 v86, v94, v95 op_sel:[0,0,1]
	v_cvt_pk_fp8_f32 v87, v98, v99 op_sel:[0,0,1]
	v_cmp_lt_f32_e32 vcc, 0x43800000, v248
	s_cbranch_vccnz .Lbm3_Bg1_redo
	s_lshr_b32 s83, s48, 8
	s_cmp_lg_u32 s83, 0
	s_cbranch_scc1 .Lbm3_Bg1_ks0
	s_lshl_b32 s83, s32, 12
	s_add_u32 s30, s40, s83
	s_addc_u32 s31, s41, 0
	global_load_dwordx4 v[20:23], v79, s[30:31]
	global_load_dwordx4 v[24:27], v79, s[30:31] offset:1024
	global_load_dwordx4 v[28:31], v79, s[30:31] offset:2048
	global_load_dwordx4 v[32:35], v79, s[30:31] offset:3072

.Lbm3_Bg1_skip:
	s_bfe_u32 s29, s48, 0x40008
	s_cmp_eq_u32 s29, 0
	s_cbranch_scc1 .Lbm3_Bg2_skip
	s_waitcnt vmcnt(12)
	v_mfma_f32_16x16x32_fp8_fp8 v[84:87], v[20:21], v[182:183], 0
	v_mfma_f32_16x16x32_fp8_fp8 v[84:87], v[22:23], v[184:185], v[84:87]
	v_mfma_f32_16x16x32_fp8_fp8 v[88:91], v[24:25], v[182:183], 0
	v_mfma_f32_16x16x32_fp8_fp8 v[88:91], v[26:27], v[184:185], v[88:91]
	s_lshl_b32 s98, s29, 3
	s_lshl_b32 s12, s29, 6
	s_or_b32 s98, s98, s29
	s_or_b32 s98, s98, s12
	s_lshl_b32 s12, s29, 9
	s_or_b32 s98, s98, s12
	s_and_b32 s98, s98, 0x1111
	s_mul_i32 s98, s98, 15
	s_lshl_b32 s12, s98, 16
	s_or_b32 s12, s12, s98
	s_mov_b32 s13, s12
	s_cmp_eq_u32 s50, 1
	s_cbranch_scc1 .Lbm3_Bg2_near0
	v_cndmask_b32_e64 v200, v77, v254, s[12:13]
	s_cmp_eq_u32 s35, 0
	s_cbranch_scc1 .Lbm3_Bg2_first0
	v_mfma_f32_16x16x32_fp8_fp8 v[92:95], v[28:29], v[182:183], 0
	v_mfma_f32_16x16x32_fp8_fp8 v[92:95], v[30:31], v[184:185], v[92:95]
	v_pk_fma_f32 v[84:85], v[84:85], s[10:11], v[200:201] op_sel_hi:[1,1,0]
	v_pk_fma_f32 v[86:87], v[86:87], s[10:11], v[200:201] op_sel_hi:[1,1,0]
	v_mfma_f32_16x16x32_fp8_fp8 v[96:99], v[32:33], v[182:183], 0
	v_mfma_f32_16x16x32_fp8_fp8 v[96:99], v[34:35], v[184:185], v[96:99]
	v_exp_f32_e32 v84, v84
	v_exp_f32_e32 v85, v85
	v_exp_f32_e32 v86, v86
	v_exp_f32_e32 v87, v87
	v_pk_fma_f32 v[88:89], v[88:89], s[10:11], v[200:201] op_sel_hi:[1,1,0]
	v_pk_fma_f32 v[90:91], v[90:91], s[10:11], v[200:201] op_sel_hi:[1,1,0]
	v_exp_f32_e32 v88, v88
	v_exp_f32_e32 v89, v89
	v_exp_f32_e32 v90, v90
	v_exp_f32_e32 v91, v91
	v_pk_fma_f32 v[92:93], v[92:93], s[10:11], v[200:201] op_sel_hi:[1,1,0]
	v_pk_fma_f32 v[94:95], v[94:95], s[10:11], v[200:201] op_sel_hi:[1,1,0]
	v_pk_fma_f32 v[96:97], v[96:97], s[10:11], v[200:201] op_sel_hi:[1,1,0]
	v_pk_fma_f32 v[98:99], v[98:99], s[10:11], v[200:201] op_sel_hi:[1,1,0]
	v_exp_f32_e32 v92, v92
	v_exp_f32_e32 v93, v93
	v_exp_f32_e32 v94, v94
	v_exp_f32_e32 v95, v95
	s_nop 0
	v_exp_f32_e32 v96, v96
	v_exp_f32_e32 v97, v97
	v_exp_f32_e32 v98, v98
	v_exp_f32_e32 v99, v99
	v_pk_add_f32 v[248:249], v[84:85], v[86:87]
	v_pk_add_f32 v[82:83], v[88:89], v[90:91]
	v_pk_add_f32 v[172:173], v[92:93], v[94:95]
	v_pk_add_f32 v[202:203], v[96:97], v[98:99]
	v_cvt_pk_fp8_f32 v84, v84, v85
	v_cvt_pk_fp8_f32 v85, v88, v89
	v_pk_add_f32 v[248:249], v[248:249], v[82:83]
	v_pk_add_f32 v[172:173], v[172:173], v[202:203]
	v_cvt_pk_fp8_f32 v84, v86, v87 op_sel:[0,0,1]
	v_cvt_pk_fp8_f32 v85, v90, v91 op_sel:[0,0,1]
	v_pk_add_f32 v[248:249], v[248:249], v[172:173]
	v_cvt_pk_fp8_f32 v86, v92, v93
	v_cvt_pk_fp8_f32 v87, v96, v97
	v_add_f32_e32 v248, v248, v249
	v_cvt_pk_fp8_f32 v86, v94, v95 op_sel:[0,0,1]
	v_cvt_pk_fp8_f32 v87, v98, v99 op_sel:[0,0,1]
	v_cmp_lt_f32_e32 vcc, 0x43800000, v248
	s_cbranch_vccnz .Lbm3_Bg2_redo
	s_lshr_b32 s83, s48, 12
	s_cmp_lg_u32 s83, 0
	s_cbranch_scc1 .Lbm3_Bg2_ks0
	s_lshl_b32 s83, s32, 12
	s_add_u32 s30, s40, s83
	s_addc_u32 s31, s41, 0
	global_load_dwordx4 v[20:23], v79, s[30:31]
	global_load_dwordx4 v[24:27], v79, s[30:31] offset:1024
	global_load_dwordx4 v[28:31], v79, s[30:31] offset:2048
	global_load_dwordx4 v[32:35], v79, s[30:31] offset:3072

.Lbm3_Bg2_skip:
	s_bfe_u32 s29, s48, 0x4000c
	s_cmp_eq_u32 s29, 0
	s_cbranch_scc1 .Lbm3_Bg3_skip
	s_waitcnt vmcnt(12)
	v_mfma_f32_16x16x32_fp8_fp8 v[84:87], v[20:21], v[186:187], 0
	v_mfma_f32_16x16x32_fp8_fp8 v[84:87], v[22:23], v[188:189], v[84:87]
	v_mfma_f32_16x16x32_fp8_fp8 v[88:91], v[24:25], v[186:187], 0
	v_mfma_f32_16x16x32_fp8_fp8 v[88:91], v[26:27], v[188:189], v[88:91]
	s_lshl_b32 s98, s29, 3
	s_lshl_b32 s12, s29, 6
	s_or_b32 s98, s98, s29
	s_or_b32 s98, s98, s12
	s_lshl_b32 s12, s29, 9
	s_or_b32 s98, s98, s12
	s_and_b32 s98, s98, 0x1111
	s_mul_i32 s98, s98, 15
	s_lshl_b32 s12, s98, 16
	s_or_b32 s12, s12, s98
	s_mov_b32 s13, s12
	s_cmp_eq_u32 s50, 1
	s_cbranch_scc1 .Lbm3_Bg3_near0
	v_cndmask_b32_e64 v200, v77, v255, s[12:13]
	s_cmp_eq_u32 s35, 0
	s_cbranch_scc1 .Lbm3_Bg3_first0
	v_mfma_f32_16x16x32_fp8_fp8 v[92:95], v[28:29], v[186:187], 0
	v_mfma_f32_16x16x32_fp8_fp8 v[92:95], v[30:31], v[188:189], v[92:95]
	v_pk_fma_f32 v[84:85], v[84:85], s[10:11], v[200:201] op_sel_hi:[1,1,0]
	v_pk_fma_f32 v[86:87], v[86:87], s[10:11], v[200:201] op_sel_hi:[1,1,0]
	v_mfma_f32_16x16x32_fp8_fp8 v[96:99], v[32:33], v[186:187], 0
	v_mfma_f32_16x16x32_fp8_fp8 v[96:99], v[34:35], v[188:189], v[96:99]
	v_exp_f32_e32 v84, v84
	v_exp_f32_e32 v85, v85
	v_exp_f32_e32 v86, v86
	v_exp_f32_e32 v87, v87
	v_pk_fma_f32 v[88:89], v[88:89], s[10:11], v[200:201] op_sel_hi:[1,1,0]
	v_pk_fma_f32 v[90:91], v[90:91], s[10:11], v[200:201] op_sel_hi:[1,1,0]
	v_exp_f32_e32 v88, v88
	v_exp_f32_e32 v89, v89
	v_exp_f32_e32 v90, v90
	v_exp_f32_e32 v91, v91
	v_pk_fma_f32 v[92:93], v[92:93], s[10:11], v[200:201] op_sel_hi:[1,1,0]
	v_pk_fma_f32 v[94:95], v[94:95], s[10:11], v[200:201] op_sel_hi:[1,1,0]
	v_pk_fma_f32 v[96:97], v[96:97], s[10:11], v[200:201] op_sel_hi:[1,1,0]
	v_pk_fma_f32 v[98:99], v[98:99], s[10:11], v[200:201] op_sel_hi:[1,1,0]
	v_exp_f32_e32 v92, v92
	v_exp_f32_e32 v93, v93
	v_exp_f32_e32 v94, v94
	v_exp_f32_e32 v95, v95
	s_nop 0
	v_exp_f32_e32 v96, v96
	v_exp_f32_e32 v97, v97
	v_exp_f32_e32 v98, v98
	v_exp_f32_e32 v99, v99
	v_pk_add_f32 v[248:249], v[84:85], v[86:87]
	v_pk_add_f32 v[82:83], v[88:89], v[90:91]
	v_pk_add_f32 v[172:173], v[92:93], v[94:95]
	v_pk_add_f32 v[202:203], v[96:97], v[98:99]
	v_cvt_pk_fp8_f32 v84, v84, v85
	v_cvt_pk_fp8_f32 v85, v88, v89
	v_pk_add_f32 v[248:249], v[248:249], v[82:83]
	v_pk_add_f32 v[172:173], v[172:173], v[202:203]
	v_cvt_pk_fp8_f32 v84, v86, v87 op_sel:[0,0,1]
	v_cvt_pk_fp8_f32 v85, v90, v91 op_sel:[0,0,1]
	v_pk_add_f32 v[248:249], v[248:249], v[172:173]
	v_cvt_pk_fp8_f32 v86, v92, v93
	v_cvt_pk_fp8_f32 v87, v96, v97
	v_add_f32_e32 v248, v248, v249
	v_cvt_pk_fp8_f32 v86, v94, v95 op_sel:[0,0,1]
	v_cvt_pk_fp8_f32 v87, v98, v99 op_sel:[0,0,1]
	v_cmp_lt_f32_e32 vcc, 0x43800000, v248
	s_cbranch_vccnz .Lbm3_Bg3_redo
	s_lshl_b32 s83, s32, 12
	s_add_u32 s30, s40, s83
	s_addc_u32 s31, s41, 0
	global_load_dwordx4 v[20:23], v79, s[30:31]
	global_load_dwordx4 v[24:27], v79, s[30:31] offset:1024
	global_load_dwordx4 v[28:31], v79, s[30:31] offset:2048
	global_load_dwordx4 v[32:35], v79, s[30:31] offset:3072
	v_add_f32_e32 v197, v197, v248
	s_waitcnt vmcnt(8)
	v_mfma_f32_16x16x32_fp8_fp8 v[148:151], v[52:53], v[84:85], v[148:151]
	v_mfma_f32_16x16x32_fp8_fp8 v[152:155], v[54:55], v[84:85], v[152:155]
	v_mfma_f32_16x16x32_fp8_fp8 v[156:159], v[56:57], v[84:85], v[156:159]
	v_mfma_f32_16x16x32_fp8_fp8 v[160:163], v[58:59], v[84:85], v[160:163]
	v_mfma_f32_16x16x32_fp8_fp8 v[148:151], v[60:61], v[86:87], v[148:151]
	v_mfma_f32_16x16x32_fp8_fp8 v[152:155], v[62:63], v[86:87], v[152:155]
	v_mfma_f32_16x16x32_fp8_fp8 v[156:159], v[64:65], v[86:87], v[156:159]
	v_mfma_f32_16x16x32_fp8_fp8 v[160:163], v[66:67], v[86:87], v[160:163]
	s_branch .Lbm3_Bg3_skip
